# v20 + loop-edge rotation (7.11): SALU/VALU heads of all four K-loop load segments and the counter update hoisted into MFMA gaps of the preceding MMA block; bit-identical
# baseline (speedup 1.0000x reference)
; #define PG8_STAGE(bufoff, gbase, voff) do { _Pragma("unroll") for (int _i = 0; _i < 2; ++_i) \
;         __builtin_amdgcn_global_load_lds((const unsigned*)((const char*)(gbase) + (voff)[_i]), (PG8_LAS unsigned*)(lds + (bufoff) + ldsw + _i * 8192), 16, 0, 0); } while (0)
; #define PG8_LDA(dst, b, h) do { _Pragma("unroll") for (int m = 0; m < 4; ++m) _Pragma("unroll") for (int k = 0; k < 2; ++k) dst[m][k] = *(const PG8_LAS bf16x8*)(lds + PG8_SA(b, h) + aoff + m * 2048 + k * 1024); } while (0)
; #define PG8_LDB(dst, b, h) do { _Pragma("unroll") for (int n = 0; n < 2; ++n) _Pragma("unroll") for (int k = 0; k < 2; ++k) dst[n][k] = *(const PG8_LAS bf16x8*)(lds + PG8_SB(b, h) + boff + n * 2048 + k * 1024); } while (0)
; #define PG8_WAIT_V(n) asm volatile("s_waitcnt vmcnt(" #n ")" ::: "memory")
; #define PG8_WAIT_L(n) asm volatile("s_waitcnt lgkmcnt(" #n ")" ::: "memory")
; #define PG8_BAR __builtin_amdgcn_s_barrier()
; #define PG8_SCHED __builtin_amdgcn_sched_barrier(0)
; template <class Epi, class Sched, bool ALIGN_EPI = false, bool SP2 = false>
; __device__ __forceinline__ void gemm_phase(PG8_LAS unsigned char* lds, const Gemm g, const Sched& S, const Epi& E) {
;     ...
;         const bool has_next = S.next(ui + 1, nxt);
;         const char* nA = has_next ? (const char*)g.A + (size_t)nxt.pm * tstepA : cA; const char* nB = has_next ? (const char*)g.Bt + (size_t)nxt.pn * tstep : cB;
;         for (int t = 0; t < nt; t += 2) {
;             const bool last = (t == nt - 2);
;             const char* a1 = cA + (size_t)(t + 1) * kstepA;
;             const char* a2 = last ? nA : cA + (size_t)(t + 2) * kstepA; const char* b2 = last ? nB : cB + (size_t)(t + 2) * kstep;
;             const char* a3 = a2 + kstepA; const char* b3 = b2 + kstep;
;             if (last && has_next) S.a_ready(nxt);
;             if constexpr (SP2) {
;             PG8_LDB(B0, 0, 0); PG8_LDB(B1, 0, 1); PG8_SCHED; PG8_LDA(At, 0, 0); PG8_STAGE(PG8_SA(1, 1), a1 + hstepA, voffA);
;             PG8_WAIT_V(8); PG8_WAIT_L(0); PG8_BAR; PG8_MMA(0, 0, At, B0); PG8_MMA(0, 1, At, B1); PG8_BAR; PG8_SCHED;
;             PG8_LDA(At, 0, 1); PG8_STAGE(PG8_SB(0, 0), b2, voffB); PG8_STAGE(PG8_SB(0, 1), b2 + hstep, voffB); PG8_STAGE(PG8_SA(0, 0), a2, voffA);
;             PG8_WAIT_V(8); PG8_WAIT_L(0); PG8_BAR; PG8_MMA(1, 0, At, B0); PG8_MMA(1, 1, At, B1); PG8_BAR; PG8_SCHED;
.LBB0_195:
	s_ashr_i32 s27, s26, 31
	s_lshl_b64 s[38:39], s[26:27], 19
	s_add_u32 s38, s20, s38
	s_addc_u32 s39, s21, s39
	s_and_b64 s[40:41], s[36:37], exec
	s_cselect_b32 s27, s39, s45
	s_cselect_b32 s54, s38, s44
	s_ashr_i32 s25, s24, 31
	s_lshl_b64 s[40:41], s[24:25], 19
	s_add_u32 s40, s2, s40
	s_addc_u32 s41, s3, s41
	s_and_b64 s[46:47], s[36:37], exec
	s_cselect_b32 s25, s41, s43
	s_cselect_b32 s55, s40, s42
	s_add_u32 s56, s42, 0x100
	s_addc_u32 s57, s43, 0
	s_add_u32 s42, s44, 0x40080
	s_addc_u32 s43, s45, 0
	s_mov_b32 s58, -2
	s_add_u32 s44, s42, 0xfffc0080
	s_addc_u32 s45, s43, -1
	s_add_i32 s59, 0, 0x10000
	s_cmp_eq_u32 s58, 12
	s_cselect_b32 s47, s27, s45
	s_cselect_b32 s46, s54, s44
	s_cselect_b32 s45, s25, s57
	s_cselect_b32 s44, s55, s56
	s_add_i32 s62, 0, 0x14000
	v_add_u32_e32 v154, s59, v143
	v_add_u32_e32 v166, s62, v143
	ds_read_b128 v[138:141], v154
	ds_read_b128 v[146:149], v154 offset:1024
	ds_read_b128 v[150:153], v154 offset:2048
	ds_read_b128 v[154:157], v154 offset:3072
	ds_read_b128 v[158:161], v166
	ds_read_b128 v[162:165], v166 offset:1024
	ds_read_b128 v[170:173], v166 offset:2048
	ds_read_b128 v[188:191], v166 offset:3072
	v_lshl_add_u64 v[166:167], s[42:43], 0, v[136:137]
	s_add_i32 m0, s7, 0xc000
	ds_read_b128 v[192:195], v145
	ds_read_b128 v[196:199], v145 offset:1024
	ds_read_b128 v[200:203], v145 offset:2048
	ds_read_b128 v[204:207], v145 offset:3072
	ds_read_b128 v[208:211], v145 offset:4096
	ds_read_b128 v[212:215], v145 offset:5120
	ds_read_b128 v[216:219], v145 offset:6144
	ds_read_b128 v[220:223], v145 offset:7168
	global_load_lds_dwordx4 v[166:167], off
	v_lshl_add_u64 v[166:167], s[42:43], 0, v[134:135]
	s_add_i32 m0, s7, 0xe000
	s_nop 0
	global_load_lds_dwordx4 v[166:167], off
	s_waitcnt vmcnt(8)
	s_waitcnt lgkmcnt(0)
	s_barrier
	s_setprio 1
	s_waitcnt lgkmcnt(0)
	v_mfma_f32_16x16x32_bf16 v[124:127], v[138:141], v[192:195], 0
	v_mfma_f32_16x16x32_bf16 v[120:123], v[150:153], v[192:195], 0
	v_mfma_f32_16x16x32_bf16 v[116:119], v[138:141], v[200:203], 0
	v_mfma_f32_16x16x32_bf16 v[108:111], v[150:153], v[200:203], 0
	v_mfma_f32_16x16x32_bf16 v[100:103], v[138:141], v[208:211], 0
	v_mfma_f32_16x16x32_bf16 v[92:95], v[150:153], v[208:211], 0
	v_mfma_f32_16x16x32_bf16 v[84:87], v[138:141], v[216:219], 0
	v_mfma_f32_16x16x32_bf16 v[76:79], v[150:153], v[216:219], 0
	v_mfma_f32_16x16x32_bf16 v[124:127], v[146:149], v[196:199], v[124:127]
	v_mfma_f32_16x16x32_bf16 v[120:123], v[154:157], v[196:199], v[120:123]
	v_mfma_f32_16x16x32_bf16 v[116:119], v[146:149], v[204:207], v[116:119]
	v_mfma_f32_16x16x32_bf16 v[108:111], v[154:157], v[204:207], v[108:111]
	v_mfma_f32_16x16x32_bf16 v[100:103], v[146:149], v[212:215], v[100:103]
	v_mfma_f32_16x16x32_bf16 v[92:95], v[154:157], v[212:215], v[92:95]
	v_mfma_f32_16x16x32_bf16 v[84:87], v[146:149], v[220:223], v[84:87]
	v_mfma_f32_16x16x32_bf16 v[76:79], v[154:157], v[220:223], v[76:79]
	s_setprio 0
	s_setprio 1
	v_mfma_f32_16x16x32_bf16 v[112:115], v[158:161], v[192:195], 0
	v_mfma_f32_16x16x32_bf16 v[104:107], v[170:173], v[192:195], 0
	v_mfma_f32_16x16x32_bf16 v[96:99], v[158:161], v[200:203], 0
	v_mfma_f32_16x16x32_bf16 v[88:91], v[170:173], v[200:203], 0
	v_mfma_f32_16x16x32_bf16 v[80:83], v[158:161], v[208:211], 0
	v_mfma_f32_16x16x32_bf16 v[72:75], v[170:173], v[208:211], 0
	v_mfma_f32_16x16x32_bf16 v[68:71], v[158:161], v[216:219], 0
	v_mfma_f32_16x16x32_bf16 v[64:67], v[170:173], v[216:219], 0
	v_mfma_f32_16x16x32_bf16 v[112:115], v[162:165], v[196:199], v[112:115]
	v_mfma_f32_16x16x32_bf16 v[104:107], v[188:191], v[196:199], v[104:107]
	v_mfma_f32_16x16x32_bf16 v[96:99], v[162:165], v[204:207], v[96:99]
	v_mfma_f32_16x16x32_bf16 v[88:91], v[188:191], v[204:207], v[88:91]
	v_mfma_f32_16x16x32_bf16 v[80:83], v[162:165], v[212:215], v[80:83]
	s_add_i32 s59, s59, s6
	v_mfma_f32_16x16x32_bf16 v[72:75], v[188:191], v[212:215], v[72:75]
	v_lshl_add_u64 v[166:167], s[44:45], 0, v[168:169]
	v_mfma_f32_16x16x32_bf16 v[68:71], v[162:165], v[220:223], v[68:71]
	s_mov_b32 m0, s59
	v_mfma_f32_16x16x32_bf16 v[64:67], v[188:191], v[220:223], v[64:67]
	s_setprio 0
	s_barrier
	ds_read_b128 v[192:195], v145 offset:16384
	ds_read_b128 v[196:199], v145 offset:17408
	ds_read_b128 v[200:203], v145 offset:18432
	ds_read_b128 v[204:207], v145 offset:19456
	ds_read_b128 v[208:211], v145 offset:20480
	ds_read_b128 v[212:215], v145 offset:21504
	ds_read_b128 v[216:219], v145 offset:22528
	ds_read_b128 v[220:223], v145 offset:23552
	global_load_lds_dwordx4 v[166:167], off
	s_add_i32 m0, s59, 0x2000
	s_add_u32 s60, s44, 0x40000
	v_lshl_add_u64 v[178:179], s[44:45], 0, v[128:129]
	s_addc_u32 s61, s45, 0
	s_add_i32 s59, s62, s6
	global_load_lds_dwordx4 v[178:179], off
	v_lshl_add_u64 v[224:225], s[60:61], 0, v[168:169]
	s_mov_b32 m0, s59
	v_lshl_add_u64 v[234:235], s[46:47], 0, v[130:131]
	global_load_lds_dwordx4 v[224:225], off
	v_lshl_add_u64 v[224:225], s[60:61], 0, v[128:129]
	s_add_i32 m0, s59, 0x2000
	s_nop 0
	global_load_lds_dwordx4 v[224:225], off
	v_lshl_add_u64 v[224:225], s[46:47], 0, v[132:133]
	s_mov_b32 m0, s7
	s_nop 0
	global_load_lds_dwordx4 v[224:225], off
	s_mov_b32 m0, s34
	s_nop 0
	global_load_lds_dwordx4 v[234:235], off
	s_waitcnt vmcnt(8)
	s_waitcnt lgkmcnt(0)
	s_barrier
; #define PG8_STAGE(bufoff, gbase, voff) do { _Pragma("unroll") for (int _i = 0; _i < 2; ++_i) \
;         __builtin_amdgcn_global_load_lds((const unsigned*)((const char*)(gbase) + (voff)[_i]), (PG8_LAS unsigned*)(lds + (bufoff) + ldsw + _i * 8192), 16, 0, 0); } while (0)
; #define PG8_LDA(dst, b, h) do { _Pragma("unroll") for (int m = 0; m < 4; ++m) _Pragma("unroll") for (int k = 0; k < 2; ++k) dst[m][k] = *(const PG8_LAS bf16x8*)(lds + PG8_SA(b, h) + aoff + m * 2048 + k * 1024); } while (0)
; #define PG8_LDB(dst, b, h) do { _Pragma("unroll") for (int n = 0; n < 2; ++n) _Pragma("unroll") for (int k = 0; k < 2; ++k) dst[n][k] = *(const PG8_LAS bf16x8*)(lds + PG8_SB(b, h) + boff + n * 2048 + k * 1024); } while (0)
; #define PG8_MMA(ai, bj, At, Bt) do { __builtin_amdgcn_s_setprio(1); _Pragma("unroll") for (int m = 0; m < 4; ++m) _Pragma("unroll") for (int n = 0; n < 2; ++n) _Pragma("unroll") for (int k = 0; k < 2; ++k) \
;         acc[ai][bj][m][n] = __builtin_amdgcn_mfma_f32_16x16x32_bf16(Bt[n][k], At[m][k], acc[ai][bj][m][n], 0, 0, 0); __builtin_amdgcn_s_setprio(0); } while (0)
; #define PG8_WAIT_V(n) asm volatile("s_waitcnt vmcnt(" #n ")" ::: "memory")
; #define PG8_WAIT_L(n) asm volatile("s_waitcnt lgkmcnt(" #n ")" ::: "memory")
; #define PG8_BAR __builtin_amdgcn_s_barrier()
; #define PG8_SCHED __builtin_amdgcn_sched_barrier(0)
; template <class Epi, class Sched, bool ALIGN_EPI = false, bool SP2 = false>
; __device__ __forceinline__ void gemm_phase(PG8_LAS unsigned char* lds, const Gemm g, const Sched& S, const Epi& E) {
;     ...
;             PG8_WAIT_V(8); PG8_WAIT_L(0); PG8_BAR; PG8_MMA(1, 0, At, B0); PG8_MMA(1, 1, At, B1); PG8_BAR; PG8_SCHED;
;             PG8_LDB(B0, 1, 0); PG8_LDB(B1, 1, 1); PG8_SCHED; PG8_LDA(At, 1, 0); PG8_STAGE(PG8_SA(0, 1), a2 + hstepA, voffA);
;             PG8_WAIT_V(8); PG8_WAIT_L(0); PG8_BAR; PG8_MMA(0, 0, At, B0); PG8_MMA(0, 1, At, B1); PG8_BAR; PG8_SCHED;
	s_setprio 1
	s_waitcnt lgkmcnt(0)
	v_mfma_f32_16x16x32_bf16 v[60:63], v[138:141], v[192:195], 0
	v_mfma_f32_16x16x32_bf16 v[56:59], v[150:153], v[192:195], 0
	v_mfma_f32_16x16x32_bf16 v[52:55], v[138:141], v[200:203], 0
	v_mfma_f32_16x16x32_bf16 v[44:47], v[150:153], v[200:203], 0
	v_mfma_f32_16x16x32_bf16 v[36:39], v[138:141], v[208:211], 0
	v_mfma_f32_16x16x32_bf16 v[28:31], v[150:153], v[208:211], 0
	v_mfma_f32_16x16x32_bf16 v[20:23], v[138:141], v[216:219], 0
	v_mfma_f32_16x16x32_bf16 v[12:15], v[150:153], v[216:219], 0
	v_mfma_f32_16x16x32_bf16 v[60:63], v[146:149], v[196:199], v[60:63]
	v_mfma_f32_16x16x32_bf16 v[56:59], v[154:157], v[196:199], v[56:59]
	v_mfma_f32_16x16x32_bf16 v[52:55], v[146:149], v[204:207], v[52:55]
	v_mfma_f32_16x16x32_bf16 v[44:47], v[154:157], v[204:207], v[44:47]
	v_mfma_f32_16x16x32_bf16 v[36:39], v[146:149], v[212:215], v[36:39]
	v_mfma_f32_16x16x32_bf16 v[28:31], v[154:157], v[212:215], v[28:31]
	v_mfma_f32_16x16x32_bf16 v[20:23], v[146:149], v[220:223], v[20:23]
	v_mfma_f32_16x16x32_bf16 v[12:15], v[154:157], v[220:223], v[12:15]
	s_setprio 0
	s_setprio 1
	v_mfma_f32_16x16x32_bf16 v[48:51], v[158:161], v[192:195], 0
	v_mfma_f32_16x16x32_bf16 v[40:43], v[170:173], v[192:195], 0
	v_mfma_f32_16x16x32_bf16 v[32:35], v[158:161], v[200:203], 0
	v_mfma_f32_16x16x32_bf16 v[24:27], v[170:173], v[200:203], 0
	v_mfma_f32_16x16x32_bf16 v[16:19], v[158:161], v[208:211], 0
	v_mfma_f32_16x16x32_bf16 v[8:11], v[170:173], v[208:211], 0
	v_mfma_f32_16x16x32_bf16 v[4:7], v[158:161], v[216:219], 0
	v_mfma_f32_16x16x32_bf16 v[0:3], v[170:173], v[216:219], 0
	v_mfma_f32_16x16x32_bf16 v[48:51], v[162:165], v[196:199], v[48:51]
	v_mfma_f32_16x16x32_bf16 v[40:43], v[188:191], v[196:199], v[40:43]
	v_mfma_f32_16x16x32_bf16 v[32:35], v[162:165], v[204:207], v[32:35]
	v_mfma_f32_16x16x32_bf16 v[24:27], v[188:191], v[204:207], v[24:27]
	s_add_i32 s59, 0, 0x18000
	v_mfma_f32_16x16x32_bf16 v[16:19], v[162:165], v[212:215], v[16:19]
	s_add_i32 s60, 0, 0x1c000
	v_mfma_f32_16x16x32_bf16 v[8:11], v[188:191], v[212:215], v[8:11]
	v_add_u32_e32 v240, s59, v143
	v_mfma_f32_16x16x32_bf16 v[4:7], v[162:165], v[220:223], v[4:7]
	v_add_u32_e32 v241, s60, v143
	v_mfma_f32_16x16x32_bf16 v[0:3], v[188:191], v[220:223], v[0:3]
	s_setprio 0
	s_barrier
	ds_read_b128 v[138:141], v240
	ds_read_b128 v[146:149], v240 offset:1024
	ds_read_b128 v[150:153], v240 offset:2048
	ds_read_b128 v[154:157], v240 offset:3072
	ds_read_b128 v[158:161], v241
	ds_read_b128 v[162:165], v241 offset:1024
	ds_read_b128 v[170:173], v241 offset:2048
	ds_read_b128 v[188:191], v241 offset:3072
	s_add_u32 s46, s46, 0x40000
	s_addc_u32 s47, s47, 0
	s_mov_b32 m0, s35
	v_lshl_add_u64 v[236:237], s[46:47], 0, v[132:133]
	ds_read_b128 v[192:195], v145 offset:32768
	ds_read_b128 v[196:199], v145 offset:33792
	ds_read_b128 v[200:203], v145 offset:34816
	ds_read_b128 v[204:207], v145 offset:35840
	ds_read_b128 v[208:211], v145 offset:36864
	ds_read_b128 v[212:215], v145 offset:37888
	ds_read_b128 v[216:219], v145 offset:38912
	ds_read_b128 v[220:223], v145 offset:39936
	global_load_lds_dwordx4 v[236:237], off
	v_lshl_add_u64 v[236:237], s[46:47], 0, v[130:131]
	s_mov_b32 m0, s48
	s_nop 0
	global_load_lds_dwordx4 v[236:237], off
	s_waitcnt vmcnt(8)
	s_waitcnt lgkmcnt(0)
	s_barrier
	s_setprio 1
	s_waitcnt lgkmcnt(0)
	v_mfma_f32_16x16x32_bf16 v[124:127], v[138:141], v[192:195], v[124:127]
	v_mfma_f32_16x16x32_bf16 v[120:123], v[150:153], v[192:195], v[120:123]
	v_mfma_f32_16x16x32_bf16 v[116:119], v[138:141], v[200:203], v[116:119]
	v_mfma_f32_16x16x32_bf16 v[108:111], v[150:153], v[200:203], v[108:111]
	v_mfma_f32_16x16x32_bf16 v[100:103], v[138:141], v[208:211], v[100:103]
	v_mfma_f32_16x16x32_bf16 v[92:95], v[150:153], v[208:211], v[92:95]
	v_mfma_f32_16x16x32_bf16 v[84:87], v[138:141], v[216:219], v[84:87]
	v_mfma_f32_16x16x32_bf16 v[76:79], v[150:153], v[216:219], v[76:79]
	v_mfma_f32_16x16x32_bf16 v[124:127], v[146:149], v[196:199], v[124:127]
	v_mfma_f32_16x16x32_bf16 v[120:123], v[154:157], v[196:199], v[120:123]
	v_mfma_f32_16x16x32_bf16 v[116:119], v[146:149], v[204:207], v[116:119]
	v_mfma_f32_16x16x32_bf16 v[108:111], v[154:157], v[204:207], v[108:111]
	v_mfma_f32_16x16x32_bf16 v[100:103], v[146:149], v[212:215], v[100:103]
	v_mfma_f32_16x16x32_bf16 v[92:95], v[154:157], v[212:215], v[92:95]
	v_mfma_f32_16x16x32_bf16 v[84:87], v[146:149], v[220:223], v[84:87]
	v_mfma_f32_16x16x32_bf16 v[76:79], v[154:157], v[220:223], v[76:79]
	s_setprio 0
	s_setprio 1
	v_mfma_f32_16x16x32_bf16 v[112:115], v[158:161], v[192:195], v[112:115]
	v_mfma_f32_16x16x32_bf16 v[104:107], v[170:173], v[192:195], v[104:107]
	v_mfma_f32_16x16x32_bf16 v[96:99], v[158:161], v[200:203], v[96:99]
	v_mfma_f32_16x16x32_bf16 v[88:91], v[170:173], v[200:203], v[88:91]
	v_mfma_f32_16x16x32_bf16 v[80:83], v[158:161], v[208:211], v[80:83]
	v_mfma_f32_16x16x32_bf16 v[72:75], v[170:173], v[208:211], v[72:75]
	v_mfma_f32_16x16x32_bf16 v[68:71], v[158:161], v[216:219], v[68:71]
	v_mfma_f32_16x16x32_bf16 v[64:67], v[170:173], v[216:219], v[64:67]
	v_mfma_f32_16x16x32_bf16 v[112:115], v[162:165], v[196:199], v[112:115]
	v_mfma_f32_16x16x32_bf16 v[104:107], v[188:191], v[196:199], v[104:107]
	v_mfma_f32_16x16x32_bf16 v[96:99], v[162:165], v[204:207], v[96:99]
	v_mfma_f32_16x16x32_bf16 v[88:91], v[188:191], v[204:207], v[88:91]
	v_mfma_f32_16x16x32_bf16 v[80:83], v[162:165], v[212:215], v[80:83]
	s_add_i32 s46, s59, s6
	v_mfma_f32_16x16x32_bf16 v[72:75], v[188:191], v[212:215], v[72:75]
	v_lshl_add_u64 v[166:167], v[166:167], 0, s[30:31]
	v_mfma_f32_16x16x32_bf16 v[68:71], v[162:165], v[220:223], v[68:71]
	s_mov_b32 m0, s46
	v_mfma_f32_16x16x32_bf16 v[64:67], v[188:191], v[220:223], v[64:67]
	s_setprio 0
	s_barrier
; #define PG8_STAGE(bufoff, gbase, voff) do { _Pragma("unroll") for (int _i = 0; _i < 2; ++_i) \
;         __builtin_amdgcn_global_load_lds((const unsigned*)((const char*)(gbase) + (voff)[_i]), (PG8_LAS unsigned*)(lds + (bufoff) + ldsw + _i * 8192), 16, 0, 0); } while (0)
; #define PG8_LDA(dst, b, h) do { _Pragma("unroll") for (int m = 0; m < 4; ++m) _Pragma("unroll") for (int k = 0; k < 2; ++k) dst[m][k] = *(const PG8_LAS bf16x8*)(lds + PG8_SA(b, h) + aoff + m * 2048 + k * 1024); } while (0)
; #define PG8_LDB(dst, b, h) do { _Pragma("unroll") for (int n = 0; n < 2; ++n) _Pragma("unroll") for (int k = 0; k < 2; ++k) dst[n][k] = *(const PG8_LAS bf16x8*)(lds + PG8_SB(b, h) + boff + n * 2048 + k * 1024); } while (0)
; #define PG8_MMA(ai, bj, At, Bt) do { __builtin_amdgcn_s_setprio(1); _Pragma("unroll") for (int m = 0; m < 4; ++m) _Pragma("unroll") for (int n = 0; n < 2; ++n) _Pragma("unroll") for (int k = 0; k < 2; ++k) \
;         acc[ai][bj][m][n] = __builtin_amdgcn_mfma_f32_16x16x32_bf16(Bt[n][k], At[m][k], acc[ai][bj][m][n], 0, 0, 0); __builtin_amdgcn_s_setprio(0); } while (0)
; #define PG8_WAIT_V(n) asm volatile("s_waitcnt vmcnt(" #n ")" ::: "memory")
; template <class Epi, class Sched, bool ALIGN_EPI = false, bool SP2 = false>
; __device__ __forceinline__ void gemm_phase(PG8_LAS unsigned char* lds, const Gemm g, const Sched& S, const Epi& E) {
;     ...
;             PG8_LDB(B0, 0, 0); PG8_LDB(B1, 0, 1); PG8_SCHED; PG8_LDA(At, 0, 0); PG8_STAGE(PG8_SA(1, 1), a1 + hstepA, voffA);
;             PG8_WAIT_V(8); PG8_WAIT_L(0); PG8_BAR; PG8_MMA(0, 0, At, B0); PG8_MMA(0, 1, At, B1); PG8_BAR; PG8_SCHED;
;             PG8_LDA(At, 0, 1); PG8_STAGE(PG8_SB(0, 0), b2, voffB); PG8_STAGE(PG8_SB(0, 1), b2 + hstep, voffB); PG8_STAGE(PG8_SA(0, 0), a2, voffA);
;             PG8_WAIT_V(8); PG8_WAIT_L(0); PG8_BAR; PG8_MMA(1, 0, At, B0); PG8_MMA(1, 1, At, B1); PG8_BAR; PG8_SCHED;
;             PG8_LDB(B0, 1, 0); PG8_LDB(B1, 1, 1); PG8_SCHED; PG8_LDA(At, 1, 0); PG8_STAGE(PG8_SA(0, 1), a2 + hstepA, voffA);
;             PG8_WAIT_V(8); PG8_WAIT_L(0); PG8_BAR; PG8_MMA(0, 0, At, B0); PG8_MMA(0, 1, At, B1); PG8_BAR; PG8_SCHED;
;             PG8_LDA(At, 1, 1); PG8_STAGE(PG8_SB(1, 0), b3, voffB); PG8_STAGE(PG8_SB(1, 1), b3 + hstep, voffB); PG8_STAGE(PG8_SA(1, 0), a3, voffA);
;             PG8_WAIT_V(8); PG8_WAIT_L(0); PG8_BAR; PG8_MMA(1, 0, At, B0); PG8_MMA(1, 1, At, B1); PG8_BAR; PG8_SCHED;
	ds_read_b128 v[192:195], v145 offset:49152
	ds_read_b128 v[196:199], v145 offset:50176
	ds_read_b128 v[200:203], v145 offset:51200
	ds_read_b128 v[204:207], v145 offset:52224
	ds_read_b128 v[208:211], v145 offset:53248
	ds_read_b128 v[212:215], v145 offset:54272
	ds_read_b128 v[216:219], v145 offset:55296
	ds_read_b128 v[220:223], v145 offset:56320
	global_load_lds_dwordx4 v[166:167], off
	s_add_i32 m0, s46, 0x2000
	s_add_u32 s44, s44, 0x40080
	v_lshl_add_u64 v[166:167], v[178:179], 0, s[30:31]
	s_addc_u32 s45, s45, 0
	s_add_i32 s46, s60, s6
	global_load_lds_dwordx4 v[166:167], off
	v_lshl_add_u64 v[166:167], s[44:45], 0, v[168:169]
	s_mov_b32 m0, s46
	s_nop 0
	global_load_lds_dwordx4 v[166:167], off
	v_lshl_add_u64 v[166:167], s[44:45], 0, v[128:129]
	s_add_i32 m0, s46, 0x2000
	s_nop 0
	global_load_lds_dwordx4 v[166:167], off
	v_lshl_add_u64 v[166:167], v[224:225], 0, s[30:31]
	s_mov_b32 m0, s49
	s_nop 0
	global_load_lds_dwordx4 v[166:167], off
	v_lshl_add_u64 v[166:167], v[234:235], 0, s[30:31]
	s_mov_b32 m0, s50
	s_nop 0
	global_load_lds_dwordx4 v[166:167], off
	s_waitcnt vmcnt(8)
	s_waitcnt lgkmcnt(0)
	s_barrier
	s_setprio 1
	s_waitcnt lgkmcnt(0)
	v_mfma_f32_16x16x32_bf16 v[60:63], v[138:141], v[192:195], v[60:63]
	v_mfma_f32_16x16x32_bf16 v[56:59], v[150:153], v[192:195], v[56:59]
	v_mfma_f32_16x16x32_bf16 v[52:55], v[138:141], v[200:203], v[52:55]
	v_mfma_f32_16x16x32_bf16 v[44:47], v[150:153], v[200:203], v[44:47]
	v_mfma_f32_16x16x32_bf16 v[36:39], v[138:141], v[208:211], v[36:39]
	v_mfma_f32_16x16x32_bf16 v[28:31], v[150:153], v[208:211], v[28:31]
	v_mfma_f32_16x16x32_bf16 v[20:23], v[138:141], v[216:219], v[20:23]
	v_mfma_f32_16x16x32_bf16 v[12:15], v[150:153], v[216:219], v[12:15]
	v_mfma_f32_16x16x32_bf16 v[60:63], v[146:149], v[196:199], v[60:63]
	v_mfma_f32_16x16x32_bf16 v[56:59], v[154:157], v[196:199], v[56:59]
	v_mfma_f32_16x16x32_bf16 v[52:55], v[146:149], v[204:207], v[52:55]
	v_mfma_f32_16x16x32_bf16 v[44:47], v[154:157], v[204:207], v[44:47]
	v_mfma_f32_16x16x32_bf16 v[36:39], v[146:149], v[212:215], v[36:39]
	v_mfma_f32_16x16x32_bf16 v[28:31], v[154:157], v[212:215], v[28:31]
	v_mfma_f32_16x16x32_bf16 v[20:23], v[146:149], v[220:223], v[20:23]
	v_mfma_f32_16x16x32_bf16 v[12:15], v[154:157], v[220:223], v[12:15]
	s_add_i32 s58, s58, 2
	s_setprio 0
	s_setprio 1
	v_mfma_f32_16x16x32_bf16 v[48:51], v[158:161], v[192:195], v[48:51]
	s_add_u32 s56, s56, 0x100
	v_mfma_f32_16x16x32_bf16 v[40:43], v[170:173], v[192:195], v[40:43]
	s_addc_u32 s57, s57, 0
	v_mfma_f32_16x16x32_bf16 v[32:35], v[158:161], v[200:203], v[32:35]
	s_add_u32 s42, s42, 0x100
	v_mfma_f32_16x16x32_bf16 v[24:27], v[170:173], v[200:203], v[24:27]
	s_addc_u32 s43, s43, 0
	v_mfma_f32_16x16x32_bf16 v[16:19], v[158:161], v[208:211], v[16:19]
	s_add_u32 s44, s42, 0xfffc0080
	v_mfma_f32_16x16x32_bf16 v[8:11], v[170:173], v[208:211], v[8:11]
	s_addc_u32 s45, s43, -1
	v_mfma_f32_16x16x32_bf16 v[4:7], v[158:161], v[216:219], v[4:7]
	s_add_i32 s59, 0, 0x10000
	v_mfma_f32_16x16x32_bf16 v[0:3], v[170:173], v[216:219], v[0:3]
	s_cmp_eq_u32 s58, 12
	v_mfma_f32_16x16x32_bf16 v[48:51], v[162:165], v[196:199], v[48:51]
	s_cselect_b32 s47, s27, s45
	v_mfma_f32_16x16x32_bf16 v[40:43], v[188:191], v[196:199], v[40:43]
	s_cselect_b32 s46, s54, s44
	v_mfma_f32_16x16x32_bf16 v[32:35], v[162:165], v[204:207], v[32:35]
	s_cselect_b32 s45, s25, s57
	v_mfma_f32_16x16x32_bf16 v[24:27], v[188:191], v[204:207], v[24:27]
	s_cselect_b32 s44, s55, s56
	v_mfma_f32_16x16x32_bf16 v[16:19], v[162:165], v[212:215], v[16:19]
	s_add_i32 s62, 0, 0x14000
	v_mfma_f32_16x16x32_bf16 v[8:11], v[188:191], v[212:215], v[8:11]
	v_add_u32_e32 v242, s59, v143
	v_mfma_f32_16x16x32_bf16 v[4:7], v[162:165], v[220:223], v[4:7]
	v_add_u32_e32 v166, s62, v143
	v_mfma_f32_16x16x32_bf16 v[0:3], v[188:191], v[220:223], v[0:3]
	s_setprio 0
	s_barrier
.LBB0_196:
	ds_read_b128 v[138:141], v242
	ds_read_b128 v[146:149], v242 offset:1024
	ds_read_b128 v[150:153], v242 offset:2048
	ds_read_b128 v[154:157], v242 offset:3072
	ds_read_b128 v[158:161], v166
	ds_read_b128 v[162:165], v166 offset:1024
	ds_read_b128 v[170:173], v166 offset:2048
	ds_read_b128 v[188:191], v166 offset:3072
	v_lshl_add_u64 v[166:167], s[42:43], 0, v[136:137]
	s_add_i32 m0, s7, 0xc000
	ds_read_b128 v[192:195], v145
	ds_read_b128 v[196:199], v145 offset:1024
	ds_read_b128 v[200:203], v145 offset:2048
	ds_read_b128 v[204:207], v145 offset:3072
	ds_read_b128 v[208:211], v145 offset:4096
	ds_read_b128 v[212:215], v145 offset:5120
	ds_read_b128 v[216:219], v145 offset:6144
	ds_read_b128 v[220:223], v145 offset:7168
	global_load_lds_dwordx4 v[166:167], off
	v_lshl_add_u64 v[166:167], s[42:43], 0, v[134:135]
	s_add_i32 m0, s7, 0xe000
	s_nop 0
	global_load_lds_dwordx4 v[166:167], off
	s_waitcnt vmcnt(8)
	s_waitcnt lgkmcnt(0)
	s_barrier
; #define PG8_STAGE(bufoff, gbase, voff) do { _Pragma("unroll") for (int _i = 0; _i < 2; ++_i) \
;         __builtin_amdgcn_global_load_lds((const unsigned*)((const char*)(gbase) + (voff)[_i]), (PG8_LAS unsigned*)(lds + (bufoff) + ldsw + _i * 8192), 16, 0, 0); } while (0)
; #define PG8_LDA(dst, b, h) do { _Pragma("unroll") for (int m = 0; m < 4; ++m) _Pragma("unroll") for (int k = 0; k < 2; ++k) dst[m][k] = *(const PG8_LAS bf16x8*)(lds + PG8_SA(b, h) + aoff + m * 2048 + k * 1024); } while (0)
; #define PG8_LDB(dst, b, h) do { _Pragma("unroll") for (int n = 0; n < 2; ++n) _Pragma("unroll") for (int k = 0; k < 2; ++k) dst[n][k] = *(const PG8_LAS bf16x8*)(lds + PG8_SB(b, h) + boff + n * 2048 + k * 1024); } while (0)
; #define PG8_MMA(ai, bj, At, Bt) do { __builtin_amdgcn_s_setprio(1); _Pragma("unroll") for (int m = 0; m < 4; ++m) _Pragma("unroll") for (int n = 0; n < 2; ++n) _Pragma("unroll") for (int k = 0; k < 2; ++k) \
;         acc[ai][bj][m][n] = __builtin_amdgcn_mfma_f32_16x16x32_bf16(Bt[n][k], At[m][k], acc[ai][bj][m][n], 0, 0, 0); __builtin_amdgcn_s_setprio(0); } while (0)
; #define PG8_WAIT_V(n) asm volatile("s_waitcnt vmcnt(" #n ")" ::: "memory")
; #define PG8_WAIT_L(n) asm volatile("s_waitcnt lgkmcnt(" #n ")" ::: "memory")
; #define PG8_BAR __builtin_amdgcn_s_barrier()
; #define PG8_SCHED __builtin_amdgcn_sched_barrier(0)
; template <class Epi, class Sched, bool ALIGN_EPI = false, bool SP2 = false>
; __device__ __forceinline__ void gemm_phase(PG8_LAS unsigned char* lds, const Gemm g, const Sched& S, const Epi& E) {
;     ...
;             PG8_WAIT_V(8); PG8_WAIT_L(0); PG8_BAR; PG8_MMA(0, 0, At, B0); PG8_MMA(0, 1, At, B1); PG8_BAR; PG8_SCHED;
;             PG8_LDA(At, 0, 1); PG8_STAGE(PG8_SB(0, 0), b2, voffB); PG8_STAGE(PG8_SB(0, 1), b2 + hstep, voffB); PG8_STAGE(PG8_SA(0, 0), a2, voffA);
;             PG8_WAIT_V(8); PG8_WAIT_L(0); PG8_BAR; PG8_MMA(1, 0, At, B0); PG8_MMA(1, 1, At, B1); PG8_BAR; PG8_SCHED;
;             PG8_LDB(B0, 1, 0); PG8_LDB(B1, 1, 1); PG8_SCHED; PG8_LDA(At, 1, 0); PG8_STAGE(PG8_SA(0, 1), a2 + hstepA, voffA);
	s_setprio 1
	s_waitcnt lgkmcnt(0)
	v_mfma_f32_16x16x32_bf16 v[124:127], v[138:141], v[192:195], v[124:127]
	v_mfma_f32_16x16x32_bf16 v[120:123], v[150:153], v[192:195], v[120:123]
	v_mfma_f32_16x16x32_bf16 v[116:119], v[138:141], v[200:203], v[116:119]
	v_mfma_f32_16x16x32_bf16 v[108:111], v[150:153], v[200:203], v[108:111]
	v_mfma_f32_16x16x32_bf16 v[100:103], v[138:141], v[208:211], v[100:103]
	v_mfma_f32_16x16x32_bf16 v[92:95], v[150:153], v[208:211], v[92:95]
	v_mfma_f32_16x16x32_bf16 v[84:87], v[138:141], v[216:219], v[84:87]
	v_mfma_f32_16x16x32_bf16 v[76:79], v[150:153], v[216:219], v[76:79]
	v_mfma_f32_16x16x32_bf16 v[124:127], v[146:149], v[196:199], v[124:127]
	v_mfma_f32_16x16x32_bf16 v[120:123], v[154:157], v[196:199], v[120:123]
	v_mfma_f32_16x16x32_bf16 v[116:119], v[146:149], v[204:207], v[116:119]
	v_mfma_f32_16x16x32_bf16 v[108:111], v[154:157], v[204:207], v[108:111]
	v_mfma_f32_16x16x32_bf16 v[100:103], v[146:149], v[212:215], v[100:103]
	v_mfma_f32_16x16x32_bf16 v[92:95], v[154:157], v[212:215], v[92:95]
	v_mfma_f32_16x16x32_bf16 v[84:87], v[146:149], v[220:223], v[84:87]
	v_mfma_f32_16x16x32_bf16 v[76:79], v[154:157], v[220:223], v[76:79]
	s_setprio 0
	s_setprio 1
	v_mfma_f32_16x16x32_bf16 v[112:115], v[158:161], v[192:195], v[112:115]
	v_mfma_f32_16x16x32_bf16 v[104:107], v[170:173], v[192:195], v[104:107]
	v_mfma_f32_16x16x32_bf16 v[96:99], v[158:161], v[200:203], v[96:99]
	v_mfma_f32_16x16x32_bf16 v[88:91], v[170:173], v[200:203], v[88:91]
	v_mfma_f32_16x16x32_bf16 v[80:83], v[158:161], v[208:211], v[80:83]
	v_mfma_f32_16x16x32_bf16 v[72:75], v[170:173], v[208:211], v[72:75]
	v_mfma_f32_16x16x32_bf16 v[68:71], v[158:161], v[216:219], v[68:71]
	v_mfma_f32_16x16x32_bf16 v[64:67], v[170:173], v[216:219], v[64:67]
	v_mfma_f32_16x16x32_bf16 v[112:115], v[162:165], v[196:199], v[112:115]
	v_mfma_f32_16x16x32_bf16 v[104:107], v[188:191], v[196:199], v[104:107]
	v_mfma_f32_16x16x32_bf16 v[96:99], v[162:165], v[204:207], v[96:99]
	v_mfma_f32_16x16x32_bf16 v[88:91], v[188:191], v[204:207], v[88:91]
	v_mfma_f32_16x16x32_bf16 v[80:83], v[162:165], v[212:215], v[80:83]
	s_add_i32 s59, s59, s6
	v_mfma_f32_16x16x32_bf16 v[72:75], v[188:191], v[212:215], v[72:75]
	v_lshl_add_u64 v[166:167], s[44:45], 0, v[168:169]
	v_mfma_f32_16x16x32_bf16 v[68:71], v[162:165], v[220:223], v[68:71]
	s_mov_b32 m0, s59
	v_mfma_f32_16x16x32_bf16 v[64:67], v[188:191], v[220:223], v[64:67]
	s_setprio 0
	s_barrier
	ds_read_b128 v[192:195], v145 offset:16384
	ds_read_b128 v[196:199], v145 offset:17408
	ds_read_b128 v[200:203], v145 offset:18432
	ds_read_b128 v[204:207], v145 offset:19456
	ds_read_b128 v[208:211], v145 offset:20480
	ds_read_b128 v[212:215], v145 offset:21504
	ds_read_b128 v[216:219], v145 offset:22528
	ds_read_b128 v[220:223], v145 offset:23552
	global_load_lds_dwordx4 v[166:167], off
	s_add_i32 m0, s59, 0x2000
	s_add_u32 s60, s44, 0x40000
	v_lshl_add_u64 v[178:179], s[44:45], 0, v[128:129]
	s_addc_u32 s61, s45, 0
	s_add_i32 s59, s62, s6
	global_load_lds_dwordx4 v[178:179], off
	v_lshl_add_u64 v[224:225], s[60:61], 0, v[168:169]
	s_mov_b32 m0, s59
	v_lshl_add_u64 v[234:235], s[46:47], 0, v[130:131]
	global_load_lds_dwordx4 v[224:225], off
	v_lshl_add_u64 v[224:225], s[60:61], 0, v[128:129]
	s_add_i32 m0, s59, 0x2000
	s_nop 0
	global_load_lds_dwordx4 v[224:225], off
	v_lshl_add_u64 v[224:225], s[46:47], 0, v[132:133]
	s_mov_b32 m0, s7
	s_nop 0
	global_load_lds_dwordx4 v[224:225], off
	s_mov_b32 m0, s34
	s_nop 0
	global_load_lds_dwordx4 v[234:235], off
	s_waitcnt vmcnt(8)
	s_waitcnt lgkmcnt(0)
	s_barrier
	s_setprio 1
	s_waitcnt lgkmcnt(0)
	v_mfma_f32_16x16x32_bf16 v[60:63], v[138:141], v[192:195], v[60:63]
	v_mfma_f32_16x16x32_bf16 v[56:59], v[150:153], v[192:195], v[56:59]
	v_mfma_f32_16x16x32_bf16 v[52:55], v[138:141], v[200:203], v[52:55]
	v_mfma_f32_16x16x32_bf16 v[44:47], v[150:153], v[200:203], v[44:47]
	v_mfma_f32_16x16x32_bf16 v[36:39], v[138:141], v[208:211], v[36:39]
	v_mfma_f32_16x16x32_bf16 v[28:31], v[150:153], v[208:211], v[28:31]
	v_mfma_f32_16x16x32_bf16 v[20:23], v[138:141], v[216:219], v[20:23]
	v_mfma_f32_16x16x32_bf16 v[12:15], v[150:153], v[216:219], v[12:15]
	v_mfma_f32_16x16x32_bf16 v[60:63], v[146:149], v[196:199], v[60:63]
	v_mfma_f32_16x16x32_bf16 v[56:59], v[154:157], v[196:199], v[56:59]
	v_mfma_f32_16x16x32_bf16 v[52:55], v[146:149], v[204:207], v[52:55]
	v_mfma_f32_16x16x32_bf16 v[44:47], v[154:157], v[204:207], v[44:47]
	v_mfma_f32_16x16x32_bf16 v[36:39], v[146:149], v[212:215], v[36:39]
	v_mfma_f32_16x16x32_bf16 v[28:31], v[154:157], v[212:215], v[28:31]
	v_mfma_f32_16x16x32_bf16 v[20:23], v[146:149], v[220:223], v[20:23]
	v_mfma_f32_16x16x32_bf16 v[12:15], v[154:157], v[220:223], v[12:15]
	s_setprio 0
	s_setprio 1
	v_mfma_f32_16x16x32_bf16 v[48:51], v[158:161], v[192:195], v[48:51]
	v_mfma_f32_16x16x32_bf16 v[40:43], v[170:173], v[192:195], v[40:43]
	v_mfma_f32_16x16x32_bf16 v[32:35], v[158:161], v[200:203], v[32:35]
	v_mfma_f32_16x16x32_bf16 v[24:27], v[170:173], v[200:203], v[24:27]
	v_mfma_f32_16x16x32_bf16 v[16:19], v[158:161], v[208:211], v[16:19]
	v_mfma_f32_16x16x32_bf16 v[8:11], v[170:173], v[208:211], v[8:11]
	v_mfma_f32_16x16x32_bf16 v[4:7], v[158:161], v[216:219], v[4:7]
	v_mfma_f32_16x16x32_bf16 v[0:3], v[170:173], v[216:219], v[0:3]
	v_mfma_f32_16x16x32_bf16 v[48:51], v[162:165], v[196:199], v[48:51]
	v_mfma_f32_16x16x32_bf16 v[40:43], v[188:191], v[196:199], v[40:43]
	v_mfma_f32_16x16x32_bf16 v[32:35], v[162:165], v[204:207], v[32:35]
	v_mfma_f32_16x16x32_bf16 v[24:27], v[188:191], v[204:207], v[24:27]
	s_add_i32 s59, 0, 0x18000
	v_mfma_f32_16x16x32_bf16 v[16:19], v[162:165], v[212:215], v[16:19]
	s_add_i32 s60, 0, 0x1c000
	v_mfma_f32_16x16x32_bf16 v[8:11], v[188:191], v[212:215], v[8:11]
	v_add_u32_e32 v240, s59, v143
	v_mfma_f32_16x16x32_bf16 v[4:7], v[162:165], v[220:223], v[4:7]
	v_add_u32_e32 v241, s60, v143
	v_mfma_f32_16x16x32_bf16 v[0:3], v[188:191], v[220:223], v[0:3]
	s_setprio 0
	s_barrier
; #define PG8_STAGE(bufoff, gbase, voff) do { _Pragma("unroll") for (int _i = 0; _i < 2; ++_i) \
;         __builtin_amdgcn_global_load_lds((const unsigned*)((const char*)(gbase) + (voff)[_i]), (PG8_LAS unsigned*)(lds + (bufoff) + ldsw + _i * 8192), 16, 0, 0); } while (0)
; #define PG8_LDA(dst, b, h) do { _Pragma("unroll") for (int m = 0; m < 4; ++m) _Pragma("unroll") for (int k = 0; k < 2; ++k) dst[m][k] = *(const PG8_LAS bf16x8*)(lds + PG8_SA(b, h) + aoff + m * 2048 + k * 1024); } while (0)
; #define PG8_LDB(dst, b, h) do { _Pragma("unroll") for (int n = 0; n < 2; ++n) _Pragma("unroll") for (int k = 0; k < 2; ++k) dst[n][k] = *(const PG8_LAS bf16x8*)(lds + PG8_SB(b, h) + boff + n * 2048 + k * 1024); } while (0)
; #define PG8_MMA(ai, bj, At, Bt) do { __builtin_amdgcn_s_setprio(1); _Pragma("unroll") for (int m = 0; m < 4; ++m) _Pragma("unroll") for (int n = 0; n < 2; ++n) _Pragma("unroll") for (int k = 0; k < 2; ++k) \
;         acc[ai][bj][m][n] = __builtin_amdgcn_mfma_f32_16x16x32_bf16(Bt[n][k], At[m][k], acc[ai][bj][m][n], 0, 0, 0); __builtin_amdgcn_s_setprio(0); } while (0)
; #define PG8_WAIT_V(n) asm volatile("s_waitcnt vmcnt(" #n ")" ::: "memory")
; #define PG8_WAIT_L(n) asm volatile("s_waitcnt lgkmcnt(" #n ")" ::: "memory")
; #define PG8_BAR __builtin_amdgcn_s_barrier()
; #define PG8_SCHED __builtin_amdgcn_sched_barrier(0)
; template <class Epi, class Sched, bool ALIGN_EPI = false, bool SP2 = false>
; __device__ __forceinline__ void gemm_phase(PG8_LAS unsigned char* lds, const Gemm g, const Sched& S, const Epi& E) {
;     ...
;             PG8_LDB(B0, 1, 0); PG8_LDB(B1, 1, 1); PG8_SCHED; PG8_LDA(At, 1, 0); PG8_STAGE(PG8_SA(0, 1), a2 + hstepA, voffA);
;             PG8_WAIT_V(8); PG8_WAIT_L(0); PG8_BAR; PG8_MMA(0, 0, At, B0); PG8_MMA(0, 1, At, B1); PG8_BAR; PG8_SCHED;
;             PG8_LDA(At, 1, 1); PG8_STAGE(PG8_SB(1, 0), b3, voffB); PG8_STAGE(PG8_SB(1, 1), b3 + hstep, voffB); PG8_STAGE(PG8_SA(1, 0), a3, voffA);
	ds_read_b128 v[138:141], v240
	ds_read_b128 v[146:149], v240 offset:1024
	ds_read_b128 v[150:153], v240 offset:2048
	ds_read_b128 v[154:157], v240 offset:3072
	ds_read_b128 v[158:161], v241
	ds_read_b128 v[162:165], v241 offset:1024
	ds_read_b128 v[170:173], v241 offset:2048
	ds_read_b128 v[188:191], v241 offset:3072
	s_add_u32 s46, s46, 0x40000
	s_addc_u32 s47, s47, 0
	s_mov_b32 m0, s35
	v_lshl_add_u64 v[236:237], s[46:47], 0, v[132:133]
	ds_read_b128 v[192:195], v145 offset:32768
	ds_read_b128 v[196:199], v145 offset:33792
	ds_read_b128 v[200:203], v145 offset:34816
	ds_read_b128 v[204:207], v145 offset:35840
	ds_read_b128 v[208:211], v145 offset:36864
	ds_read_b128 v[212:215], v145 offset:37888
	ds_read_b128 v[216:219], v145 offset:38912
	ds_read_b128 v[220:223], v145 offset:39936
	global_load_lds_dwordx4 v[236:237], off
	v_lshl_add_u64 v[236:237], s[46:47], 0, v[130:131]
	s_mov_b32 m0, s48
	s_nop 0
	global_load_lds_dwordx4 v[236:237], off
	s_waitcnt vmcnt(8)
	s_waitcnt lgkmcnt(0)
	s_barrier
	s_setprio 1
	s_waitcnt lgkmcnt(0)
	v_mfma_f32_16x16x32_bf16 v[124:127], v[138:141], v[192:195], v[124:127]
	v_mfma_f32_16x16x32_bf16 v[120:123], v[150:153], v[192:195], v[120:123]
	v_mfma_f32_16x16x32_bf16 v[116:119], v[138:141], v[200:203], v[116:119]
	v_mfma_f32_16x16x32_bf16 v[108:111], v[150:153], v[200:203], v[108:111]
	v_mfma_f32_16x16x32_bf16 v[100:103], v[138:141], v[208:211], v[100:103]
	v_mfma_f32_16x16x32_bf16 v[92:95], v[150:153], v[208:211], v[92:95]
	v_mfma_f32_16x16x32_bf16 v[84:87], v[138:141], v[216:219], v[84:87]
	v_mfma_f32_16x16x32_bf16 v[76:79], v[150:153], v[216:219], v[76:79]
	v_mfma_f32_16x16x32_bf16 v[124:127], v[146:149], v[196:199], v[124:127]
	v_mfma_f32_16x16x32_bf16 v[120:123], v[154:157], v[196:199], v[120:123]
	v_mfma_f32_16x16x32_bf16 v[116:119], v[146:149], v[204:207], v[116:119]
	v_mfma_f32_16x16x32_bf16 v[108:111], v[154:157], v[204:207], v[108:111]
	v_mfma_f32_16x16x32_bf16 v[100:103], v[146:149], v[212:215], v[100:103]
	v_mfma_f32_16x16x32_bf16 v[92:95], v[154:157], v[212:215], v[92:95]
	v_mfma_f32_16x16x32_bf16 v[84:87], v[146:149], v[220:223], v[84:87]
	v_mfma_f32_16x16x32_bf16 v[76:79], v[154:157], v[220:223], v[76:79]
	s_setprio 0
	s_setprio 1
	v_mfma_f32_16x16x32_bf16 v[112:115], v[158:161], v[192:195], v[112:115]
	v_mfma_f32_16x16x32_bf16 v[104:107], v[170:173], v[192:195], v[104:107]
	v_mfma_f32_16x16x32_bf16 v[96:99], v[158:161], v[200:203], v[96:99]
	v_mfma_f32_16x16x32_bf16 v[88:91], v[170:173], v[200:203], v[88:91]
	v_mfma_f32_16x16x32_bf16 v[80:83], v[158:161], v[208:211], v[80:83]
	v_mfma_f32_16x16x32_bf16 v[72:75], v[170:173], v[208:211], v[72:75]
	v_mfma_f32_16x16x32_bf16 v[68:71], v[158:161], v[216:219], v[68:71]
	v_mfma_f32_16x16x32_bf16 v[64:67], v[170:173], v[216:219], v[64:67]
	v_mfma_f32_16x16x32_bf16 v[112:115], v[162:165], v[196:199], v[112:115]
	v_mfma_f32_16x16x32_bf16 v[104:107], v[188:191], v[196:199], v[104:107]
	v_mfma_f32_16x16x32_bf16 v[96:99], v[162:165], v[204:207], v[96:99]
	v_mfma_f32_16x16x32_bf16 v[88:91], v[188:191], v[204:207], v[88:91]
	v_mfma_f32_16x16x32_bf16 v[80:83], v[162:165], v[212:215], v[80:83]
	s_add_i32 s46, s59, s6
	v_mfma_f32_16x16x32_bf16 v[72:75], v[188:191], v[212:215], v[72:75]
	v_lshl_add_u64 v[166:167], v[166:167], 0, s[30:31]
	v_mfma_f32_16x16x32_bf16 v[68:71], v[162:165], v[220:223], v[68:71]
	s_mov_b32 m0, s46
	v_mfma_f32_16x16x32_bf16 v[64:67], v[188:191], v[220:223], v[64:67]
	s_setprio 0
	s_barrier
; #define PG8_STAGE(bufoff, gbase, voff) do { _Pragma("unroll") for (int _i = 0; _i < 2; ++_i) \
;         __builtin_amdgcn_global_load_lds((const unsigned*)((const char*)(gbase) + (voff)[_i]), (PG8_LAS unsigned*)(lds + (bufoff) + ldsw + _i * 8192), 16, 0, 0); } while (0)
; #define PG8_LDA(dst, b, h) do { _Pragma("unroll") for (int m = 0; m < 4; ++m) _Pragma("unroll") for (int k = 0; k < 2; ++k) dst[m][k] = *(const PG8_LAS bf16x8*)(lds + PG8_SA(b, h) + aoff + m * 2048 + k * 1024); } while (0)
; #define PG8_MMA(ai, bj, At, Bt) do { __builtin_amdgcn_s_setprio(1); _Pragma("unroll") for (int m = 0; m < 4; ++m) _Pragma("unroll") for (int n = 0; n < 2; ++n) _Pragma("unroll") for (int k = 0; k < 2; ++k) \
;         acc[ai][bj][m][n] = __builtin_amdgcn_mfma_f32_16x16x32_bf16(Bt[n][k], At[m][k], acc[ai][bj][m][n], 0, 0, 0); __builtin_amdgcn_s_setprio(0); } while (0)
; #define PG8_WAIT_V(n) asm volatile("s_waitcnt vmcnt(" #n ")" ::: "memory")
; #define PG8_WAIT_L(n) asm volatile("s_waitcnt lgkmcnt(" #n ")" ::: "memory")
; #define PG8_BAR __builtin_amdgcn_s_barrier()
; #define PG8_SCHED __builtin_amdgcn_sched_barrier(0)
; template <class Epi, class Sched, bool ALIGN_EPI = false, bool SP2 = false>
; __device__ __forceinline__ void gemm_phase(PG8_LAS unsigned char* lds, const Gemm g, const Sched& S, const Epi& E) {
;     ...
;             PG8_LDA(At, 1, 1); PG8_STAGE(PG8_SB(1, 0), b3, voffB); PG8_STAGE(PG8_SB(1, 1), b3 + hstep, voffB); PG8_STAGE(PG8_SA(1, 0), a3, voffA);
;             PG8_WAIT_V(8); PG8_WAIT_L(0); PG8_BAR; PG8_MMA(1, 0, At, B0); PG8_MMA(1, 1, At, B1); PG8_BAR; PG8_SCHED;
;     ...
;         if constexpr (ALIGN_EPI) { if (wr == 0) PG8_BAR; }
	ds_read_b128 v[192:195], v145 offset:49152
	ds_read_b128 v[196:199], v145 offset:50176
	ds_read_b128 v[200:203], v145 offset:51200
	ds_read_b128 v[204:207], v145 offset:52224
	ds_read_b128 v[208:211], v145 offset:53248
	ds_read_b128 v[212:215], v145 offset:54272
	ds_read_b128 v[216:219], v145 offset:55296
	ds_read_b128 v[220:223], v145 offset:56320
	global_load_lds_dwordx4 v[166:167], off
	s_add_i32 m0, s46, 0x2000
	s_add_u32 s44, s44, 0x40080
	v_lshl_add_u64 v[166:167], v[178:179], 0, s[30:31]
	s_addc_u32 s45, s45, 0
	s_add_i32 s46, s60, s6
	global_load_lds_dwordx4 v[166:167], off
	v_lshl_add_u64 v[166:167], s[44:45], 0, v[168:169]
	s_mov_b32 m0, s46
	s_nop 0
	global_load_lds_dwordx4 v[166:167], off
	v_lshl_add_u64 v[166:167], s[44:45], 0, v[128:129]
	s_add_i32 m0, s46, 0x2000
	s_nop 0
	global_load_lds_dwordx4 v[166:167], off
	v_lshl_add_u64 v[166:167], v[224:225], 0, s[30:31]
	s_mov_b32 m0, s49
	s_nop 0
	global_load_lds_dwordx4 v[166:167], off
	v_lshl_add_u64 v[166:167], v[234:235], 0, s[30:31]
	s_mov_b32 m0, s50
	s_nop 0
	global_load_lds_dwordx4 v[166:167], off
	s_waitcnt vmcnt(8)
	s_waitcnt lgkmcnt(0)
	s_barrier
	s_setprio 1
	s_waitcnt lgkmcnt(0)
	v_mfma_f32_16x16x32_bf16 v[60:63], v[138:141], v[192:195], v[60:63]
	v_mfma_f32_16x16x32_bf16 v[56:59], v[150:153], v[192:195], v[56:59]
	v_mfma_f32_16x16x32_bf16 v[52:55], v[138:141], v[200:203], v[52:55]
	v_mfma_f32_16x16x32_bf16 v[44:47], v[150:153], v[200:203], v[44:47]
	v_mfma_f32_16x16x32_bf16 v[36:39], v[138:141], v[208:211], v[36:39]
	v_mfma_f32_16x16x32_bf16 v[28:31], v[150:153], v[208:211], v[28:31]
	v_mfma_f32_16x16x32_bf16 v[20:23], v[138:141], v[216:219], v[20:23]
	v_mfma_f32_16x16x32_bf16 v[12:15], v[150:153], v[216:219], v[12:15]
	v_mfma_f32_16x16x32_bf16 v[60:63], v[146:149], v[196:199], v[60:63]
	v_mfma_f32_16x16x32_bf16 v[56:59], v[154:157], v[196:199], v[56:59]
	v_mfma_f32_16x16x32_bf16 v[52:55], v[146:149], v[204:207], v[52:55]
	v_mfma_f32_16x16x32_bf16 v[44:47], v[154:157], v[204:207], v[44:47]
	v_mfma_f32_16x16x32_bf16 v[36:39], v[146:149], v[212:215], v[36:39]
	v_mfma_f32_16x16x32_bf16 v[28:31], v[154:157], v[212:215], v[28:31]
	v_mfma_f32_16x16x32_bf16 v[20:23], v[146:149], v[220:223], v[20:23]
	s_add_i32 s58, s58, 2
	v_mfma_f32_16x16x32_bf16 v[12:15], v[154:157], v[220:223], v[12:15]
	s_add_u32 s56, s56, 0x100
	s_setprio 0
	s_setprio 1
	v_mfma_f32_16x16x32_bf16 v[48:51], v[158:161], v[192:195], v[48:51]
	s_addc_u32 s57, s57, 0
	v_mfma_f32_16x16x32_bf16 v[40:43], v[170:173], v[192:195], v[40:43]
	s_add_u32 s42, s42, 0x100
	v_mfma_f32_16x16x32_bf16 v[32:35], v[158:161], v[200:203], v[32:35]
	s_addc_u32 s43, s43, 0
	v_mfma_f32_16x16x32_bf16 v[24:27], v[170:173], v[200:203], v[24:27]
	s_add_u32 s44, s42, 0xfffc0080
	v_mfma_f32_16x16x32_bf16 v[16:19], v[158:161], v[208:211], v[16:19]
	s_addc_u32 s45, s43, -1
	v_mfma_f32_16x16x32_bf16 v[8:11], v[170:173], v[208:211], v[8:11]
	s_add_i32 s59, 0, 0x10000
	v_mfma_f32_16x16x32_bf16 v[4:7], v[158:161], v[216:219], v[4:7]
	s_cmp_eq_u32 s58, 12
	v_mfma_f32_16x16x32_bf16 v[0:3], v[170:173], v[216:219], v[0:3]
	s_cselect_b32 s47, s27, s45
	v_mfma_f32_16x16x32_bf16 v[48:51], v[162:165], v[196:199], v[48:51]
	s_cselect_b32 s46, s54, s44
	v_mfma_f32_16x16x32_bf16 v[40:43], v[188:191], v[196:199], v[40:43]
	s_cselect_b32 s45, s25, s57
	v_mfma_f32_16x16x32_bf16 v[32:35], v[162:165], v[204:207], v[32:35]
	s_cselect_b32 s44, s55, s56
	v_mfma_f32_16x16x32_bf16 v[24:27], v[188:191], v[204:207], v[24:27]
	s_add_i32 s62, 0, 0x14000
	v_mfma_f32_16x16x32_bf16 v[16:19], v[162:165], v[212:215], v[16:19]
	v_add_u32_e32 v242, s59, v143
	v_mfma_f32_16x16x32_bf16 v[8:11], v[188:191], v[212:215], v[8:11]
	v_add_u32_e32 v166, s62, v143
	v_mfma_f32_16x16x32_bf16 v[4:7], v[162:165], v[220:223], v[4:7]
	s_cmp_gt_u32 s58, 13
	v_mfma_f32_16x16x32_bf16 v[0:3], v[188:191], v[220:223], v[0:3]
	s_setprio 0
	s_barrier
	s_cbranch_scc0 .LBB0_196
	s_and_b64 vcc, exec, s[4:5]
	s_cbranch_vccz .LBB0_199
	s_barrier

; #define PG8_STAGE(bufoff, gbase, voff) do { _Pragma("unroll") for (int _i = 0; _i < 2; ++_i) \
;         __builtin_amdgcn_global_load_lds((const unsigned*)((const char*)(gbase) + (voff)[_i]), (PG8_LAS unsigned*)(lds + (bufoff) + ldsw + _i * 8192), 16, 0, 0); } while (0)
; #define PG8_LDA(dst, b, h) do { _Pragma("unroll") for (int m = 0; m < 4; ++m) _Pragma("unroll") for (int k = 0; k < 2; ++k) dst[m][k] = *(const PG8_LAS bf16x8*)(lds + PG8_SA(b, h) + aoff + m * 2048 + k * 1024); } while (0)
; #define PG8_LDB(dst, b, h) do { _Pragma("unroll") for (int n = 0; n < 2; ++n) _Pragma("unroll") for (int k = 0; k < 2; ++k) dst[n][k] = *(const PG8_LAS bf16x8*)(lds + PG8_SB(b, h) + boff + n * 2048 + k * 1024); } while (0)
; #define PG8_WAIT_V(n) asm volatile("s_waitcnt vmcnt(" #n ")" ::: "memory")
; #define PG8_WAIT_L(n) asm volatile("s_waitcnt lgkmcnt(" #n ")" ::: "memory")
; #define PG8_BAR __builtin_amdgcn_s_barrier()
; #define PG8_SCHED __builtin_amdgcn_sched_barrier(0)
; template <class Epi, class Sched, bool ALIGN_EPI = false, bool SP2 = false>
; __device__ __forceinline__ void gemm_phase(PG8_LAS unsigned char* lds, const Gemm g, const Sched& S, const Epi& E) {
;     ...
;         const bool has_next = S.next(ui + 1, nxt);
;         const char* nA = has_next ? (const char*)g.A + (size_t)nxt.pm * tstepA : cA; const char* nB = has_next ? (const char*)g.Bt + (size_t)nxt.pn * tstep : cB;
;         for (int t = 0; t < nt; t += 2) {
;             const bool last = (t == nt - 2);
;             const char* a1 = cA + (size_t)(t + 1) * kstepA;
;             const char* a2 = last ? nA : cA + (size_t)(t + 2) * kstepA; const char* b2 = last ? nB : cB + (size_t)(t + 2) * kstep;
;             const char* a3 = a2 + kstepA; const char* b3 = b2 + kstep;
;             if (last && has_next) S.a_ready(nxt);
;             if constexpr (SP2) {
;             PG8_LDB(B0, 0, 0); PG8_LDB(B1, 0, 1); PG8_SCHED; PG8_LDA(At, 0, 0); PG8_STAGE(PG8_SA(1, 1), a1 + hstepA, voffA);
;             PG8_WAIT_V(8); PG8_WAIT_L(0); PG8_BAR; PG8_MMA(0, 0, At, B0); PG8_MMA(0, 1, At, B1); PG8_BAR; PG8_SCHED;
;             PG8_LDA(At, 0, 1); PG8_STAGE(PG8_SB(0, 0), b2, voffB); PG8_STAGE(PG8_SB(0, 1), b2 + hstep, voffB); PG8_STAGE(PG8_SA(0, 0), a2, voffA);
;             PG8_WAIT_V(8); PG8_WAIT_L(0); PG8_BAR; PG8_MMA(1, 0, At, B0); PG8_MMA(1, 1, At, B1); PG8_BAR; PG8_SCHED;
.LBB0_433:
	s_ashr_i32 s41, s40, 31
	s_lshl_b64 s[42:43], s[40:41], 19
	s_add_u32 s42, s20, s42
	s_addc_u32 s43, s21, s43
	s_and_b64 s[44:45], s[36:37], exec
	s_cselect_b32 s41, s43, s39
	s_cselect_b32 s54, s42, s38
	s_ashr_i32 s27, s26, 31
	s_lshl_b64 s[44:45], s[26:27], 19
	s_add_u32 s44, s3, s44
	s_addc_u32 s45, s6, s45
	s_and_b64 s[46:47], s[36:37], exec
	s_cselect_b32 s27, s45, s5
	s_cselect_b32 s55, s44, s4
	s_add_u32 s56, s4, 0x100
	s_addc_u32 s57, s5, 0
	s_add_u32 s4, s38, 0x40080
	s_addc_u32 s5, s39, 0
	s_mov_b32 s58, -2
	s_add_u32 s38, s4, 0xfffc0080
	s_addc_u32 s39, s5, -1
	s_add_i32 s59, 0, 0x10000
	s_cmp_eq_u32 s58, 12
	s_cselect_b32 s47, s41, s39
	s_cselect_b32 s46, s54, s38
	s_cselect_b32 s39, s27, s57
	s_cselect_b32 s38, s55, s56
	s_add_i32 s62, 0, 0x14000
	v_add_u32_e32 v154, s59, v143
	v_add_u32_e32 v166, s62, v143
	ds_read_b128 v[138:141], v154
	ds_read_b128 v[146:149], v154 offset:1024
	ds_read_b128 v[150:153], v154 offset:2048
	ds_read_b128 v[154:157], v154 offset:3072
	ds_read_b128 v[158:161], v166
	ds_read_b128 v[162:165], v166 offset:1024
	ds_read_b128 v[188:191], v166 offset:2048
	ds_read_b128 v[192:195], v166 offset:3072
	v_lshl_add_u64 v[166:167], s[4:5], 0, v[136:137]
	s_add_i32 m0, s2, 0xc000
	ds_read_b128 v[196:199], v145
	ds_read_b128 v[200:203], v145 offset:1024
	ds_read_b128 v[204:207], v145 offset:2048
	ds_read_b128 v[208:211], v145 offset:3072
	ds_read_b128 v[212:215], v145 offset:4096
	ds_read_b128 v[216:219], v145 offset:5120
	ds_read_b128 v[220:223], v145 offset:6144
	ds_read_b128 v[234:237], v145 offset:7168
	global_load_lds_dwordx4 v[166:167], off
	v_lshl_add_u64 v[166:167], s[4:5], 0, v[134:135]
	s_add_i32 m0, s2, 0xe000
	s_nop 0
	global_load_lds_dwordx4 v[166:167], off
	s_waitcnt vmcnt(8)
	s_waitcnt lgkmcnt(0)
	s_barrier
	s_setprio 1
	s_waitcnt lgkmcnt(0)
	v_mfma_f32_16x16x32_bf16 v[124:127], v[138:141], v[196:199], 0
	v_mfma_f32_16x16x32_bf16 v[120:123], v[150:153], v[196:199], 0
	v_mfma_f32_16x16x32_bf16 v[108:111], v[138:141], v[204:207], 0
	v_mfma_f32_16x16x32_bf16 v[104:107], v[150:153], v[204:207], 0
	v_mfma_f32_16x16x32_bf16 v[92:95], v[138:141], v[212:215], 0
	v_mfma_f32_16x16x32_bf16 v[88:91], v[150:153], v[212:215], 0
	v_mfma_f32_16x16x32_bf16 v[76:79], v[138:141], v[220:223], 0
	v_mfma_f32_16x16x32_bf16 v[72:75], v[150:153], v[220:223], 0
	v_mfma_f32_16x16x32_bf16 v[124:127], v[146:149], v[200:203], v[124:127]
	v_mfma_f32_16x16x32_bf16 v[120:123], v[154:157], v[200:203], v[120:123]
	v_mfma_f32_16x16x32_bf16 v[108:111], v[146:149], v[208:211], v[108:111]
	v_mfma_f32_16x16x32_bf16 v[104:107], v[154:157], v[208:211], v[104:107]
	v_mfma_f32_16x16x32_bf16 v[92:95], v[146:149], v[216:219], v[92:95]
	v_mfma_f32_16x16x32_bf16 v[88:91], v[154:157], v[216:219], v[88:91]
	v_mfma_f32_16x16x32_bf16 v[76:79], v[146:149], v[234:237], v[76:79]
	v_mfma_f32_16x16x32_bf16 v[72:75], v[154:157], v[234:237], v[72:75]
	s_setprio 0
	s_setprio 1
	v_mfma_f32_16x16x32_bf16 v[116:119], v[158:161], v[196:199], 0
	v_mfma_f32_16x16x32_bf16 v[112:115], v[188:191], v[196:199], 0
	v_mfma_f32_16x16x32_bf16 v[100:103], v[158:161], v[204:207], 0
	v_mfma_f32_16x16x32_bf16 v[96:99], v[188:191], v[204:207], 0
	v_mfma_f32_16x16x32_bf16 v[84:87], v[158:161], v[212:215], 0
	v_mfma_f32_16x16x32_bf16 v[80:83], v[188:191], v[212:215], 0
	v_mfma_f32_16x16x32_bf16 v[68:71], v[158:161], v[220:223], 0
	v_mfma_f32_16x16x32_bf16 v[64:67], v[188:191], v[220:223], 0
	v_mfma_f32_16x16x32_bf16 v[116:119], v[162:165], v[200:203], v[116:119]
	v_mfma_f32_16x16x32_bf16 v[112:115], v[192:195], v[200:203], v[112:115]
	v_mfma_f32_16x16x32_bf16 v[100:103], v[162:165], v[208:211], v[100:103]
	v_mfma_f32_16x16x32_bf16 v[96:99], v[192:195], v[208:211], v[96:99]
	v_mfma_f32_16x16x32_bf16 v[84:87], v[162:165], v[216:219], v[84:87]
	s_add_i32 s59, s59, s7
	v_mfma_f32_16x16x32_bf16 v[80:83], v[192:195], v[216:219], v[80:83]
	v_lshl_add_u64 v[166:167], s[38:39], 0, v[168:169]
	v_mfma_f32_16x16x32_bf16 v[68:71], v[162:165], v[234:237], v[68:71]
	s_mov_b32 m0, s59
	v_mfma_f32_16x16x32_bf16 v[64:67], v[192:195], v[234:237], v[64:67]
	s_setprio 0
	s_barrier
	ds_read_b128 v[196:199], v145 offset:16384
	ds_read_b128 v[200:203], v145 offset:17408
	ds_read_b128 v[204:207], v145 offset:18432
	ds_read_b128 v[208:211], v145 offset:19456
	ds_read_b128 v[212:215], v145 offset:20480
	ds_read_b128 v[216:219], v145 offset:21504
	ds_read_b128 v[220:223], v145 offset:22528
	ds_read_b128 v[234:237], v145 offset:23552
	global_load_lds_dwordx4 v[166:167], off
	s_add_i32 m0, s59, 0x2000
	s_add_u32 s60, s38, 0x40000
	v_lshl_add_u64 v[170:171], s[38:39], 0, v[128:129]
	s_addc_u32 s61, s39, 0
	s_add_i32 s59, s62, s7
	global_load_lds_dwordx4 v[170:171], off
	v_lshl_add_u64 v[172:173], s[60:61], 0, v[168:169]
	s_mov_b32 m0, s59
	v_lshl_add_u64 v[224:225], s[46:47], 0, v[130:131]
	global_load_lds_dwordx4 v[172:173], off
	v_lshl_add_u64 v[172:173], s[60:61], 0, v[128:129]
	s_add_i32 m0, s59, 0x2000
	s_nop 0
	global_load_lds_dwordx4 v[172:173], off
	v_lshl_add_u64 v[172:173], s[46:47], 0, v[132:133]
	s_mov_b32 m0, s2
	s_nop 0
	global_load_lds_dwordx4 v[172:173], off
	s_mov_b32 m0, s34
	s_nop 0
	global_load_lds_dwordx4 v[224:225], off
	s_waitcnt vmcnt(8)
	s_waitcnt lgkmcnt(0)
	s_barrier
; #define PG8_STAGE(bufoff, gbase, voff) do { _Pragma("unroll") for (int _i = 0; _i < 2; ++_i) \
;         __builtin_amdgcn_global_load_lds((const unsigned*)((const char*)(gbase) + (voff)[_i]), (PG8_LAS unsigned*)(lds + (bufoff) + ldsw + _i * 8192), 16, 0, 0); } while (0)
; #define PG8_LDA(dst, b, h) do { _Pragma("unroll") for (int m = 0; m < 4; ++m) _Pragma("unroll") for (int k = 0; k < 2; ++k) dst[m][k] = *(const PG8_LAS bf16x8*)(lds + PG8_SA(b, h) + aoff + m * 2048 + k * 1024); } while (0)
; #define PG8_LDB(dst, b, h) do { _Pragma("unroll") for (int n = 0; n < 2; ++n) _Pragma("unroll") for (int k = 0; k < 2; ++k) dst[n][k] = *(const PG8_LAS bf16x8*)(lds + PG8_SB(b, h) + boff + n * 2048 + k * 1024); } while (0)
; #define PG8_MMA(ai, bj, At, Bt) do { __builtin_amdgcn_s_setprio(1); _Pragma("unroll") for (int m = 0; m < 4; ++m) _Pragma("unroll") for (int n = 0; n < 2; ++n) _Pragma("unroll") for (int k = 0; k < 2; ++k) \
;         acc[ai][bj][m][n] = __builtin_amdgcn_mfma_f32_16x16x32_bf16(Bt[n][k], At[m][k], acc[ai][bj][m][n], 0, 0, 0); __builtin_amdgcn_s_setprio(0); } while (0)
; #define PG8_WAIT_V(n) asm volatile("s_waitcnt vmcnt(" #n ")" ::: "memory")
; #define PG8_WAIT_L(n) asm volatile("s_waitcnt lgkmcnt(" #n ")" ::: "memory")
; #define PG8_BAR __builtin_amdgcn_s_barrier()
; #define PG8_SCHED __builtin_amdgcn_sched_barrier(0)
; template <class Epi, class Sched, bool ALIGN_EPI = false, bool SP2 = false>
; __device__ __forceinline__ void gemm_phase(PG8_LAS unsigned char* lds, const Gemm g, const Sched& S, const Epi& E) {
;     ...
;             PG8_WAIT_V(8); PG8_WAIT_L(0); PG8_BAR; PG8_MMA(1, 0, At, B0); PG8_MMA(1, 1, At, B1); PG8_BAR; PG8_SCHED;
;             PG8_LDB(B0, 1, 0); PG8_LDB(B1, 1, 1); PG8_SCHED; PG8_LDA(At, 1, 0); PG8_STAGE(PG8_SA(0, 1), a2 + hstepA, voffA);
;             PG8_WAIT_V(8); PG8_WAIT_L(0); PG8_BAR; PG8_MMA(0, 0, At, B0); PG8_MMA(0, 1, At, B1); PG8_BAR; PG8_SCHED;
	s_setprio 1
	s_waitcnt lgkmcnt(0)
	v_mfma_f32_16x16x32_bf16 v[60:63], v[138:141], v[196:199], 0
	v_mfma_f32_16x16x32_bf16 v[56:59], v[150:153], v[196:199], 0
	v_mfma_f32_16x16x32_bf16 v[44:47], v[138:141], v[204:207], 0
	v_mfma_f32_16x16x32_bf16 v[40:43], v[150:153], v[204:207], 0
	v_mfma_f32_16x16x32_bf16 v[28:31], v[138:141], v[212:215], 0
	v_mfma_f32_16x16x32_bf16 v[24:27], v[150:153], v[212:215], 0
	v_mfma_f32_16x16x32_bf16 v[12:15], v[138:141], v[220:223], 0
	v_mfma_f32_16x16x32_bf16 v[8:11], v[150:153], v[220:223], 0
	v_mfma_f32_16x16x32_bf16 v[60:63], v[146:149], v[200:203], v[60:63]
	v_mfma_f32_16x16x32_bf16 v[56:59], v[154:157], v[200:203], v[56:59]
	v_mfma_f32_16x16x32_bf16 v[44:47], v[146:149], v[208:211], v[44:47]
	v_mfma_f32_16x16x32_bf16 v[40:43], v[154:157], v[208:211], v[40:43]
	v_mfma_f32_16x16x32_bf16 v[28:31], v[146:149], v[216:219], v[28:31]
	v_mfma_f32_16x16x32_bf16 v[24:27], v[154:157], v[216:219], v[24:27]
	v_mfma_f32_16x16x32_bf16 v[12:15], v[146:149], v[234:237], v[12:15]
	v_mfma_f32_16x16x32_bf16 v[8:11], v[154:157], v[234:237], v[8:11]
	s_setprio 0
	s_setprio 1
	v_mfma_f32_16x16x32_bf16 v[52:55], v[158:161], v[196:199], 0
	v_mfma_f32_16x16x32_bf16 v[48:51], v[188:191], v[196:199], 0
	v_mfma_f32_16x16x32_bf16 v[36:39], v[158:161], v[204:207], 0
	v_mfma_f32_16x16x32_bf16 v[32:35], v[188:191], v[204:207], 0
	v_mfma_f32_16x16x32_bf16 v[20:23], v[158:161], v[212:215], 0
	v_mfma_f32_16x16x32_bf16 v[16:19], v[188:191], v[212:215], 0
	v_mfma_f32_16x16x32_bf16 v[4:7], v[158:161], v[220:223], 0
	v_mfma_f32_16x16x32_bf16 v[0:3], v[188:191], v[220:223], 0
	v_mfma_f32_16x16x32_bf16 v[52:55], v[162:165], v[200:203], v[52:55]
	v_mfma_f32_16x16x32_bf16 v[48:51], v[192:195], v[200:203], v[48:51]
	v_mfma_f32_16x16x32_bf16 v[36:39], v[162:165], v[208:211], v[36:39]
	v_mfma_f32_16x16x32_bf16 v[32:35], v[192:195], v[208:211], v[32:35]
	s_add_i32 s59, 0, 0x18000
	v_mfma_f32_16x16x32_bf16 v[20:23], v[162:165], v[216:219], v[20:23]
	s_add_i32 s60, 0, 0x1c000
	v_mfma_f32_16x16x32_bf16 v[16:19], v[192:195], v[216:219], v[16:19]
	v_add_u32_e32 v240, s59, v143
	v_mfma_f32_16x16x32_bf16 v[4:7], v[162:165], v[234:237], v[4:7]
	v_add_u32_e32 v178, s60, v143
	v_mfma_f32_16x16x32_bf16 v[0:3], v[192:195], v[234:237], v[0:3]
	s_setprio 0
	s_barrier
	ds_read_b128 v[138:141], v240
	ds_read_b128 v[146:149], v240 offset:1024
	ds_read_b128 v[150:153], v240 offset:2048
	ds_read_b128 v[154:157], v240 offset:3072
	ds_read_b128 v[158:161], v178
	ds_read_b128 v[162:165], v178 offset:1024
	ds_read_b128 v[188:191], v178 offset:2048
	ds_read_b128 v[192:195], v178 offset:3072
	s_add_u32 s46, s46, 0x40000
	s_addc_u32 s47, s47, 0
	s_mov_b32 m0, s35
	v_lshl_add_u64 v[238:239], s[46:47], 0, v[132:133]
	ds_read_b128 v[196:199], v145 offset:32768
	ds_read_b128 v[200:203], v145 offset:33792
	ds_read_b128 v[204:207], v145 offset:34816
	ds_read_b128 v[208:211], v145 offset:35840
	ds_read_b128 v[212:215], v145 offset:36864
	ds_read_b128 v[216:219], v145 offset:37888
	ds_read_b128 v[220:223], v145 offset:38912
	ds_read_b128 v[234:237], v145 offset:39936
	global_load_lds_dwordx4 v[238:239], off
	v_lshl_add_u64 v[238:239], s[46:47], 0, v[130:131]
	s_mov_b32 m0, s48
	s_nop 0
	global_load_lds_dwordx4 v[238:239], off
	s_waitcnt vmcnt(8)
	s_waitcnt lgkmcnt(0)
	s_barrier
	s_setprio 1
	s_waitcnt lgkmcnt(0)
	v_mfma_f32_16x16x32_bf16 v[124:127], v[138:141], v[196:199], v[124:127]
	v_mfma_f32_16x16x32_bf16 v[120:123], v[150:153], v[196:199], v[120:123]
	v_mfma_f32_16x16x32_bf16 v[108:111], v[138:141], v[204:207], v[108:111]
	v_mfma_f32_16x16x32_bf16 v[104:107], v[150:153], v[204:207], v[104:107]
	v_mfma_f32_16x16x32_bf16 v[92:95], v[138:141], v[212:215], v[92:95]
	v_mfma_f32_16x16x32_bf16 v[88:91], v[150:153], v[212:215], v[88:91]
	v_mfma_f32_16x16x32_bf16 v[76:79], v[138:141], v[220:223], v[76:79]
	v_mfma_f32_16x16x32_bf16 v[72:75], v[150:153], v[220:223], v[72:75]
	v_mfma_f32_16x16x32_bf16 v[124:127], v[146:149], v[200:203], v[124:127]
	v_mfma_f32_16x16x32_bf16 v[120:123], v[154:157], v[200:203], v[120:123]
	v_mfma_f32_16x16x32_bf16 v[108:111], v[146:149], v[208:211], v[108:111]
	v_mfma_f32_16x16x32_bf16 v[104:107], v[154:157], v[208:211], v[104:107]
	v_mfma_f32_16x16x32_bf16 v[92:95], v[146:149], v[216:219], v[92:95]
	v_mfma_f32_16x16x32_bf16 v[88:91], v[154:157], v[216:219], v[88:91]
	v_mfma_f32_16x16x32_bf16 v[76:79], v[146:149], v[234:237], v[76:79]
	v_mfma_f32_16x16x32_bf16 v[72:75], v[154:157], v[234:237], v[72:75]
	s_setprio 0
	s_setprio 1
	v_mfma_f32_16x16x32_bf16 v[116:119], v[158:161], v[196:199], v[116:119]
	v_mfma_f32_16x16x32_bf16 v[112:115], v[188:191], v[196:199], v[112:115]
	v_mfma_f32_16x16x32_bf16 v[100:103], v[158:161], v[204:207], v[100:103]
	v_mfma_f32_16x16x32_bf16 v[96:99], v[188:191], v[204:207], v[96:99]
	v_mfma_f32_16x16x32_bf16 v[84:87], v[158:161], v[212:215], v[84:87]
	v_mfma_f32_16x16x32_bf16 v[80:83], v[188:191], v[212:215], v[80:83]
	v_mfma_f32_16x16x32_bf16 v[68:71], v[158:161], v[220:223], v[68:71]
	v_mfma_f32_16x16x32_bf16 v[64:67], v[188:191], v[220:223], v[64:67]
	v_mfma_f32_16x16x32_bf16 v[116:119], v[162:165], v[200:203], v[116:119]
	v_mfma_f32_16x16x32_bf16 v[112:115], v[192:195], v[200:203], v[112:115]
	v_mfma_f32_16x16x32_bf16 v[100:103], v[162:165], v[208:211], v[100:103]
	v_mfma_f32_16x16x32_bf16 v[96:99], v[192:195], v[208:211], v[96:99]
	v_mfma_f32_16x16x32_bf16 v[84:87], v[162:165], v[216:219], v[84:87]
	s_add_i32 s46, s59, s7
	v_mfma_f32_16x16x32_bf16 v[80:83], v[192:195], v[216:219], v[80:83]
	v_lshl_add_u64 v[166:167], v[166:167], 0, s[30:31]
	v_mfma_f32_16x16x32_bf16 v[68:71], v[162:165], v[234:237], v[68:71]
	s_mov_b32 m0, s46
	v_mfma_f32_16x16x32_bf16 v[64:67], v[192:195], v[234:237], v[64:67]
	s_setprio 0
	s_barrier
; #define PG8_STAGE(bufoff, gbase, voff) do { _Pragma("unroll") for (int _i = 0; _i < 2; ++_i) \
;         __builtin_amdgcn_global_load_lds((const unsigned*)((const char*)(gbase) + (voff)[_i]), (PG8_LAS unsigned*)(lds + (bufoff) + ldsw + _i * 8192), 16, 0, 0); } while (0)
; #define PG8_LDA(dst, b, h) do { _Pragma("unroll") for (int m = 0; m < 4; ++m) _Pragma("unroll") for (int k = 0; k < 2; ++k) dst[m][k] = *(const PG8_LAS bf16x8*)(lds + PG8_SA(b, h) + aoff + m * 2048 + k * 1024); } while (0)
; #define PG8_LDB(dst, b, h) do { _Pragma("unroll") for (int n = 0; n < 2; ++n) _Pragma("unroll") for (int k = 0; k < 2; ++k) dst[n][k] = *(const PG8_LAS bf16x8*)(lds + PG8_SB(b, h) + boff + n * 2048 + k * 1024); } while (0)
; #define PG8_MMA(ai, bj, At, Bt) do { __builtin_amdgcn_s_setprio(1); _Pragma("unroll") for (int m = 0; m < 4; ++m) _Pragma("unroll") for (int n = 0; n < 2; ++n) _Pragma("unroll") for (int k = 0; k < 2; ++k) \
;         acc[ai][bj][m][n] = __builtin_amdgcn_mfma_f32_16x16x32_bf16(Bt[n][k], At[m][k], acc[ai][bj][m][n], 0, 0, 0); __builtin_amdgcn_s_setprio(0); } while (0)
; #define PG8_WAIT_V(n) asm volatile("s_waitcnt vmcnt(" #n ")" ::: "memory")
; template <class Epi, class Sched, bool ALIGN_EPI = false, bool SP2 = false>
; __device__ __forceinline__ void gemm_phase(PG8_LAS unsigned char* lds, const Gemm g, const Sched& S, const Epi& E) {
;     ...
;             PG8_LDB(B0, 0, 0); PG8_LDB(B1, 0, 1); PG8_SCHED; PG8_LDA(At, 0, 0); PG8_STAGE(PG8_SA(1, 1), a1 + hstepA, voffA);
;             PG8_WAIT_V(8); PG8_WAIT_L(0); PG8_BAR; PG8_MMA(0, 0, At, B0); PG8_MMA(0, 1, At, B1); PG8_BAR; PG8_SCHED;
;             PG8_LDA(At, 0, 1); PG8_STAGE(PG8_SB(0, 0), b2, voffB); PG8_STAGE(PG8_SB(0, 1), b2 + hstep, voffB); PG8_STAGE(PG8_SA(0, 0), a2, voffA);
;             PG8_WAIT_V(8); PG8_WAIT_L(0); PG8_BAR; PG8_MMA(1, 0, At, B0); PG8_MMA(1, 1, At, B1); PG8_BAR; PG8_SCHED;
;             PG8_LDB(B0, 1, 0); PG8_LDB(B1, 1, 1); PG8_SCHED; PG8_LDA(At, 1, 0); PG8_STAGE(PG8_SA(0, 1), a2 + hstepA, voffA);
;             PG8_WAIT_V(8); PG8_WAIT_L(0); PG8_BAR; PG8_MMA(0, 0, At, B0); PG8_MMA(0, 1, At, B1); PG8_BAR; PG8_SCHED;
;             PG8_LDA(At, 1, 1); PG8_STAGE(PG8_SB(1, 0), b3, voffB); PG8_STAGE(PG8_SB(1, 1), b3 + hstep, voffB); PG8_STAGE(PG8_SA(1, 0), a3, voffA);
;             PG8_WAIT_V(8); PG8_WAIT_L(0); PG8_BAR; PG8_MMA(1, 0, At, B0); PG8_MMA(1, 1, At, B1); PG8_BAR; PG8_SCHED;
	ds_read_b128 v[196:199], v145 offset:49152
	ds_read_b128 v[200:203], v145 offset:50176
	ds_read_b128 v[204:207], v145 offset:51200
	ds_read_b128 v[208:211], v145 offset:52224
	ds_read_b128 v[212:215], v145 offset:53248
	ds_read_b128 v[216:219], v145 offset:54272
	ds_read_b128 v[220:223], v145 offset:55296
	ds_read_b128 v[234:237], v145 offset:56320
	global_load_lds_dwordx4 v[166:167], off
	s_add_i32 m0, s46, 0x2000
	s_add_u32 s38, s38, 0x40080
	v_lshl_add_u64 v[166:167], v[170:171], 0, s[30:31]
	s_addc_u32 s39, s39, 0
	s_add_i32 s46, s60, s7
	global_load_lds_dwordx4 v[166:167], off
	v_lshl_add_u64 v[166:167], s[38:39], 0, v[168:169]
	s_mov_b32 m0, s46
	s_nop 0
	global_load_lds_dwordx4 v[166:167], off
	v_lshl_add_u64 v[166:167], s[38:39], 0, v[128:129]
	s_add_i32 m0, s46, 0x2000
	s_nop 0
	global_load_lds_dwordx4 v[166:167], off
	v_lshl_add_u64 v[166:167], v[172:173], 0, s[30:31]
	s_mov_b32 m0, s49
	s_nop 0
	global_load_lds_dwordx4 v[166:167], off
	v_lshl_add_u64 v[166:167], v[224:225], 0, s[30:31]
	s_mov_b32 m0, s50
	s_nop 0
	global_load_lds_dwordx4 v[166:167], off
	s_waitcnt vmcnt(8)
	s_waitcnt lgkmcnt(0)
	s_barrier
	s_setprio 1
	s_waitcnt lgkmcnt(0)
	v_mfma_f32_16x16x32_bf16 v[60:63], v[138:141], v[196:199], v[60:63]
	v_mfma_f32_16x16x32_bf16 v[56:59], v[150:153], v[196:199], v[56:59]
	v_mfma_f32_16x16x32_bf16 v[44:47], v[138:141], v[204:207], v[44:47]
	v_mfma_f32_16x16x32_bf16 v[40:43], v[150:153], v[204:207], v[40:43]
	v_mfma_f32_16x16x32_bf16 v[28:31], v[138:141], v[212:215], v[28:31]
	v_mfma_f32_16x16x32_bf16 v[24:27], v[150:153], v[212:215], v[24:27]
	v_mfma_f32_16x16x32_bf16 v[12:15], v[138:141], v[220:223], v[12:15]
	v_mfma_f32_16x16x32_bf16 v[8:11], v[150:153], v[220:223], v[8:11]
	v_mfma_f32_16x16x32_bf16 v[60:63], v[146:149], v[200:203], v[60:63]
	v_mfma_f32_16x16x32_bf16 v[56:59], v[154:157], v[200:203], v[56:59]
	v_mfma_f32_16x16x32_bf16 v[44:47], v[146:149], v[208:211], v[44:47]
	v_mfma_f32_16x16x32_bf16 v[40:43], v[154:157], v[208:211], v[40:43]
	v_mfma_f32_16x16x32_bf16 v[28:31], v[146:149], v[216:219], v[28:31]
	v_mfma_f32_16x16x32_bf16 v[24:27], v[154:157], v[216:219], v[24:27]
	v_mfma_f32_16x16x32_bf16 v[12:15], v[146:149], v[234:237], v[12:15]
	v_mfma_f32_16x16x32_bf16 v[8:11], v[154:157], v[234:237], v[8:11]
	s_add_i32 s58, s58, 2
	s_setprio 0
	s_setprio 1
	v_mfma_f32_16x16x32_bf16 v[52:55], v[158:161], v[196:199], v[52:55]
	s_add_u32 s56, s56, 0x100
	v_mfma_f32_16x16x32_bf16 v[48:51], v[188:191], v[196:199], v[48:51]
	s_addc_u32 s57, s57, 0
	v_mfma_f32_16x16x32_bf16 v[36:39], v[158:161], v[204:207], v[36:39]
	s_add_u32 s4, s4, 0x100
	v_mfma_f32_16x16x32_bf16 v[32:35], v[188:191], v[204:207], v[32:35]
	s_addc_u32 s5, s5, 0
	v_mfma_f32_16x16x32_bf16 v[20:23], v[158:161], v[212:215], v[20:23]
	s_add_u32 s38, s4, 0xfffc0080
	v_mfma_f32_16x16x32_bf16 v[16:19], v[188:191], v[212:215], v[16:19]
	s_addc_u32 s39, s5, -1
	v_mfma_f32_16x16x32_bf16 v[4:7], v[158:161], v[220:223], v[4:7]
	s_add_i32 s59, 0, 0x10000
	v_mfma_f32_16x16x32_bf16 v[0:3], v[188:191], v[220:223], v[0:3]
	s_cmp_eq_u32 s58, 12
	v_mfma_f32_16x16x32_bf16 v[52:55], v[162:165], v[200:203], v[52:55]
	s_cselect_b32 s47, s41, s39
	v_mfma_f32_16x16x32_bf16 v[48:51], v[192:195], v[200:203], v[48:51]
	s_cselect_b32 s46, s54, s38
	v_mfma_f32_16x16x32_bf16 v[36:39], v[162:165], v[208:211], v[36:39]
	s_cselect_b32 s39, s27, s57
	v_mfma_f32_16x16x32_bf16 v[32:35], v[192:195], v[208:211], v[32:35]
	s_cselect_b32 s38, s55, s56
	v_mfma_f32_16x16x32_bf16 v[20:23], v[162:165], v[216:219], v[20:23]
	s_add_i32 s62, 0, 0x14000
	v_mfma_f32_16x16x32_bf16 v[16:19], v[192:195], v[216:219], v[16:19]
	v_add_u32_e32 v241, s59, v143
	v_mfma_f32_16x16x32_bf16 v[4:7], v[162:165], v[234:237], v[4:7]
	v_add_u32_e32 v166, s62, v143
	v_mfma_f32_16x16x32_bf16 v[0:3], v[192:195], v[234:237], v[0:3]
	s_setprio 0
	s_barrier
.LBB0_434:
	ds_read_b128 v[138:141], v241
	ds_read_b128 v[146:149], v241 offset:1024
	ds_read_b128 v[150:153], v241 offset:2048
	ds_read_b128 v[154:157], v241 offset:3072
	ds_read_b128 v[158:161], v166
	ds_read_b128 v[162:165], v166 offset:1024
	ds_read_b128 v[188:191], v166 offset:2048
	ds_read_b128 v[192:195], v166 offset:3072
	v_lshl_add_u64 v[166:167], s[4:5], 0, v[136:137]
	s_add_i32 m0, s2, 0xc000
	ds_read_b128 v[196:199], v145
	ds_read_b128 v[200:203], v145 offset:1024
	ds_read_b128 v[204:207], v145 offset:2048
	ds_read_b128 v[208:211], v145 offset:3072
	ds_read_b128 v[212:215], v145 offset:4096
	ds_read_b128 v[216:219], v145 offset:5120
	ds_read_b128 v[220:223], v145 offset:6144
	ds_read_b128 v[234:237], v145 offset:7168
	global_load_lds_dwordx4 v[166:167], off
	v_lshl_add_u64 v[166:167], s[4:5], 0, v[134:135]
	s_add_i32 m0, s2, 0xe000
	s_nop 0
	global_load_lds_dwordx4 v[166:167], off
	s_waitcnt vmcnt(8)
	s_waitcnt lgkmcnt(0)
	s_barrier
; #define PG8_STAGE(bufoff, gbase, voff) do { _Pragma("unroll") for (int _i = 0; _i < 2; ++_i) \
;         __builtin_amdgcn_global_load_lds((const unsigned*)((const char*)(gbase) + (voff)[_i]), (PG8_LAS unsigned*)(lds + (bufoff) + ldsw + _i * 8192), 16, 0, 0); } while (0)
; #define PG8_LDA(dst, b, h) do { _Pragma("unroll") for (int m = 0; m < 4; ++m) _Pragma("unroll") for (int k = 0; k < 2; ++k) dst[m][k] = *(const PG8_LAS bf16x8*)(lds + PG8_SA(b, h) + aoff + m * 2048 + k * 1024); } while (0)
; #define PG8_LDB(dst, b, h) do { _Pragma("unroll") for (int n = 0; n < 2; ++n) _Pragma("unroll") for (int k = 0; k < 2; ++k) dst[n][k] = *(const PG8_LAS bf16x8*)(lds + PG8_SB(b, h) + boff + n * 2048 + k * 1024); } while (0)
; #define PG8_MMA(ai, bj, At, Bt) do { __builtin_amdgcn_s_setprio(1); _Pragma("unroll") for (int m = 0; m < 4; ++m) _Pragma("unroll") for (int n = 0; n < 2; ++n) _Pragma("unroll") for (int k = 0; k < 2; ++k) \
;         acc[ai][bj][m][n] = __builtin_amdgcn_mfma_f32_16x16x32_bf16(Bt[n][k], At[m][k], acc[ai][bj][m][n], 0, 0, 0); __builtin_amdgcn_s_setprio(0); } while (0)
; #define PG8_WAIT_V(n) asm volatile("s_waitcnt vmcnt(" #n ")" ::: "memory")
; #define PG8_WAIT_L(n) asm volatile("s_waitcnt lgkmcnt(" #n ")" ::: "memory")
; #define PG8_BAR __builtin_amdgcn_s_barrier()
; #define PG8_SCHED __builtin_amdgcn_sched_barrier(0)
; template <class Epi, class Sched, bool ALIGN_EPI = false, bool SP2 = false>
; __device__ __forceinline__ void gemm_phase(PG8_LAS unsigned char* lds, const Gemm g, const Sched& S, const Epi& E) {
;     ...
;             PG8_WAIT_V(8); PG8_WAIT_L(0); PG8_BAR; PG8_MMA(0, 0, At, B0); PG8_MMA(0, 1, At, B1); PG8_BAR; PG8_SCHED;
;             PG8_LDA(At, 0, 1); PG8_STAGE(PG8_SB(0, 0), b2, voffB); PG8_STAGE(PG8_SB(0, 1), b2 + hstep, voffB); PG8_STAGE(PG8_SA(0, 0), a2, voffA);
;             PG8_WAIT_V(8); PG8_WAIT_L(0); PG8_BAR; PG8_MMA(1, 0, At, B0); PG8_MMA(1, 1, At, B1); PG8_BAR; PG8_SCHED;
;             PG8_LDB(B0, 1, 0); PG8_LDB(B1, 1, 1); PG8_SCHED; PG8_LDA(At, 1, 0); PG8_STAGE(PG8_SA(0, 1), a2 + hstepA, voffA);
	s_setprio 1
	s_waitcnt lgkmcnt(0)
	v_mfma_f32_16x16x32_bf16 v[124:127], v[138:141], v[196:199], v[124:127]
	v_mfma_f32_16x16x32_bf16 v[120:123], v[150:153], v[196:199], v[120:123]
	v_mfma_f32_16x16x32_bf16 v[108:111], v[138:141], v[204:207], v[108:111]
	v_mfma_f32_16x16x32_bf16 v[104:107], v[150:153], v[204:207], v[104:107]
	v_mfma_f32_16x16x32_bf16 v[92:95], v[138:141], v[212:215], v[92:95]
	v_mfma_f32_16x16x32_bf16 v[88:91], v[150:153], v[212:215], v[88:91]
	v_mfma_f32_16x16x32_bf16 v[76:79], v[138:141], v[220:223], v[76:79]
	v_mfma_f32_16x16x32_bf16 v[72:75], v[150:153], v[220:223], v[72:75]
	v_mfma_f32_16x16x32_bf16 v[124:127], v[146:149], v[200:203], v[124:127]
	v_mfma_f32_16x16x32_bf16 v[120:123], v[154:157], v[200:203], v[120:123]
	v_mfma_f32_16x16x32_bf16 v[108:111], v[146:149], v[208:211], v[108:111]
	v_mfma_f32_16x16x32_bf16 v[104:107], v[154:157], v[208:211], v[104:107]
	v_mfma_f32_16x16x32_bf16 v[92:95], v[146:149], v[216:219], v[92:95]
	v_mfma_f32_16x16x32_bf16 v[88:91], v[154:157], v[216:219], v[88:91]
	v_mfma_f32_16x16x32_bf16 v[76:79], v[146:149], v[234:237], v[76:79]
	v_mfma_f32_16x16x32_bf16 v[72:75], v[154:157], v[234:237], v[72:75]
	s_setprio 0
	s_setprio 1
	v_mfma_f32_16x16x32_bf16 v[116:119], v[158:161], v[196:199], v[116:119]
	v_mfma_f32_16x16x32_bf16 v[112:115], v[188:191], v[196:199], v[112:115]
	v_mfma_f32_16x16x32_bf16 v[100:103], v[158:161], v[204:207], v[100:103]
	v_mfma_f32_16x16x32_bf16 v[96:99], v[188:191], v[204:207], v[96:99]
	v_mfma_f32_16x16x32_bf16 v[84:87], v[158:161], v[212:215], v[84:87]
	v_mfma_f32_16x16x32_bf16 v[80:83], v[188:191], v[212:215], v[80:83]
	v_mfma_f32_16x16x32_bf16 v[68:71], v[158:161], v[220:223], v[68:71]
	v_mfma_f32_16x16x32_bf16 v[64:67], v[188:191], v[220:223], v[64:67]
	v_mfma_f32_16x16x32_bf16 v[116:119], v[162:165], v[200:203], v[116:119]
	v_mfma_f32_16x16x32_bf16 v[112:115], v[192:195], v[200:203], v[112:115]
	v_mfma_f32_16x16x32_bf16 v[100:103], v[162:165], v[208:211], v[100:103]
	v_mfma_f32_16x16x32_bf16 v[96:99], v[192:195], v[208:211], v[96:99]
	v_mfma_f32_16x16x32_bf16 v[84:87], v[162:165], v[216:219], v[84:87]
	s_add_i32 s59, s59, s7
	v_mfma_f32_16x16x32_bf16 v[80:83], v[192:195], v[216:219], v[80:83]
	v_lshl_add_u64 v[166:167], s[38:39], 0, v[168:169]
	v_mfma_f32_16x16x32_bf16 v[68:71], v[162:165], v[234:237], v[68:71]
	s_mov_b32 m0, s59
	v_mfma_f32_16x16x32_bf16 v[64:67], v[192:195], v[234:237], v[64:67]
	s_setprio 0
	s_barrier
	ds_read_b128 v[196:199], v145 offset:16384
	ds_read_b128 v[200:203], v145 offset:17408
	ds_read_b128 v[204:207], v145 offset:18432
	ds_read_b128 v[208:211], v145 offset:19456
	ds_read_b128 v[212:215], v145 offset:20480
	ds_read_b128 v[216:219], v145 offset:21504
	ds_read_b128 v[220:223], v145 offset:22528
	ds_read_b128 v[234:237], v145 offset:23552
	global_load_lds_dwordx4 v[166:167], off
	s_add_i32 m0, s59, 0x2000
	s_add_u32 s60, s38, 0x40000
	v_lshl_add_u64 v[170:171], s[38:39], 0, v[128:129]
	s_addc_u32 s61, s39, 0
	s_add_i32 s59, s62, s7
	global_load_lds_dwordx4 v[170:171], off
	v_lshl_add_u64 v[172:173], s[60:61], 0, v[168:169]
	s_mov_b32 m0, s59
	v_lshl_add_u64 v[224:225], s[46:47], 0, v[130:131]
	global_load_lds_dwordx4 v[172:173], off
	v_lshl_add_u64 v[172:173], s[60:61], 0, v[128:129]
	s_add_i32 m0, s59, 0x2000
	s_nop 0
	global_load_lds_dwordx4 v[172:173], off
	v_lshl_add_u64 v[172:173], s[46:47], 0, v[132:133]
	s_mov_b32 m0, s2
	s_nop 0
	global_load_lds_dwordx4 v[172:173], off
	s_mov_b32 m0, s34
	s_nop 0
	global_load_lds_dwordx4 v[224:225], off
	s_waitcnt vmcnt(8)
	s_waitcnt lgkmcnt(0)
	s_barrier
	s_setprio 1
	s_waitcnt lgkmcnt(0)
	v_mfma_f32_16x16x32_bf16 v[60:63], v[138:141], v[196:199], v[60:63]
	v_mfma_f32_16x16x32_bf16 v[56:59], v[150:153], v[196:199], v[56:59]
	v_mfma_f32_16x16x32_bf16 v[44:47], v[138:141], v[204:207], v[44:47]
	v_mfma_f32_16x16x32_bf16 v[40:43], v[150:153], v[204:207], v[40:43]
	v_mfma_f32_16x16x32_bf16 v[28:31], v[138:141], v[212:215], v[28:31]
	v_mfma_f32_16x16x32_bf16 v[24:27], v[150:153], v[212:215], v[24:27]
	v_mfma_f32_16x16x32_bf16 v[12:15], v[138:141], v[220:223], v[12:15]
	v_mfma_f32_16x16x32_bf16 v[8:11], v[150:153], v[220:223], v[8:11]
	v_mfma_f32_16x16x32_bf16 v[60:63], v[146:149], v[200:203], v[60:63]
	v_mfma_f32_16x16x32_bf16 v[56:59], v[154:157], v[200:203], v[56:59]
	v_mfma_f32_16x16x32_bf16 v[44:47], v[146:149], v[208:211], v[44:47]
	v_mfma_f32_16x16x32_bf16 v[40:43], v[154:157], v[208:211], v[40:43]
	v_mfma_f32_16x16x32_bf16 v[28:31], v[146:149], v[216:219], v[28:31]
	v_mfma_f32_16x16x32_bf16 v[24:27], v[154:157], v[216:219], v[24:27]
	v_mfma_f32_16x16x32_bf16 v[12:15], v[146:149], v[234:237], v[12:15]
	v_mfma_f32_16x16x32_bf16 v[8:11], v[154:157], v[234:237], v[8:11]
	s_setprio 0
	s_setprio 1
	v_mfma_f32_16x16x32_bf16 v[52:55], v[158:161], v[196:199], v[52:55]
	v_mfma_f32_16x16x32_bf16 v[48:51], v[188:191], v[196:199], v[48:51]
	v_mfma_f32_16x16x32_bf16 v[36:39], v[158:161], v[204:207], v[36:39]
	v_mfma_f32_16x16x32_bf16 v[32:35], v[188:191], v[204:207], v[32:35]
	v_mfma_f32_16x16x32_bf16 v[20:23], v[158:161], v[212:215], v[20:23]
	v_mfma_f32_16x16x32_bf16 v[16:19], v[188:191], v[212:215], v[16:19]
	v_mfma_f32_16x16x32_bf16 v[4:7], v[158:161], v[220:223], v[4:7]
	v_mfma_f32_16x16x32_bf16 v[0:3], v[188:191], v[220:223], v[0:3]
	v_mfma_f32_16x16x32_bf16 v[52:55], v[162:165], v[200:203], v[52:55]
	v_mfma_f32_16x16x32_bf16 v[48:51], v[192:195], v[200:203], v[48:51]
	v_mfma_f32_16x16x32_bf16 v[36:39], v[162:165], v[208:211], v[36:39]
	v_mfma_f32_16x16x32_bf16 v[32:35], v[192:195], v[208:211], v[32:35]
	s_add_i32 s59, 0, 0x18000
	v_mfma_f32_16x16x32_bf16 v[20:23], v[162:165], v[216:219], v[20:23]
	s_add_i32 s60, 0, 0x1c000
	v_mfma_f32_16x16x32_bf16 v[16:19], v[192:195], v[216:219], v[16:19]
	v_add_u32_e32 v240, s59, v143
	v_mfma_f32_16x16x32_bf16 v[4:7], v[162:165], v[234:237], v[4:7]
	v_add_u32_e32 v178, s60, v143
	v_mfma_f32_16x16x32_bf16 v[0:3], v[192:195], v[234:237], v[0:3]
	s_setprio 0
	s_barrier
; #define PG8_STAGE(bufoff, gbase, voff) do { _Pragma("unroll") for (int _i = 0; _i < 2; ++_i) \
;         __builtin_amdgcn_global_load_lds((const unsigned*)((const char*)(gbase) + (voff)[_i]), (PG8_LAS unsigned*)(lds + (bufoff) + ldsw + _i * 8192), 16, 0, 0); } while (0)
; #define PG8_LDA(dst, b, h) do { _Pragma("unroll") for (int m = 0; m < 4; ++m) _Pragma("unroll") for (int k = 0; k < 2; ++k) dst[m][k] = *(const PG8_LAS bf16x8*)(lds + PG8_SA(b, h) + aoff + m * 2048 + k * 1024); } while (0)
; #define PG8_LDB(dst, b, h) do { _Pragma("unroll") for (int n = 0; n < 2; ++n) _Pragma("unroll") for (int k = 0; k < 2; ++k) dst[n][k] = *(const PG8_LAS bf16x8*)(lds + PG8_SB(b, h) + boff + n * 2048 + k * 1024); } while (0)
; #define PG8_MMA(ai, bj, At, Bt) do { __builtin_amdgcn_s_setprio(1); _Pragma("unroll") for (int m = 0; m < 4; ++m) _Pragma("unroll") for (int n = 0; n < 2; ++n) _Pragma("unroll") for (int k = 0; k < 2; ++k) \
;         acc[ai][bj][m][n] = __builtin_amdgcn_mfma_f32_16x16x32_bf16(Bt[n][k], At[m][k], acc[ai][bj][m][n], 0, 0, 0); __builtin_amdgcn_s_setprio(0); } while (0)
; #define PG8_WAIT_V(n) asm volatile("s_waitcnt vmcnt(" #n ")" ::: "memory")
; #define PG8_WAIT_L(n) asm volatile("s_waitcnt lgkmcnt(" #n ")" ::: "memory")
; #define PG8_BAR __builtin_amdgcn_s_barrier()
; #define PG8_SCHED __builtin_amdgcn_sched_barrier(0)
; template <class Epi, class Sched, bool ALIGN_EPI = false, bool SP2 = false>
; __device__ __forceinline__ void gemm_phase(PG8_LAS unsigned char* lds, const Gemm g, const Sched& S, const Epi& E) {
;     ...
;             PG8_LDB(B0, 1, 0); PG8_LDB(B1, 1, 1); PG8_SCHED; PG8_LDA(At, 1, 0); PG8_STAGE(PG8_SA(0, 1), a2 + hstepA, voffA);
;             PG8_WAIT_V(8); PG8_WAIT_L(0); PG8_BAR; PG8_MMA(0, 0, At, B0); PG8_MMA(0, 1, At, B1); PG8_BAR; PG8_SCHED;
;             PG8_LDA(At, 1, 1); PG8_STAGE(PG8_SB(1, 0), b3, voffB); PG8_STAGE(PG8_SB(1, 1), b3 + hstep, voffB); PG8_STAGE(PG8_SA(1, 0), a3, voffA);
	ds_read_b128 v[138:141], v240
	ds_read_b128 v[146:149], v240 offset:1024
	ds_read_b128 v[150:153], v240 offset:2048
	ds_read_b128 v[154:157], v240 offset:3072
	ds_read_b128 v[158:161], v178
	ds_read_b128 v[162:165], v178 offset:1024
	ds_read_b128 v[188:191], v178 offset:2048
	ds_read_b128 v[192:195], v178 offset:3072
	s_add_u32 s46, s46, 0x40000
	s_addc_u32 s47, s47, 0
	s_mov_b32 m0, s35
	v_lshl_add_u64 v[238:239], s[46:47], 0, v[132:133]
	ds_read_b128 v[196:199], v145 offset:32768
	ds_read_b128 v[200:203], v145 offset:33792
	ds_read_b128 v[204:207], v145 offset:34816
	ds_read_b128 v[208:211], v145 offset:35840
	ds_read_b128 v[212:215], v145 offset:36864
	ds_read_b128 v[216:219], v145 offset:37888
	ds_read_b128 v[220:223], v145 offset:38912
	ds_read_b128 v[234:237], v145 offset:39936
	global_load_lds_dwordx4 v[238:239], off
	v_lshl_add_u64 v[238:239], s[46:47], 0, v[130:131]
	s_mov_b32 m0, s48
	s_nop 0
	global_load_lds_dwordx4 v[238:239], off
	s_waitcnt vmcnt(8)
	s_waitcnt lgkmcnt(0)
	s_barrier
	s_setprio 1
	s_waitcnt lgkmcnt(0)
	v_mfma_f32_16x16x32_bf16 v[124:127], v[138:141], v[196:199], v[124:127]
	v_mfma_f32_16x16x32_bf16 v[120:123], v[150:153], v[196:199], v[120:123]
	v_mfma_f32_16x16x32_bf16 v[108:111], v[138:141], v[204:207], v[108:111]
	v_mfma_f32_16x16x32_bf16 v[104:107], v[150:153], v[204:207], v[104:107]
	v_mfma_f32_16x16x32_bf16 v[92:95], v[138:141], v[212:215], v[92:95]
	v_mfma_f32_16x16x32_bf16 v[88:91], v[150:153], v[212:215], v[88:91]
	v_mfma_f32_16x16x32_bf16 v[76:79], v[138:141], v[220:223], v[76:79]
	v_mfma_f32_16x16x32_bf16 v[72:75], v[150:153], v[220:223], v[72:75]
	v_mfma_f32_16x16x32_bf16 v[124:127], v[146:149], v[200:203], v[124:127]
	v_mfma_f32_16x16x32_bf16 v[120:123], v[154:157], v[200:203], v[120:123]
	v_mfma_f32_16x16x32_bf16 v[108:111], v[146:149], v[208:211], v[108:111]
	v_mfma_f32_16x16x32_bf16 v[104:107], v[154:157], v[208:211], v[104:107]
	v_mfma_f32_16x16x32_bf16 v[92:95], v[146:149], v[216:219], v[92:95]
	v_mfma_f32_16x16x32_bf16 v[88:91], v[154:157], v[216:219], v[88:91]
	v_mfma_f32_16x16x32_bf16 v[76:79], v[146:149], v[234:237], v[76:79]
	v_mfma_f32_16x16x32_bf16 v[72:75], v[154:157], v[234:237], v[72:75]
	s_setprio 0
	s_setprio 1
	v_mfma_f32_16x16x32_bf16 v[116:119], v[158:161], v[196:199], v[116:119]
	v_mfma_f32_16x16x32_bf16 v[112:115], v[188:191], v[196:199], v[112:115]
	v_mfma_f32_16x16x32_bf16 v[100:103], v[158:161], v[204:207], v[100:103]
	v_mfma_f32_16x16x32_bf16 v[96:99], v[188:191], v[204:207], v[96:99]
	v_mfma_f32_16x16x32_bf16 v[84:87], v[158:161], v[212:215], v[84:87]
	v_mfma_f32_16x16x32_bf16 v[80:83], v[188:191], v[212:215], v[80:83]
	v_mfma_f32_16x16x32_bf16 v[68:71], v[158:161], v[220:223], v[68:71]
	v_mfma_f32_16x16x32_bf16 v[64:67], v[188:191], v[220:223], v[64:67]
	v_mfma_f32_16x16x32_bf16 v[116:119], v[162:165], v[200:203], v[116:119]
	v_mfma_f32_16x16x32_bf16 v[112:115], v[192:195], v[200:203], v[112:115]
	v_mfma_f32_16x16x32_bf16 v[100:103], v[162:165], v[208:211], v[100:103]
	v_mfma_f32_16x16x32_bf16 v[96:99], v[192:195], v[208:211], v[96:99]
	v_mfma_f32_16x16x32_bf16 v[84:87], v[162:165], v[216:219], v[84:87]
	s_add_i32 s46, s59, s7
	v_mfma_f32_16x16x32_bf16 v[80:83], v[192:195], v[216:219], v[80:83]
	v_lshl_add_u64 v[166:167], v[166:167], 0, s[30:31]
	v_mfma_f32_16x16x32_bf16 v[68:71], v[162:165], v[234:237], v[68:71]
	s_mov_b32 m0, s46
	v_mfma_f32_16x16x32_bf16 v[64:67], v[192:195], v[234:237], v[64:67]
	s_setprio 0
	s_barrier
; #define PG8_STAGE(bufoff, gbase, voff) do { _Pragma("unroll") for (int _i = 0; _i < 2; ++_i) \
;         __builtin_amdgcn_global_load_lds((const unsigned*)((const char*)(gbase) + (voff)[_i]), (PG8_LAS unsigned*)(lds + (bufoff) + ldsw + _i * 8192), 16, 0, 0); } while (0)
; #define PG8_LDA(dst, b, h) do { _Pragma("unroll") for (int m = 0; m < 4; ++m) _Pragma("unroll") for (int k = 0; k < 2; ++k) dst[m][k] = *(const PG8_LAS bf16x8*)(lds + PG8_SA(b, h) + aoff + m * 2048 + k * 1024); } while (0)
; #define PG8_MMA(ai, bj, At, Bt) do { __builtin_amdgcn_s_setprio(1); _Pragma("unroll") for (int m = 0; m < 4; ++m) _Pragma("unroll") for (int n = 0; n < 2; ++n) _Pragma("unroll") for (int k = 0; k < 2; ++k) \
;         acc[ai][bj][m][n] = __builtin_amdgcn_mfma_f32_16x16x32_bf16(Bt[n][k], At[m][k], acc[ai][bj][m][n], 0, 0, 0); __builtin_amdgcn_s_setprio(0); } while (0)
; #define PG8_WAIT_V(n) asm volatile("s_waitcnt vmcnt(" #n ")" ::: "memory")
; #define PG8_WAIT_L(n) asm volatile("s_waitcnt lgkmcnt(" #n ")" ::: "memory")
; #define PG8_BAR __builtin_amdgcn_s_barrier()
; #define PG8_SCHED __builtin_amdgcn_sched_barrier(0)
; template <class Epi, class Sched, bool ALIGN_EPI = false, bool SP2 = false>
; __device__ __forceinline__ void gemm_phase(PG8_LAS unsigned char* lds, const Gemm g, const Sched& S, const Epi& E) {
;     ...
;             PG8_LDA(At, 1, 1); PG8_STAGE(PG8_SB(1, 0), b3, voffB); PG8_STAGE(PG8_SB(1, 1), b3 + hstep, voffB); PG8_STAGE(PG8_SA(1, 0), a3, voffA);
;             PG8_WAIT_V(8); PG8_WAIT_L(0); PG8_BAR; PG8_MMA(1, 0, At, B0); PG8_MMA(1, 1, At, B1); PG8_BAR; PG8_SCHED;
;     ...
;         if constexpr (ALIGN_EPI) { if (wr == 0) PG8_BAR; }
	ds_read_b128 v[196:199], v145 offset:49152
	ds_read_b128 v[200:203], v145 offset:50176
	ds_read_b128 v[204:207], v145 offset:51200
	ds_read_b128 v[208:211], v145 offset:52224
	ds_read_b128 v[212:215], v145 offset:53248
	ds_read_b128 v[216:219], v145 offset:54272
	ds_read_b128 v[220:223], v145 offset:55296
	ds_read_b128 v[234:237], v145 offset:56320
	global_load_lds_dwordx4 v[166:167], off
	s_add_i32 m0, s46, 0x2000
	s_add_u32 s38, s38, 0x40080
	v_lshl_add_u64 v[166:167], v[170:171], 0, s[30:31]
	s_addc_u32 s39, s39, 0
	s_add_i32 s46, s60, s7
	global_load_lds_dwordx4 v[166:167], off
	v_lshl_add_u64 v[166:167], s[38:39], 0, v[168:169]
	s_mov_b32 m0, s46
	s_nop 0
	global_load_lds_dwordx4 v[166:167], off
	v_lshl_add_u64 v[166:167], s[38:39], 0, v[128:129]
	s_add_i32 m0, s46, 0x2000
	s_nop 0
	global_load_lds_dwordx4 v[166:167], off
	v_lshl_add_u64 v[166:167], v[172:173], 0, s[30:31]
	s_mov_b32 m0, s49
	s_nop 0
	global_load_lds_dwordx4 v[166:167], off
	v_lshl_add_u64 v[166:167], v[224:225], 0, s[30:31]
	s_mov_b32 m0, s50
	s_nop 0
	global_load_lds_dwordx4 v[166:167], off
	s_waitcnt vmcnt(8)
	s_waitcnt lgkmcnt(0)
	s_barrier
	s_setprio 1
	s_waitcnt lgkmcnt(0)
	v_mfma_f32_16x16x32_bf16 v[60:63], v[138:141], v[196:199], v[60:63]
	v_mfma_f32_16x16x32_bf16 v[56:59], v[150:153], v[196:199], v[56:59]
	v_mfma_f32_16x16x32_bf16 v[44:47], v[138:141], v[204:207], v[44:47]
	v_mfma_f32_16x16x32_bf16 v[40:43], v[150:153], v[204:207], v[40:43]
	v_mfma_f32_16x16x32_bf16 v[28:31], v[138:141], v[212:215], v[28:31]
	v_mfma_f32_16x16x32_bf16 v[24:27], v[150:153], v[212:215], v[24:27]
	v_mfma_f32_16x16x32_bf16 v[12:15], v[138:141], v[220:223], v[12:15]
	v_mfma_f32_16x16x32_bf16 v[8:11], v[150:153], v[220:223], v[8:11]
	v_mfma_f32_16x16x32_bf16 v[60:63], v[146:149], v[200:203], v[60:63]
	v_mfma_f32_16x16x32_bf16 v[56:59], v[154:157], v[200:203], v[56:59]
	v_mfma_f32_16x16x32_bf16 v[44:47], v[146:149], v[208:211], v[44:47]
	v_mfma_f32_16x16x32_bf16 v[40:43], v[154:157], v[208:211], v[40:43]
	v_mfma_f32_16x16x32_bf16 v[28:31], v[146:149], v[216:219], v[28:31]
	v_mfma_f32_16x16x32_bf16 v[24:27], v[154:157], v[216:219], v[24:27]
	v_mfma_f32_16x16x32_bf16 v[12:15], v[146:149], v[234:237], v[12:15]
	s_add_i32 s58, s58, 2
	v_mfma_f32_16x16x32_bf16 v[8:11], v[154:157], v[234:237], v[8:11]
	s_add_u32 s56, s56, 0x100
	s_setprio 0
	s_setprio 1
	v_mfma_f32_16x16x32_bf16 v[52:55], v[158:161], v[196:199], v[52:55]
	s_addc_u32 s57, s57, 0
	v_mfma_f32_16x16x32_bf16 v[48:51], v[188:191], v[196:199], v[48:51]
	s_add_u32 s4, s4, 0x100
	v_mfma_f32_16x16x32_bf16 v[36:39], v[158:161], v[204:207], v[36:39]
	s_addc_u32 s5, s5, 0
	v_mfma_f32_16x16x32_bf16 v[32:35], v[188:191], v[204:207], v[32:35]
	s_add_u32 s38, s4, 0xfffc0080
	v_mfma_f32_16x16x32_bf16 v[20:23], v[158:161], v[212:215], v[20:23]
	s_addc_u32 s39, s5, -1
	v_mfma_f32_16x16x32_bf16 v[16:19], v[188:191], v[212:215], v[16:19]
	s_add_i32 s59, 0, 0x10000
	v_mfma_f32_16x16x32_bf16 v[4:7], v[158:161], v[220:223], v[4:7]
	s_cmp_eq_u32 s58, 12
	v_mfma_f32_16x16x32_bf16 v[0:3], v[188:191], v[220:223], v[0:3]
	s_cselect_b32 s47, s41, s39
	v_mfma_f32_16x16x32_bf16 v[52:55], v[162:165], v[200:203], v[52:55]
	s_cselect_b32 s46, s54, s38
	v_mfma_f32_16x16x32_bf16 v[48:51], v[192:195], v[200:203], v[48:51]
	s_cselect_b32 s39, s27, s57
	v_mfma_f32_16x16x32_bf16 v[36:39], v[162:165], v[208:211], v[36:39]
	s_cselect_b32 s38, s55, s56
	v_mfma_f32_16x16x32_bf16 v[32:35], v[192:195], v[208:211], v[32:35]
	s_add_i32 s62, 0, 0x14000
	v_mfma_f32_16x16x32_bf16 v[20:23], v[162:165], v[216:219], v[20:23]
	v_add_u32_e32 v241, s59, v143
	v_mfma_f32_16x16x32_bf16 v[16:19], v[192:195], v[216:219], v[16:19]
	v_add_u32_e32 v166, s62, v143
	v_mfma_f32_16x16x32_bf16 v[4:7], v[162:165], v[234:237], v[4:7]
	s_cmp_gt_u32 s58, 13
	v_mfma_f32_16x16x32_bf16 v[0:3], v[192:195], v[234:237], v[0:3]
	s_setprio 0
	s_barrier
	s_cbranch_scc0 .LBB0_434
	s_and_b64 vcc, exec, s[24:25]
	s_cbranch_vccz .LBB0_437
	s_barrier

; #define PG8_STAGE(bufoff, gbase, voff) do { _Pragma("unroll") for (int _i = 0; _i < 2; ++_i) \
;         __builtin_amdgcn_global_load_lds((const unsigned*)((const char*)(gbase) + (voff)[_i]), (PG8_LAS unsigned*)(lds + (bufoff) + ldsw + _i * 8192), 16, 0, 0); } while (0)
; #define PG8_LDA(dst, b, h) do { _Pragma("unroll") for (int m = 0; m < 4; ++m) _Pragma("unroll") for (int k = 0; k < 2; ++k) dst[m][k] = *(const PG8_LAS bf16x8*)(lds + PG8_SA(b, h) + aoff + m * 2048 + k * 1024); } while (0)
; #define PG8_LDB(dst, b, h) do { _Pragma("unroll") for (int n = 0; n < 2; ++n) _Pragma("unroll") for (int k = 0; k < 2; ++k) dst[n][k] = *(const PG8_LAS bf16x8*)(lds + PG8_SB(b, h) + boff + n * 2048 + k * 1024); } while (0)
; #define PG8_WAIT_V(n) asm volatile("s_waitcnt vmcnt(" #n ")" ::: "memory")
; #define PG8_WAIT_L(n) asm volatile("s_waitcnt lgkmcnt(" #n ")" ::: "memory")
; #define PG8_BAR __builtin_amdgcn_s_barrier()
; #define PG8_SCHED __builtin_amdgcn_sched_barrier(0)
; template <class Epi, class Sched, bool ALIGN_EPI = false, bool SP2 = false>
; __device__ __forceinline__ void gemm_phase(PG8_LAS unsigned char* lds, const Gemm g, const Sched& S, const Epi& E) {
;     ...
;         const bool has_next = S.next(ui + 1, nxt);
;         const char* nA = has_next ? (const char*)g.A + (size_t)nxt.pm * tstepA : cA; const char* nB = has_next ? (const char*)g.Bt + (size_t)nxt.pn * tstep : cB;
;         for (int t = 0; t < nt; t += 2) {
;             const bool last = (t == nt - 2);
;             const char* a1 = cA + (size_t)(t + 1) * kstepA;
;             const char* a2 = last ? nA : cA + (size_t)(t + 2) * kstepA; const char* b2 = last ? nB : cB + (size_t)(t + 2) * kstep;
;             const char* a3 = a2 + kstepA; const char* b3 = b2 + kstep;
;             if (last && has_next) S.a_ready(nxt);
;             if constexpr (SP2) {
;             PG8_LDB(B0, 0, 0); PG8_LDB(B1, 0, 1); PG8_SCHED; PG8_LDA(At, 0, 0); PG8_STAGE(PG8_SA(1, 1), a1 + hstepA, voffA);
;             PG8_WAIT_V(8); PG8_WAIT_L(0); PG8_BAR; PG8_MMA(0, 0, At, B0); PG8_MMA(0, 1, At, B1); PG8_BAR; PG8_SCHED;
;             PG8_LDA(At, 0, 1); PG8_STAGE(PG8_SB(0, 0), b2, voffB); PG8_STAGE(PG8_SB(0, 1), b2 + hstep, voffB); PG8_STAGE(PG8_SA(0, 0), a2, voffA);
;             PG8_WAIT_V(8); PG8_WAIT_L(0); PG8_BAR; PG8_MMA(1, 0, At, B0); PG8_MMA(1, 1, At, B1); PG8_BAR; PG8_SCHED;
.LBB0_732:
	s_ashr_i32 s53, s52, 31
	s_lshl_b64 s[6:7], s[52:53], 19
	s_add_u32 s54, s78, s6
	s_addc_u32 s55, s79, s7
	s_and_b64 s[6:7], s[38:39], exec
	s_cselect_b32 s5, s55, s37
	s_cselect_b32 s6, s54, s36
	s_ashr_i32 s51, s50, 31
	s_lshl_b64 s[56:57], s[50:51], 19
	s_add_u32 s56, s2, s56
	s_addc_u32 s57, s3, s57
	s_and_b64 s[60:61], s[38:39], exec
	s_cselect_b32 s7, s57, s41
	s_cselect_b32 s51, s56, s40
	s_add_u32 s53, s40, 0x100
	s_addc_u32 s64, s41, 0
	s_add_u32 s40, s36, 0x40080
	s_addc_u32 s41, s37, 0
	s_mov_b32 s65, -2
	s_add_u32 s58, s40, 0xfffc0080
	s_addc_u32 s59, s41, -1
	s_add_i32 s74, 0, 0x10000
	s_cmp_eq_u32 s65, 12
	s_cselect_b32 s61, s5, s59
	s_cselect_b32 s60, s6, s58
	s_cselect_b32 s59, s7, s64
	s_cselect_b32 s58, s51, s53
	s_add_i32 s91, 0, 0x14000
	v_add_u32_e32 v140, s74, v224
	v_add_u32_e32 v156, s91, v224
	ds_read_b128 v[128:131], v140
	ds_read_b128 v[132:135], v140 offset:1024
	ds_read_b128 v[136:139], v140 offset:2048
	ds_read_b128 v[140:143], v140 offset:3072
	ds_read_b128 v[144:147], v156
	ds_read_b128 v[148:151], v156 offset:1024
	ds_read_b128 v[152:155], v156 offset:2048
	ds_read_b128 v[156:159], v156 offset:3072
	v_lshl_add_u64 v[178:179], s[40:41], 0, v[196:197]
	s_add_i32 m0, s35, 0xc000
	ds_read_b128 v[160:163], v225
	ds_read_b128 v[164:167], v225 offset:1024
	ds_read_b128 v[170:173], v225 offset:2048
	ds_read_b128 v[198:201], v225 offset:3072
	ds_read_b128 v[202:205], v225 offset:4096
	ds_read_b128 v[206:209], v225 offset:5120
	ds_read_b128 v[210:213], v225 offset:6144
	ds_read_b128 v[214:217], v225 offset:7168
	global_load_lds_dwordx4 v[178:179], off
	v_lshl_add_u64 v[178:179], s[40:41], 0, v[194:195]
	s_add_i32 m0, s35, 0xe000
	s_nop 0
	global_load_lds_dwordx4 v[178:179], off
	s_waitcnt vmcnt(8)
	s_waitcnt lgkmcnt(0)
	s_barrier
	s_setprio 1
	s_waitcnt lgkmcnt(0)
	v_mfma_f32_16x16x32_bf16 v[124:127], v[128:131], v[160:163], 0
	v_mfma_f32_16x16x32_bf16 v[120:123], v[136:139], v[160:163], 0
	v_mfma_f32_16x16x32_bf16 v[108:111], v[128:131], v[170:173], 0
	v_mfma_f32_16x16x32_bf16 v[104:107], v[136:139], v[170:173], 0
	v_mfma_f32_16x16x32_bf16 v[92:95], v[128:131], v[202:205], 0
	v_mfma_f32_16x16x32_bf16 v[88:91], v[136:139], v[202:205], 0
	v_mfma_f32_16x16x32_bf16 v[76:79], v[128:131], v[210:213], 0
	v_mfma_f32_16x16x32_bf16 v[72:75], v[136:139], v[210:213], 0
	v_mfma_f32_16x16x32_bf16 v[124:127], v[132:135], v[164:167], v[124:127]
	v_mfma_f32_16x16x32_bf16 v[120:123], v[140:143], v[164:167], v[120:123]
	v_mfma_f32_16x16x32_bf16 v[108:111], v[132:135], v[198:201], v[108:111]
	v_mfma_f32_16x16x32_bf16 v[104:107], v[140:143], v[198:201], v[104:107]
	v_mfma_f32_16x16x32_bf16 v[92:95], v[132:135], v[206:209], v[92:95]
	v_mfma_f32_16x16x32_bf16 v[88:91], v[140:143], v[206:209], v[88:91]
	v_mfma_f32_16x16x32_bf16 v[76:79], v[132:135], v[214:217], v[76:79]
	v_mfma_f32_16x16x32_bf16 v[72:75], v[140:143], v[214:217], v[72:75]
	s_setprio 0
	s_setprio 1
	v_mfma_f32_16x16x32_bf16 v[116:119], v[144:147], v[160:163], 0
	v_mfma_f32_16x16x32_bf16 v[112:115], v[152:155], v[160:163], 0
	v_mfma_f32_16x16x32_bf16 v[100:103], v[144:147], v[170:173], 0
	v_mfma_f32_16x16x32_bf16 v[96:99], v[152:155], v[170:173], 0
	v_mfma_f32_16x16x32_bf16 v[84:87], v[144:147], v[202:205], 0
	v_mfma_f32_16x16x32_bf16 v[80:83], v[152:155], v[202:205], 0
	v_mfma_f32_16x16x32_bf16 v[68:71], v[144:147], v[210:213], 0
	v_mfma_f32_16x16x32_bf16 v[64:67], v[152:155], v[210:213], 0
	v_mfma_f32_16x16x32_bf16 v[116:119], v[148:151], v[164:167], v[116:119]
	v_mfma_f32_16x16x32_bf16 v[112:115], v[156:159], v[164:167], v[112:115]
	v_mfma_f32_16x16x32_bf16 v[100:103], v[148:151], v[198:201], v[100:103]
	v_mfma_f32_16x16x32_bf16 v[96:99], v[156:159], v[198:201], v[96:99]
	v_mfma_f32_16x16x32_bf16 v[84:87], v[148:151], v[206:209], v[84:87]
	s_add_i32 s74, s74, s34
	v_mfma_f32_16x16x32_bf16 v[80:83], v[156:159], v[206:209], v[80:83]
	v_lshl_add_u64 v[178:179], s[58:59], 0, v[168:169]
	v_mfma_f32_16x16x32_bf16 v[68:71], v[148:151], v[214:217], v[68:71]
	s_mov_b32 m0, s74
	v_mfma_f32_16x16x32_bf16 v[64:67], v[156:159], v[214:217], v[64:67]
	s_setprio 0
	s_barrier
	ds_read_b128 v[160:163], v225 offset:16384
	ds_read_b128 v[164:167], v225 offset:17408
	ds_read_b128 v[170:173], v225 offset:18432
	ds_read_b128 v[198:201], v225 offset:19456
	ds_read_b128 v[202:205], v225 offset:20480
	ds_read_b128 v[206:209], v225 offset:21504
	ds_read_b128 v[210:213], v225 offset:22528
	ds_read_b128 v[214:217], v225 offset:23552
	global_load_lds_dwordx4 v[178:179], off
	s_add_i32 m0, s74, 0x2000
	s_add_u32 s74, s58, 0x40000
	v_lshl_add_u64 v[218:219], s[58:59], 0, v[188:189]
	s_addc_u32 s75, s59, 0
	s_add_i32 s91, s91, s34
	global_load_lds_dwordx4 v[218:219], off
	v_lshl_add_u64 v[220:221], s[74:75], 0, v[168:169]
	s_mov_b32 m0, s91
	v_lshl_add_u64 v[234:235], s[60:61], 0, v[190:191]
	global_load_lds_dwordx4 v[220:221], off
	v_lshl_add_u64 v[220:221], s[74:75], 0, v[188:189]
	s_add_i32 m0, s91, 0x2000
	s_nop 0
	global_load_lds_dwordx4 v[220:221], off
	v_lshl_add_u64 v[220:221], s[60:61], 0, v[192:193]
	s_mov_b32 m0, s35
	s_nop 0
	global_load_lds_dwordx4 v[220:221], off
	s_mov_b32 m0, s69
	s_nop 0
	global_load_lds_dwordx4 v[234:235], off
	s_waitcnt vmcnt(8)
	s_waitcnt lgkmcnt(0)
	s_barrier
; #define PG8_STAGE(bufoff, gbase, voff) do { _Pragma("unroll") for (int _i = 0; _i < 2; ++_i) \
;         __builtin_amdgcn_global_load_lds((const unsigned*)((const char*)(gbase) + (voff)[_i]), (PG8_LAS unsigned*)(lds + (bufoff) + ldsw + _i * 8192), 16, 0, 0); } while (0)
; #define PG8_LDA(dst, b, h) do { _Pragma("unroll") for (int m = 0; m < 4; ++m) _Pragma("unroll") for (int k = 0; k < 2; ++k) dst[m][k] = *(const PG8_LAS bf16x8*)(lds + PG8_SA(b, h) + aoff + m * 2048 + k * 1024); } while (0)
; #define PG8_LDB(dst, b, h) do { _Pragma("unroll") for (int n = 0; n < 2; ++n) _Pragma("unroll") for (int k = 0; k < 2; ++k) dst[n][k] = *(const PG8_LAS bf16x8*)(lds + PG8_SB(b, h) + boff + n * 2048 + k * 1024); } while (0)
; #define PG8_MMA(ai, bj, At, Bt) do { __builtin_amdgcn_s_setprio(1); _Pragma("unroll") for (int m = 0; m < 4; ++m) _Pragma("unroll") for (int n = 0; n < 2; ++n) _Pragma("unroll") for (int k = 0; k < 2; ++k) \
;         acc[ai][bj][m][n] = __builtin_amdgcn_mfma_f32_16x16x32_bf16(Bt[n][k], At[m][k], acc[ai][bj][m][n], 0, 0, 0); __builtin_amdgcn_s_setprio(0); } while (0)
; #define PG8_WAIT_V(n) asm volatile("s_waitcnt vmcnt(" #n ")" ::: "memory")
; #define PG8_WAIT_L(n) asm volatile("s_waitcnt lgkmcnt(" #n ")" ::: "memory")
; #define PG8_BAR __builtin_amdgcn_s_barrier()
; #define PG8_SCHED __builtin_amdgcn_sched_barrier(0)
; template <class Epi, class Sched, bool ALIGN_EPI = false, bool SP2 = false>
; __device__ __forceinline__ void gemm_phase(PG8_LAS unsigned char* lds, const Gemm g, const Sched& S, const Epi& E) {
;     ...
;             PG8_WAIT_V(8); PG8_WAIT_L(0); PG8_BAR; PG8_MMA(1, 0, At, B0); PG8_MMA(1, 1, At, B1); PG8_BAR; PG8_SCHED;
;             PG8_LDB(B0, 1, 0); PG8_LDB(B1, 1, 1); PG8_SCHED; PG8_LDA(At, 1, 0); PG8_STAGE(PG8_SA(0, 1), a2 + hstepA, voffA);
;             PG8_WAIT_V(8); PG8_WAIT_L(0); PG8_BAR; PG8_MMA(0, 0, At, B0); PG8_MMA(0, 1, At, B1); PG8_BAR; PG8_SCHED;
	s_setprio 1
	s_waitcnt lgkmcnt(0)
	v_mfma_f32_16x16x32_bf16 v[60:63], v[128:131], v[160:163], 0
	v_mfma_f32_16x16x32_bf16 v[56:59], v[136:139], v[160:163], 0
	v_mfma_f32_16x16x32_bf16 v[44:47], v[128:131], v[170:173], 0
	v_mfma_f32_16x16x32_bf16 v[40:43], v[136:139], v[170:173], 0
	v_mfma_f32_16x16x32_bf16 v[28:31], v[128:131], v[202:205], 0
	v_mfma_f32_16x16x32_bf16 v[24:27], v[136:139], v[202:205], 0
	v_mfma_f32_16x16x32_bf16 v[12:15], v[128:131], v[210:213], 0
	v_mfma_f32_16x16x32_bf16 v[8:11], v[136:139], v[210:213], 0
	v_mfma_f32_16x16x32_bf16 v[60:63], v[132:135], v[164:167], v[60:63]
	v_mfma_f32_16x16x32_bf16 v[56:59], v[140:143], v[164:167], v[56:59]
	v_mfma_f32_16x16x32_bf16 v[44:47], v[132:135], v[198:201], v[44:47]
	v_mfma_f32_16x16x32_bf16 v[40:43], v[140:143], v[198:201], v[40:43]
	v_mfma_f32_16x16x32_bf16 v[28:31], v[132:135], v[206:209], v[28:31]
	v_mfma_f32_16x16x32_bf16 v[24:27], v[140:143], v[206:209], v[24:27]
	v_mfma_f32_16x16x32_bf16 v[12:15], v[132:135], v[214:217], v[12:15]
	v_mfma_f32_16x16x32_bf16 v[8:11], v[140:143], v[214:217], v[8:11]
	s_setprio 0
	s_setprio 1
	v_mfma_f32_16x16x32_bf16 v[52:55], v[144:147], v[160:163], 0
	v_mfma_f32_16x16x32_bf16 v[48:51], v[152:155], v[160:163], 0
	v_mfma_f32_16x16x32_bf16 v[36:39], v[144:147], v[170:173], 0
	v_mfma_f32_16x16x32_bf16 v[32:35], v[152:155], v[170:173], 0
	v_mfma_f32_16x16x32_bf16 v[20:23], v[144:147], v[202:205], 0
	v_mfma_f32_16x16x32_bf16 v[16:19], v[152:155], v[202:205], 0
	v_mfma_f32_16x16x32_bf16 v[4:7], v[144:147], v[210:213], 0
	v_mfma_f32_16x16x32_bf16 v[0:3], v[152:155], v[210:213], 0
	v_mfma_f32_16x16x32_bf16 v[52:55], v[148:151], v[164:167], v[52:55]
	v_mfma_f32_16x16x32_bf16 v[48:51], v[156:159], v[164:167], v[48:51]
	v_mfma_f32_16x16x32_bf16 v[36:39], v[148:151], v[198:201], v[36:39]
	v_mfma_f32_16x16x32_bf16 v[32:35], v[156:159], v[198:201], v[32:35]
	s_add_i32 s74, 0, 0x18000
	v_mfma_f32_16x16x32_bf16 v[20:23], v[148:151], v[206:209], v[20:23]
	s_add_i32 s75, 0, 0x1c000
	v_mfma_f32_16x16x32_bf16 v[16:19], v[156:159], v[206:209], v[16:19]
	v_add_u32_e32 v240, s74, v224
	v_mfma_f32_16x16x32_bf16 v[4:7], v[148:151], v[214:217], v[4:7]
	v_add_u32_e32 v241, s75, v224
	v_mfma_f32_16x16x32_bf16 v[0:3], v[156:159], v[214:217], v[0:3]
	s_setprio 0
	s_barrier
	ds_read_b128 v[128:131], v240
	ds_read_b128 v[132:135], v240 offset:1024
	ds_read_b128 v[136:139], v240 offset:2048
	ds_read_b128 v[140:143], v240 offset:3072
	ds_read_b128 v[144:147], v241
	ds_read_b128 v[148:151], v241 offset:1024
	ds_read_b128 v[152:155], v241 offset:2048
	ds_read_b128 v[156:159], v241 offset:3072
	s_add_u32 s60, s60, 0x40000
	s_addc_u32 s61, s61, 0
	s_mov_b32 m0, s73
	v_lshl_add_u64 v[236:237], s[60:61], 0, v[192:193]
	ds_read_b128 v[160:163], v225 offset:32768
	ds_read_b128 v[164:167], v225 offset:33792
	ds_read_b128 v[170:173], v225 offset:34816
	ds_read_b128 v[198:201], v225 offset:35840
	ds_read_b128 v[202:205], v225 offset:36864
	ds_read_b128 v[206:209], v225 offset:37888
	ds_read_b128 v[210:213], v225 offset:38912
	ds_read_b128 v[214:217], v225 offset:39936
	global_load_lds_dwordx4 v[236:237], off
	v_lshl_add_u64 v[236:237], s[60:61], 0, v[190:191]
	s_mov_b32 m0, s80
	s_nop 0
	global_load_lds_dwordx4 v[236:237], off
	s_waitcnt vmcnt(8)
	s_waitcnt lgkmcnt(0)
	s_barrier
	s_setprio 1
	s_waitcnt lgkmcnt(0)
	v_mfma_f32_16x16x32_bf16 v[124:127], v[128:131], v[160:163], v[124:127]
	v_mfma_f32_16x16x32_bf16 v[120:123], v[136:139], v[160:163], v[120:123]
	v_mfma_f32_16x16x32_bf16 v[108:111], v[128:131], v[170:173], v[108:111]
	v_mfma_f32_16x16x32_bf16 v[104:107], v[136:139], v[170:173], v[104:107]
	v_mfma_f32_16x16x32_bf16 v[92:95], v[128:131], v[202:205], v[92:95]
	v_mfma_f32_16x16x32_bf16 v[88:91], v[136:139], v[202:205], v[88:91]
	v_mfma_f32_16x16x32_bf16 v[76:79], v[128:131], v[210:213], v[76:79]
	v_mfma_f32_16x16x32_bf16 v[72:75], v[136:139], v[210:213], v[72:75]
	v_mfma_f32_16x16x32_bf16 v[124:127], v[132:135], v[164:167], v[124:127]
	v_mfma_f32_16x16x32_bf16 v[120:123], v[140:143], v[164:167], v[120:123]
	v_mfma_f32_16x16x32_bf16 v[108:111], v[132:135], v[198:201], v[108:111]
	v_mfma_f32_16x16x32_bf16 v[104:107], v[140:143], v[198:201], v[104:107]
	v_mfma_f32_16x16x32_bf16 v[92:95], v[132:135], v[206:209], v[92:95]
	v_mfma_f32_16x16x32_bf16 v[88:91], v[140:143], v[206:209], v[88:91]
	v_mfma_f32_16x16x32_bf16 v[76:79], v[132:135], v[214:217], v[76:79]
	v_mfma_f32_16x16x32_bf16 v[72:75], v[140:143], v[214:217], v[72:75]
	s_setprio 0
	s_setprio 1
	v_mfma_f32_16x16x32_bf16 v[116:119], v[144:147], v[160:163], v[116:119]
	v_mfma_f32_16x16x32_bf16 v[112:115], v[152:155], v[160:163], v[112:115]
	v_mfma_f32_16x16x32_bf16 v[100:103], v[144:147], v[170:173], v[100:103]
	v_mfma_f32_16x16x32_bf16 v[96:99], v[152:155], v[170:173], v[96:99]
	v_mfma_f32_16x16x32_bf16 v[84:87], v[144:147], v[202:205], v[84:87]
	v_mfma_f32_16x16x32_bf16 v[80:83], v[152:155], v[202:205], v[80:83]
	v_mfma_f32_16x16x32_bf16 v[68:71], v[144:147], v[210:213], v[68:71]
	v_mfma_f32_16x16x32_bf16 v[64:67], v[152:155], v[210:213], v[64:67]
	v_mfma_f32_16x16x32_bf16 v[116:119], v[148:151], v[164:167], v[116:119]
	v_mfma_f32_16x16x32_bf16 v[112:115], v[156:159], v[164:167], v[112:115]
	v_mfma_f32_16x16x32_bf16 v[100:103], v[148:151], v[198:201], v[100:103]
	v_mfma_f32_16x16x32_bf16 v[96:99], v[156:159], v[198:201], v[96:99]
	v_mfma_f32_16x16x32_bf16 v[84:87], v[148:151], v[206:209], v[84:87]
	s_add_i32 s60, s74, s34
	v_mfma_f32_16x16x32_bf16 v[80:83], v[156:159], v[206:209], v[80:83]
	v_lshl_add_u64 v[178:179], v[178:179], 0, s[30:31]
	v_mfma_f32_16x16x32_bf16 v[68:71], v[148:151], v[214:217], v[68:71]
	s_mov_b32 m0, s60
	v_mfma_f32_16x16x32_bf16 v[64:67], v[156:159], v[214:217], v[64:67]
	s_setprio 0
	s_barrier
; #define PG8_STAGE(bufoff, gbase, voff) do { _Pragma("unroll") for (int _i = 0; _i < 2; ++_i) \
;         __builtin_amdgcn_global_load_lds((const unsigned*)((const char*)(gbase) + (voff)[_i]), (PG8_LAS unsigned*)(lds + (bufoff) + ldsw + _i * 8192), 16, 0, 0); } while (0)
; #define PG8_LDA(dst, b, h) do { _Pragma("unroll") for (int m = 0; m < 4; ++m) _Pragma("unroll") for (int k = 0; k < 2; ++k) dst[m][k] = *(const PG8_LAS bf16x8*)(lds + PG8_SA(b, h) + aoff + m * 2048 + k * 1024); } while (0)
; #define PG8_LDB(dst, b, h) do { _Pragma("unroll") for (int n = 0; n < 2; ++n) _Pragma("unroll") for (int k = 0; k < 2; ++k) dst[n][k] = *(const PG8_LAS bf16x8*)(lds + PG8_SB(b, h) + boff + n * 2048 + k * 1024); } while (0)
; #define PG8_MMA(ai, bj, At, Bt) do { __builtin_amdgcn_s_setprio(1); _Pragma("unroll") for (int m = 0; m < 4; ++m) _Pragma("unroll") for (int n = 0; n < 2; ++n) _Pragma("unroll") for (int k = 0; k < 2; ++k) \
;         acc[ai][bj][m][n] = __builtin_amdgcn_mfma_f32_16x16x32_bf16(Bt[n][k], At[m][k], acc[ai][bj][m][n], 0, 0, 0); __builtin_amdgcn_s_setprio(0); } while (0)
; #define PG8_WAIT_V(n) asm volatile("s_waitcnt vmcnt(" #n ")" ::: "memory")
; template <class Epi, class Sched, bool ALIGN_EPI = false, bool SP2 = false>
; __device__ __forceinline__ void gemm_phase(PG8_LAS unsigned char* lds, const Gemm g, const Sched& S, const Epi& E) {
;     ...
;             PG8_LDB(B0, 0, 0); PG8_LDB(B1, 0, 1); PG8_SCHED; PG8_LDA(At, 0, 0); PG8_STAGE(PG8_SA(1, 1), a1 + hstepA, voffA);
;             PG8_WAIT_V(8); PG8_WAIT_L(0); PG8_BAR; PG8_MMA(0, 0, At, B0); PG8_MMA(0, 1, At, B1); PG8_BAR; PG8_SCHED;
;             PG8_LDA(At, 0, 1); PG8_STAGE(PG8_SB(0, 0), b2, voffB); PG8_STAGE(PG8_SB(0, 1), b2 + hstep, voffB); PG8_STAGE(PG8_SA(0, 0), a2, voffA);
;             PG8_WAIT_V(8); PG8_WAIT_L(0); PG8_BAR; PG8_MMA(1, 0, At, B0); PG8_MMA(1, 1, At, B1); PG8_BAR; PG8_SCHED;
;             PG8_LDB(B0, 1, 0); PG8_LDB(B1, 1, 1); PG8_SCHED; PG8_LDA(At, 1, 0); PG8_STAGE(PG8_SA(0, 1), a2 + hstepA, voffA);
;             PG8_WAIT_V(8); PG8_WAIT_L(0); PG8_BAR; PG8_MMA(0, 0, At, B0); PG8_MMA(0, 1, At, B1); PG8_BAR; PG8_SCHED;
;             PG8_LDA(At, 1, 1); PG8_STAGE(PG8_SB(1, 0), b3, voffB); PG8_STAGE(PG8_SB(1, 1), b3 + hstep, voffB); PG8_STAGE(PG8_SA(1, 0), a3, voffA);
;             PG8_WAIT_V(8); PG8_WAIT_L(0); PG8_BAR; PG8_MMA(1, 0, At, B0); PG8_MMA(1, 1, At, B1); PG8_BAR; PG8_SCHED;
	ds_read_b128 v[160:163], v225 offset:49152
	ds_read_b128 v[164:167], v225 offset:50176
	ds_read_b128 v[170:173], v225 offset:51200
	ds_read_b128 v[198:201], v225 offset:52224
	ds_read_b128 v[202:205], v225 offset:53248
	ds_read_b128 v[206:209], v225 offset:54272
	ds_read_b128 v[210:213], v225 offset:55296
	ds_read_b128 v[214:217], v225 offset:56320
	global_load_lds_dwordx4 v[178:179], off
	s_add_i32 m0, s60, 0x2000
	s_add_u32 s58, s58, 0x40080
	v_lshl_add_u64 v[178:179], v[218:219], 0, s[30:31]
	s_addc_u32 s59, s59, 0
	s_add_i32 s60, s75, s34
	global_load_lds_dwordx4 v[178:179], off
	v_lshl_add_u64 v[178:179], s[58:59], 0, v[168:169]
	s_mov_b32 m0, s60
	s_nop 0
	global_load_lds_dwordx4 v[178:179], off
	v_lshl_add_u64 v[178:179], s[58:59], 0, v[188:189]
	s_add_i32 m0, s60, 0x2000
	s_nop 0
	global_load_lds_dwordx4 v[178:179], off
	v_lshl_add_u64 v[178:179], v[220:221], 0, s[30:31]
	s_mov_b32 m0, s84
	s_nop 0
	global_load_lds_dwordx4 v[178:179], off
	v_lshl_add_u64 v[178:179], v[234:235], 0, s[30:31]
	s_mov_b32 m0, s85
	s_nop 0
	global_load_lds_dwordx4 v[178:179], off
	s_waitcnt vmcnt(8)
	s_waitcnt lgkmcnt(0)
	s_barrier
	s_setprio 1
	s_waitcnt lgkmcnt(0)
	v_mfma_f32_16x16x32_bf16 v[60:63], v[128:131], v[160:163], v[60:63]
	v_mfma_f32_16x16x32_bf16 v[56:59], v[136:139], v[160:163], v[56:59]
	v_mfma_f32_16x16x32_bf16 v[44:47], v[128:131], v[170:173], v[44:47]
	v_mfma_f32_16x16x32_bf16 v[40:43], v[136:139], v[170:173], v[40:43]
	v_mfma_f32_16x16x32_bf16 v[28:31], v[128:131], v[202:205], v[28:31]
	v_mfma_f32_16x16x32_bf16 v[24:27], v[136:139], v[202:205], v[24:27]
	v_mfma_f32_16x16x32_bf16 v[12:15], v[128:131], v[210:213], v[12:15]
	v_mfma_f32_16x16x32_bf16 v[8:11], v[136:139], v[210:213], v[8:11]
	v_mfma_f32_16x16x32_bf16 v[60:63], v[132:135], v[164:167], v[60:63]
	v_mfma_f32_16x16x32_bf16 v[56:59], v[140:143], v[164:167], v[56:59]
	v_mfma_f32_16x16x32_bf16 v[44:47], v[132:135], v[198:201], v[44:47]
	v_mfma_f32_16x16x32_bf16 v[40:43], v[140:143], v[198:201], v[40:43]
	v_mfma_f32_16x16x32_bf16 v[28:31], v[132:135], v[206:209], v[28:31]
	v_mfma_f32_16x16x32_bf16 v[24:27], v[140:143], v[206:209], v[24:27]
	v_mfma_f32_16x16x32_bf16 v[12:15], v[132:135], v[214:217], v[12:15]
	v_mfma_f32_16x16x32_bf16 v[8:11], v[140:143], v[214:217], v[8:11]
	s_add_i32 s65, s65, 2
	s_setprio 0
	s_setprio 1
	v_mfma_f32_16x16x32_bf16 v[52:55], v[144:147], v[160:163], v[52:55]
	s_add_u32 s53, s53, 0x100
	v_mfma_f32_16x16x32_bf16 v[48:51], v[152:155], v[160:163], v[48:51]
	s_addc_u32 s64, s64, 0
	v_mfma_f32_16x16x32_bf16 v[36:39], v[144:147], v[170:173], v[36:39]
	s_add_u32 s40, s40, 0x100
	v_mfma_f32_16x16x32_bf16 v[32:35], v[152:155], v[170:173], v[32:35]
	s_addc_u32 s41, s41, 0
	v_mfma_f32_16x16x32_bf16 v[20:23], v[144:147], v[202:205], v[20:23]
	s_add_u32 s58, s40, 0xfffc0080
	v_mfma_f32_16x16x32_bf16 v[16:19], v[152:155], v[202:205], v[16:19]
	s_addc_u32 s59, s41, -1
	v_mfma_f32_16x16x32_bf16 v[4:7], v[144:147], v[210:213], v[4:7]
	s_add_i32 s74, 0, 0x10000
	v_mfma_f32_16x16x32_bf16 v[0:3], v[152:155], v[210:213], v[0:3]
	s_cmp_eq_u32 s65, 12
	v_mfma_f32_16x16x32_bf16 v[52:55], v[148:151], v[164:167], v[52:55]
	s_cselect_b32 s61, s5, s59
	v_mfma_f32_16x16x32_bf16 v[48:51], v[156:159], v[164:167], v[48:51]
	s_cselect_b32 s60, s6, s58
	v_mfma_f32_16x16x32_bf16 v[36:39], v[148:151], v[198:201], v[36:39]
	s_cselect_b32 s59, s7, s64
	v_mfma_f32_16x16x32_bf16 v[32:35], v[156:159], v[198:201], v[32:35]
	s_cselect_b32 s58, s51, s53
	v_mfma_f32_16x16x32_bf16 v[20:23], v[148:151], v[206:209], v[20:23]
	s_add_i32 s91, 0, 0x14000
	v_mfma_f32_16x16x32_bf16 v[16:19], v[156:159], v[206:209], v[16:19]
	v_add_u32_e32 v242, s74, v224
	v_mfma_f32_16x16x32_bf16 v[4:7], v[148:151], v[214:217], v[4:7]
	v_add_u32_e32 v243, s91, v224
	v_mfma_f32_16x16x32_bf16 v[0:3], v[156:159], v[214:217], v[0:3]
	s_setprio 0
	s_barrier
.LBB0_733:
	ds_read_b128 v[128:131], v242
	ds_read_b128 v[132:135], v242 offset:1024
	ds_read_b128 v[136:139], v242 offset:2048
	ds_read_b128 v[140:143], v242 offset:3072
	ds_read_b128 v[144:147], v243
	ds_read_b128 v[148:151], v243 offset:1024
	ds_read_b128 v[152:155], v243 offset:2048
	ds_read_b128 v[156:159], v243 offset:3072
	v_lshl_add_u64 v[178:179], s[40:41], 0, v[196:197]
	s_add_i32 m0, s35, 0xc000
	ds_read_b128 v[160:163], v225
	ds_read_b128 v[164:167], v225 offset:1024
	ds_read_b128 v[170:173], v225 offset:2048
	ds_read_b128 v[198:201], v225 offset:3072
	ds_read_b128 v[202:205], v225 offset:4096
	ds_read_b128 v[206:209], v225 offset:5120
	ds_read_b128 v[210:213], v225 offset:6144
	ds_read_b128 v[214:217], v225 offset:7168
	global_load_lds_dwordx4 v[178:179], off
	v_lshl_add_u64 v[178:179], s[40:41], 0, v[194:195]
	s_add_i32 m0, s35, 0xe000
	s_nop 0
	global_load_lds_dwordx4 v[178:179], off
	s_waitcnt vmcnt(8)
	s_waitcnt lgkmcnt(0)
	s_barrier
; #define PG8_STAGE(bufoff, gbase, voff) do { _Pragma("unroll") for (int _i = 0; _i < 2; ++_i) \
;         __builtin_amdgcn_global_load_lds((const unsigned*)((const char*)(gbase) + (voff)[_i]), (PG8_LAS unsigned*)(lds + (bufoff) + ldsw + _i * 8192), 16, 0, 0); } while (0)
; #define PG8_LDA(dst, b, h) do { _Pragma("unroll") for (int m = 0; m < 4; ++m) _Pragma("unroll") for (int k = 0; k < 2; ++k) dst[m][k] = *(const PG8_LAS bf16x8*)(lds + PG8_SA(b, h) + aoff + m * 2048 + k * 1024); } while (0)
; #define PG8_LDB(dst, b, h) do { _Pragma("unroll") for (int n = 0; n < 2; ++n) _Pragma("unroll") for (int k = 0; k < 2; ++k) dst[n][k] = *(const PG8_LAS bf16x8*)(lds + PG8_SB(b, h) + boff + n * 2048 + k * 1024); } while (0)
; #define PG8_MMA(ai, bj, At, Bt) do { __builtin_amdgcn_s_setprio(1); _Pragma("unroll") for (int m = 0; m < 4; ++m) _Pragma("unroll") for (int n = 0; n < 2; ++n) _Pragma("unroll") for (int k = 0; k < 2; ++k) \
;         acc[ai][bj][m][n] = __builtin_amdgcn_mfma_f32_16x16x32_bf16(Bt[n][k], At[m][k], acc[ai][bj][m][n], 0, 0, 0); __builtin_amdgcn_s_setprio(0); } while (0)
; #define PG8_WAIT_V(n) asm volatile("s_waitcnt vmcnt(" #n ")" ::: "memory")
; #define PG8_WAIT_L(n) asm volatile("s_waitcnt lgkmcnt(" #n ")" ::: "memory")
; #define PG8_BAR __builtin_amdgcn_s_barrier()
; #define PG8_SCHED __builtin_amdgcn_sched_barrier(0)
; template <class Epi, class Sched, bool ALIGN_EPI = false, bool SP2 = false>
; __device__ __forceinline__ void gemm_phase(PG8_LAS unsigned char* lds, const Gemm g, const Sched& S, const Epi& E) {
;     ...
;             PG8_LDB(B0, 0, 0); PG8_LDB(B1, 0, 1); PG8_SCHED; PG8_LDA(At, 0, 0); PG8_STAGE(PG8_SA(1, 1), a1 + hstepA, voffA);
;             PG8_WAIT_V(8); PG8_WAIT_L(0); PG8_BAR; PG8_MMA(0, 0, At, B0); PG8_MMA(0, 1, At, B1); PG8_BAR; PG8_SCHED;
;             PG8_LDA(At, 0, 1); PG8_STAGE(PG8_SB(0, 0), b2, voffB); PG8_STAGE(PG8_SB(0, 1), b2 + hstep, voffB); PG8_STAGE(PG8_SA(0, 0), a2, voffA);
;             PG8_WAIT_V(8); PG8_WAIT_L(0); PG8_BAR; PG8_MMA(1, 0, At, B0); PG8_MMA(1, 1, At, B1); PG8_BAR; PG8_SCHED;
	s_setprio 1
	s_waitcnt lgkmcnt(0)
	v_mfma_f32_16x16x32_bf16 v[124:127], v[128:131], v[160:163], v[124:127]
	v_mfma_f32_16x16x32_bf16 v[120:123], v[136:139], v[160:163], v[120:123]
	v_mfma_f32_16x16x32_bf16 v[108:111], v[128:131], v[170:173], v[108:111]
	v_mfma_f32_16x16x32_bf16 v[104:107], v[136:139], v[170:173], v[104:107]
	v_mfma_f32_16x16x32_bf16 v[92:95], v[128:131], v[202:205], v[92:95]
	v_mfma_f32_16x16x32_bf16 v[88:91], v[136:139], v[202:205], v[88:91]
	v_mfma_f32_16x16x32_bf16 v[76:79], v[128:131], v[210:213], v[76:79]
	v_mfma_f32_16x16x32_bf16 v[72:75], v[136:139], v[210:213], v[72:75]
	v_mfma_f32_16x16x32_bf16 v[124:127], v[132:135], v[164:167], v[124:127]
	v_mfma_f32_16x16x32_bf16 v[120:123], v[140:143], v[164:167], v[120:123]
	v_mfma_f32_16x16x32_bf16 v[108:111], v[132:135], v[198:201], v[108:111]
	v_mfma_f32_16x16x32_bf16 v[104:107], v[140:143], v[198:201], v[104:107]
	v_mfma_f32_16x16x32_bf16 v[92:95], v[132:135], v[206:209], v[92:95]
	v_mfma_f32_16x16x32_bf16 v[88:91], v[140:143], v[206:209], v[88:91]
	v_mfma_f32_16x16x32_bf16 v[76:79], v[132:135], v[214:217], v[76:79]
	v_mfma_f32_16x16x32_bf16 v[72:75], v[140:143], v[214:217], v[72:75]
	s_setprio 0
	s_setprio 1
	v_mfma_f32_16x16x32_bf16 v[116:119], v[144:147], v[160:163], v[116:119]
	v_mfma_f32_16x16x32_bf16 v[112:115], v[152:155], v[160:163], v[112:115]
	v_mfma_f32_16x16x32_bf16 v[100:103], v[144:147], v[170:173], v[100:103]
	v_mfma_f32_16x16x32_bf16 v[96:99], v[152:155], v[170:173], v[96:99]
	v_mfma_f32_16x16x32_bf16 v[84:87], v[144:147], v[202:205], v[84:87]
	v_mfma_f32_16x16x32_bf16 v[80:83], v[152:155], v[202:205], v[80:83]
	v_mfma_f32_16x16x32_bf16 v[68:71], v[144:147], v[210:213], v[68:71]
	v_mfma_f32_16x16x32_bf16 v[64:67], v[152:155], v[210:213], v[64:67]
	v_mfma_f32_16x16x32_bf16 v[116:119], v[148:151], v[164:167], v[116:119]
	v_mfma_f32_16x16x32_bf16 v[112:115], v[156:159], v[164:167], v[112:115]
	v_mfma_f32_16x16x32_bf16 v[100:103], v[148:151], v[198:201], v[100:103]
	v_mfma_f32_16x16x32_bf16 v[96:99], v[156:159], v[198:201], v[96:99]
	v_mfma_f32_16x16x32_bf16 v[84:87], v[148:151], v[206:209], v[84:87]
	s_add_i32 s74, s74, s34
	v_mfma_f32_16x16x32_bf16 v[80:83], v[156:159], v[206:209], v[80:83]
	v_lshl_add_u64 v[178:179], s[58:59], 0, v[168:169]
	v_mfma_f32_16x16x32_bf16 v[68:71], v[148:151], v[214:217], v[68:71]
	s_mov_b32 m0, s74
	v_mfma_f32_16x16x32_bf16 v[64:67], v[156:159], v[214:217], v[64:67]
	s_setprio 0
	s_barrier
	ds_read_b128 v[160:163], v225 offset:16384
	ds_read_b128 v[164:167], v225 offset:17408
	ds_read_b128 v[170:173], v225 offset:18432
	ds_read_b128 v[198:201], v225 offset:19456
	ds_read_b128 v[202:205], v225 offset:20480
	ds_read_b128 v[206:209], v225 offset:21504
	ds_read_b128 v[210:213], v225 offset:22528
	ds_read_b128 v[214:217], v225 offset:23552
	global_load_lds_dwordx4 v[178:179], off
	s_add_i32 m0, s74, 0x2000
	s_add_u32 s74, s58, 0x40000
	v_lshl_add_u64 v[218:219], s[58:59], 0, v[188:189]
	s_addc_u32 s75, s59, 0
	s_add_i32 s91, s91, s34
	global_load_lds_dwordx4 v[218:219], off
	v_lshl_add_u64 v[220:221], s[74:75], 0, v[168:169]
	s_mov_b32 m0, s91
	v_lshl_add_u64 v[234:235], s[60:61], 0, v[190:191]
	global_load_lds_dwordx4 v[220:221], off
	v_lshl_add_u64 v[220:221], s[74:75], 0, v[188:189]
	s_add_i32 m0, s91, 0x2000
	s_nop 0
	global_load_lds_dwordx4 v[220:221], off
	v_lshl_add_u64 v[220:221], s[60:61], 0, v[192:193]
	s_mov_b32 m0, s35
	s_nop 0
	global_load_lds_dwordx4 v[220:221], off
	s_mov_b32 m0, s69
	s_nop 0
	global_load_lds_dwordx4 v[234:235], off
	s_waitcnt vmcnt(8)
	s_waitcnt lgkmcnt(0)
	s_barrier
	s_setprio 1
	s_waitcnt lgkmcnt(0)
	v_mfma_f32_16x16x32_bf16 v[60:63], v[128:131], v[160:163], v[60:63]
	v_mfma_f32_16x16x32_bf16 v[56:59], v[136:139], v[160:163], v[56:59]
	v_mfma_f32_16x16x32_bf16 v[44:47], v[128:131], v[170:173], v[44:47]
	v_mfma_f32_16x16x32_bf16 v[40:43], v[136:139], v[170:173], v[40:43]
	v_mfma_f32_16x16x32_bf16 v[28:31], v[128:131], v[202:205], v[28:31]
	v_mfma_f32_16x16x32_bf16 v[24:27], v[136:139], v[202:205], v[24:27]
	v_mfma_f32_16x16x32_bf16 v[12:15], v[128:131], v[210:213], v[12:15]
	v_mfma_f32_16x16x32_bf16 v[8:11], v[136:139], v[210:213], v[8:11]
	v_mfma_f32_16x16x32_bf16 v[60:63], v[132:135], v[164:167], v[60:63]
	v_mfma_f32_16x16x32_bf16 v[56:59], v[140:143], v[164:167], v[56:59]
	v_mfma_f32_16x16x32_bf16 v[44:47], v[132:135], v[198:201], v[44:47]
	v_mfma_f32_16x16x32_bf16 v[40:43], v[140:143], v[198:201], v[40:43]
	v_mfma_f32_16x16x32_bf16 v[28:31], v[132:135], v[206:209], v[28:31]
	v_mfma_f32_16x16x32_bf16 v[24:27], v[140:143], v[206:209], v[24:27]
	v_mfma_f32_16x16x32_bf16 v[12:15], v[132:135], v[214:217], v[12:15]
	v_mfma_f32_16x16x32_bf16 v[8:11], v[140:143], v[214:217], v[8:11]
	s_setprio 0
	s_setprio 1
	v_mfma_f32_16x16x32_bf16 v[52:55], v[144:147], v[160:163], v[52:55]
	v_mfma_f32_16x16x32_bf16 v[48:51], v[152:155], v[160:163], v[48:51]
	v_mfma_f32_16x16x32_bf16 v[36:39], v[144:147], v[170:173], v[36:39]
	v_mfma_f32_16x16x32_bf16 v[32:35], v[152:155], v[170:173], v[32:35]
	v_mfma_f32_16x16x32_bf16 v[20:23], v[144:147], v[202:205], v[20:23]
	v_mfma_f32_16x16x32_bf16 v[16:19], v[152:155], v[202:205], v[16:19]
	v_mfma_f32_16x16x32_bf16 v[4:7], v[144:147], v[210:213], v[4:7]
	v_mfma_f32_16x16x32_bf16 v[0:3], v[152:155], v[210:213], v[0:3]
	v_mfma_f32_16x16x32_bf16 v[52:55], v[148:151], v[164:167], v[52:55]
	v_mfma_f32_16x16x32_bf16 v[48:51], v[156:159], v[164:167], v[48:51]
	v_mfma_f32_16x16x32_bf16 v[36:39], v[148:151], v[198:201], v[36:39]
	v_mfma_f32_16x16x32_bf16 v[32:35], v[156:159], v[198:201], v[32:35]
	s_add_i32 s74, 0, 0x18000
	v_mfma_f32_16x16x32_bf16 v[20:23], v[148:151], v[206:209], v[20:23]
	s_add_i32 s75, 0, 0x1c000
	v_mfma_f32_16x16x32_bf16 v[16:19], v[156:159], v[206:209], v[16:19]
	v_add_u32_e32 v240, s74, v224
	v_mfma_f32_16x16x32_bf16 v[4:7], v[148:151], v[214:217], v[4:7]
	v_add_u32_e32 v241, s75, v224
	v_mfma_f32_16x16x32_bf16 v[0:3], v[156:159], v[214:217], v[0:3]
	s_setprio 0
	s_barrier
; #define PG8_STAGE(bufoff, gbase, voff) do { _Pragma("unroll") for (int _i = 0; _i < 2; ++_i) \
;         __builtin_amdgcn_global_load_lds((const unsigned*)((const char*)(gbase) + (voff)[_i]), (PG8_LAS unsigned*)(lds + (bufoff) + ldsw + _i * 8192), 16, 0, 0); } while (0)
; #define PG8_LDA(dst, b, h) do { _Pragma("unroll") for (int m = 0; m < 4; ++m) _Pragma("unroll") for (int k = 0; k < 2; ++k) dst[m][k] = *(const PG8_LAS bf16x8*)(lds + PG8_SA(b, h) + aoff + m * 2048 + k * 1024); } while (0)
; #define PG8_LDB(dst, b, h) do { _Pragma("unroll") for (int n = 0; n < 2; ++n) _Pragma("unroll") for (int k = 0; k < 2; ++k) dst[n][k] = *(const PG8_LAS bf16x8*)(lds + PG8_SB(b, h) + boff + n * 2048 + k * 1024); } while (0)
; #define PG8_MMA(ai, bj, At, Bt) do { __builtin_amdgcn_s_setprio(1); _Pragma("unroll") for (int m = 0; m < 4; ++m) _Pragma("unroll") for (int n = 0; n < 2; ++n) _Pragma("unroll") for (int k = 0; k < 2; ++k) \
;         acc[ai][bj][m][n] = __builtin_amdgcn_mfma_f32_16x16x32_bf16(Bt[n][k], At[m][k], acc[ai][bj][m][n], 0, 0, 0); __builtin_amdgcn_s_setprio(0); } while (0)
; #define PG8_WAIT_V(n) asm volatile("s_waitcnt vmcnt(" #n ")" ::: "memory")
; #define PG8_WAIT_L(n) asm volatile("s_waitcnt lgkmcnt(" #n ")" ::: "memory")
; #define PG8_BAR __builtin_amdgcn_s_barrier()
; #define PG8_SCHED __builtin_amdgcn_sched_barrier(0)
; template <class Epi, class Sched, bool ALIGN_EPI = false, bool SP2 = false>
; __device__ __forceinline__ void gemm_phase(PG8_LAS unsigned char* lds, const Gemm g, const Sched& S, const Epi& E) {
;     ...
;             PG8_LDB(B0, 1, 0); PG8_LDB(B1, 1, 1); PG8_SCHED; PG8_LDA(At, 1, 0); PG8_STAGE(PG8_SA(0, 1), a2 + hstepA, voffA);
;             PG8_WAIT_V(8); PG8_WAIT_L(0); PG8_BAR; PG8_MMA(0, 0, At, B0); PG8_MMA(0, 1, At, B1); PG8_BAR; PG8_SCHED;
;             PG8_LDA(At, 1, 1); PG8_STAGE(PG8_SB(1, 0), b3, voffB); PG8_STAGE(PG8_SB(1, 1), b3 + hstep, voffB); PG8_STAGE(PG8_SA(1, 0), a3, voffA);
	ds_read_b128 v[128:131], v240
	ds_read_b128 v[132:135], v240 offset:1024
	ds_read_b128 v[136:139], v240 offset:2048
	ds_read_b128 v[140:143], v240 offset:3072
	ds_read_b128 v[144:147], v241
	ds_read_b128 v[148:151], v241 offset:1024
	ds_read_b128 v[152:155], v241 offset:2048
	ds_read_b128 v[156:159], v241 offset:3072
	s_add_u32 s60, s60, 0x40000
	s_addc_u32 s61, s61, 0
	s_mov_b32 m0, s73
	v_lshl_add_u64 v[236:237], s[60:61], 0, v[192:193]
	ds_read_b128 v[160:163], v225 offset:32768
	ds_read_b128 v[164:167], v225 offset:33792
	ds_read_b128 v[170:173], v225 offset:34816
	ds_read_b128 v[198:201], v225 offset:35840
	ds_read_b128 v[202:205], v225 offset:36864
	ds_read_b128 v[206:209], v225 offset:37888
	ds_read_b128 v[210:213], v225 offset:38912
	ds_read_b128 v[214:217], v225 offset:39936
	global_load_lds_dwordx4 v[236:237], off
	v_lshl_add_u64 v[236:237], s[60:61], 0, v[190:191]
	s_mov_b32 m0, s80
	s_nop 0
	global_load_lds_dwordx4 v[236:237], off
	s_waitcnt vmcnt(8)
	s_waitcnt lgkmcnt(0)
	s_barrier
	s_setprio 1
	s_waitcnt lgkmcnt(0)
	v_mfma_f32_16x16x32_bf16 v[124:127], v[128:131], v[160:163], v[124:127]
	v_mfma_f32_16x16x32_bf16 v[120:123], v[136:139], v[160:163], v[120:123]
	v_mfma_f32_16x16x32_bf16 v[108:111], v[128:131], v[170:173], v[108:111]
	v_mfma_f32_16x16x32_bf16 v[104:107], v[136:139], v[170:173], v[104:107]
	v_mfma_f32_16x16x32_bf16 v[92:95], v[128:131], v[202:205], v[92:95]
	v_mfma_f32_16x16x32_bf16 v[88:91], v[136:139], v[202:205], v[88:91]
	v_mfma_f32_16x16x32_bf16 v[76:79], v[128:131], v[210:213], v[76:79]
	v_mfma_f32_16x16x32_bf16 v[72:75], v[136:139], v[210:213], v[72:75]
	v_mfma_f32_16x16x32_bf16 v[124:127], v[132:135], v[164:167], v[124:127]
	v_mfma_f32_16x16x32_bf16 v[120:123], v[140:143], v[164:167], v[120:123]
	v_mfma_f32_16x16x32_bf16 v[108:111], v[132:135], v[198:201], v[108:111]
	v_mfma_f32_16x16x32_bf16 v[104:107], v[140:143], v[198:201], v[104:107]
	v_mfma_f32_16x16x32_bf16 v[92:95], v[132:135], v[206:209], v[92:95]
	v_mfma_f32_16x16x32_bf16 v[88:91], v[140:143], v[206:209], v[88:91]
	v_mfma_f32_16x16x32_bf16 v[76:79], v[132:135], v[214:217], v[76:79]
	v_mfma_f32_16x16x32_bf16 v[72:75], v[140:143], v[214:217], v[72:75]
	s_setprio 0
	s_setprio 1
	v_mfma_f32_16x16x32_bf16 v[116:119], v[144:147], v[160:163], v[116:119]
	v_mfma_f32_16x16x32_bf16 v[112:115], v[152:155], v[160:163], v[112:115]
	v_mfma_f32_16x16x32_bf16 v[100:103], v[144:147], v[170:173], v[100:103]
	v_mfma_f32_16x16x32_bf16 v[96:99], v[152:155], v[170:173], v[96:99]
	v_mfma_f32_16x16x32_bf16 v[84:87], v[144:147], v[202:205], v[84:87]
	v_mfma_f32_16x16x32_bf16 v[80:83], v[152:155], v[202:205], v[80:83]
	v_mfma_f32_16x16x32_bf16 v[68:71], v[144:147], v[210:213], v[68:71]
	v_mfma_f32_16x16x32_bf16 v[64:67], v[152:155], v[210:213], v[64:67]
	v_mfma_f32_16x16x32_bf16 v[116:119], v[148:151], v[164:167], v[116:119]
	v_mfma_f32_16x16x32_bf16 v[112:115], v[156:159], v[164:167], v[112:115]
	v_mfma_f32_16x16x32_bf16 v[100:103], v[148:151], v[198:201], v[100:103]
	v_mfma_f32_16x16x32_bf16 v[96:99], v[156:159], v[198:201], v[96:99]
	v_mfma_f32_16x16x32_bf16 v[84:87], v[148:151], v[206:209], v[84:87]
	s_add_i32 s60, s74, s34
	v_mfma_f32_16x16x32_bf16 v[80:83], v[156:159], v[206:209], v[80:83]
	v_lshl_add_u64 v[178:179], v[178:179], 0, s[30:31]
	v_mfma_f32_16x16x32_bf16 v[68:71], v[148:151], v[214:217], v[68:71]
	s_mov_b32 m0, s60
	v_mfma_f32_16x16x32_bf16 v[64:67], v[156:159], v[214:217], v[64:67]
	s_setprio 0
	s_barrier
; #define PG8_STAGE(bufoff, gbase, voff) do { _Pragma("unroll") for (int _i = 0; _i < 2; ++_i) \
;         __builtin_amdgcn_global_load_lds((const unsigned*)((const char*)(gbase) + (voff)[_i]), (PG8_LAS unsigned*)(lds + (bufoff) + ldsw + _i * 8192), 16, 0, 0); } while (0)
; #define PG8_LDA(dst, b, h) do { _Pragma("unroll") for (int m = 0; m < 4; ++m) _Pragma("unroll") for (int k = 0; k < 2; ++k) dst[m][k] = *(const PG8_LAS bf16x8*)(lds + PG8_SA(b, h) + aoff + m * 2048 + k * 1024); } while (0)
; #define PG8_LDB(dst, b, h) do { _Pragma("unroll") for (int n = 0; n < 2; ++n) _Pragma("unroll") for (int k = 0; k < 2; ++k) dst[n][k] = *(const PG8_LAS bf16x8*)(lds + PG8_SB(b, h) + boff + n * 2048 + k * 1024); } while (0)
; template <class Epi, class Sched, bool ALIGN_EPI = false, bool SP2 = false>
; __device__ __forceinline__ void gemm_phase(PG8_LAS unsigned char* lds, const Gemm g, const Sched& S, const Epi& E) {
;     ...
;         for (int t = 0; t < nt; t += 2) {
;             const bool last = (t == nt - 2);
;             const char* a1 = cA + (size_t)(t + 1) * kstepA;
;             const char* a2 = last ? nA : cA + (size_t)(t + 2) * kstepA; const char* b2 = last ? nB : cB + (size_t)(t + 2) * kstep;
;             const char* a3 = a2 + kstepA; const char* b3 = b2 + kstep;
;             if (last && has_next) S.a_ready(nxt);
;             if constexpr (SP2) {
;             PG8_LDB(B0, 0, 0); PG8_LDB(B1, 0, 1); PG8_SCHED; PG8_LDA(At, 0, 0); PG8_STAGE(PG8_SA(1, 1), a1 + hstepA, voffA);
;             PG8_WAIT_V(8); PG8_WAIT_L(0); PG8_BAR; PG8_MMA(0, 0, At, B0); PG8_MMA(0, 1, At, B1); PG8_BAR; PG8_SCHED;
;             PG8_LDA(At, 0, 1); PG8_STAGE(PG8_SB(0, 0), b2, voffB); PG8_STAGE(PG8_SB(0, 1), b2 + hstep, voffB); PG8_STAGE(PG8_SA(0, 0), a2, voffA);
;             PG8_WAIT_V(8); PG8_WAIT_L(0); PG8_BAR; PG8_MMA(1, 0, At, B0); PG8_MMA(1, 1, At, B1); PG8_BAR; PG8_SCHED;
;             PG8_LDB(B0, 1, 0); PG8_LDB(B1, 1, 1); PG8_SCHED; PG8_LDA(At, 1, 0); PG8_STAGE(PG8_SA(0, 1), a2 + hstepA, voffA);
;             PG8_WAIT_V(8); PG8_WAIT_L(0); PG8_BAR; PG8_MMA(0, 0, At, B0); PG8_MMA(0, 1, At, B1); PG8_BAR; PG8_SCHED;
;             PG8_LDA(At, 1, 1); PG8_STAGE(PG8_SB(1, 0), b3, voffB); PG8_STAGE(PG8_SB(1, 1), b3 + hstep, voffB); PG8_STAGE(PG8_SA(1, 0), a3, voffA);
;             PG8_WAIT_V(8); PG8_WAIT_L(0); PG8_BAR; PG8_MMA(1, 0, At, B0); PG8_MMA(1, 1, At, B1); PG8_BAR; PG8_SCHED;
	ds_read_b128 v[160:163], v225 offset:49152
	ds_read_b128 v[164:167], v225 offset:50176
	ds_read_b128 v[170:173], v225 offset:51200
	ds_read_b128 v[198:201], v225 offset:52224
	ds_read_b128 v[202:205], v225 offset:53248
	ds_read_b128 v[206:209], v225 offset:54272
	ds_read_b128 v[210:213], v225 offset:55296
	ds_read_b128 v[214:217], v225 offset:56320
	global_load_lds_dwordx4 v[178:179], off
	s_add_i32 m0, s60, 0x2000
	s_add_u32 s58, s58, 0x40080
	v_lshl_add_u64 v[178:179], v[218:219], 0, s[30:31]
	s_addc_u32 s59, s59, 0
	s_add_i32 s60, s75, s34
	global_load_lds_dwordx4 v[178:179], off
	v_lshl_add_u64 v[178:179], s[58:59], 0, v[168:169]
	s_mov_b32 m0, s60
	s_nop 0
	global_load_lds_dwordx4 v[178:179], off
	v_lshl_add_u64 v[178:179], s[58:59], 0, v[188:189]
	s_add_i32 m0, s60, 0x2000
	s_nop 0
	global_load_lds_dwordx4 v[178:179], off
	v_lshl_add_u64 v[178:179], v[220:221], 0, s[30:31]
	s_mov_b32 m0, s84
	s_nop 0
	global_load_lds_dwordx4 v[178:179], off
	v_lshl_add_u64 v[178:179], v[234:235], 0, s[30:31]
	s_mov_b32 m0, s85
	s_nop 0
	global_load_lds_dwordx4 v[178:179], off
	s_waitcnt vmcnt(8)
	s_waitcnt lgkmcnt(0)
	s_barrier
	s_setprio 1
	s_waitcnt lgkmcnt(0)
	v_mfma_f32_16x16x32_bf16 v[60:63], v[128:131], v[160:163], v[60:63]
	v_mfma_f32_16x16x32_bf16 v[56:59], v[136:139], v[160:163], v[56:59]
	v_mfma_f32_16x16x32_bf16 v[44:47], v[128:131], v[170:173], v[44:47]
	v_mfma_f32_16x16x32_bf16 v[40:43], v[136:139], v[170:173], v[40:43]
	v_mfma_f32_16x16x32_bf16 v[28:31], v[128:131], v[202:205], v[28:31]
	v_mfma_f32_16x16x32_bf16 v[24:27], v[136:139], v[202:205], v[24:27]
	v_mfma_f32_16x16x32_bf16 v[12:15], v[128:131], v[210:213], v[12:15]
	v_mfma_f32_16x16x32_bf16 v[8:11], v[136:139], v[210:213], v[8:11]
	v_mfma_f32_16x16x32_bf16 v[60:63], v[132:135], v[164:167], v[60:63]
	v_mfma_f32_16x16x32_bf16 v[56:59], v[140:143], v[164:167], v[56:59]
	v_mfma_f32_16x16x32_bf16 v[44:47], v[132:135], v[198:201], v[44:47]
	v_mfma_f32_16x16x32_bf16 v[40:43], v[140:143], v[198:201], v[40:43]
	v_mfma_f32_16x16x32_bf16 v[28:31], v[132:135], v[206:209], v[28:31]
	v_mfma_f32_16x16x32_bf16 v[24:27], v[140:143], v[206:209], v[24:27]
	v_mfma_f32_16x16x32_bf16 v[12:15], v[132:135], v[214:217], v[12:15]
	s_add_i32 s65, s65, 2
	v_mfma_f32_16x16x32_bf16 v[8:11], v[140:143], v[214:217], v[8:11]
	s_add_u32 s53, s53, 0x100
	s_setprio 0
	s_setprio 1
	v_mfma_f32_16x16x32_bf16 v[52:55], v[144:147], v[160:163], v[52:55]
	s_addc_u32 s64, s64, 0
	v_mfma_f32_16x16x32_bf16 v[48:51], v[152:155], v[160:163], v[48:51]
	s_add_u32 s40, s40, 0x100
	v_mfma_f32_16x16x32_bf16 v[36:39], v[144:147], v[170:173], v[36:39]
	s_addc_u32 s41, s41, 0
	v_mfma_f32_16x16x32_bf16 v[32:35], v[152:155], v[170:173], v[32:35]
	s_add_u32 s58, s40, 0xfffc0080
	v_mfma_f32_16x16x32_bf16 v[20:23], v[144:147], v[202:205], v[20:23]
	s_addc_u32 s59, s41, -1
	v_mfma_f32_16x16x32_bf16 v[16:19], v[152:155], v[202:205], v[16:19]
	s_add_i32 s74, 0, 0x10000
	v_mfma_f32_16x16x32_bf16 v[4:7], v[144:147], v[210:213], v[4:7]
	s_cmp_eq_u32 s65, 12
	v_mfma_f32_16x16x32_bf16 v[0:3], v[152:155], v[210:213], v[0:3]
	s_cselect_b32 s61, s5, s59
	v_mfma_f32_16x16x32_bf16 v[52:55], v[148:151], v[164:167], v[52:55]
	s_cselect_b32 s60, s6, s58
	v_mfma_f32_16x16x32_bf16 v[48:51], v[156:159], v[164:167], v[48:51]
	s_cselect_b32 s59, s7, s64
	v_mfma_f32_16x16x32_bf16 v[36:39], v[148:151], v[198:201], v[36:39]
	s_cselect_b32 s58, s51, s53
	v_mfma_f32_16x16x32_bf16 v[32:35], v[156:159], v[198:201], v[32:35]
	s_add_i32 s91, 0, 0x14000
	v_mfma_f32_16x16x32_bf16 v[20:23], v[148:151], v[206:209], v[20:23]
	v_add_u32_e32 v242, s74, v224
	v_mfma_f32_16x16x32_bf16 v[16:19], v[156:159], v[206:209], v[16:19]
	v_add_u32_e32 v243, s91, v224
	v_mfma_f32_16x16x32_bf16 v[4:7], v[148:151], v[214:217], v[4:7]
	s_cmp_gt_u32 s65, 13
	v_mfma_f32_16x16x32_bf16 v[0:3], v[156:159], v[214:217], v[0:3]
	s_setprio 0
	s_barrier
	s_cbranch_scc0 .LBB0_733
	s_and_b64 vcc, exec, s[44:45]
	s_cbranch_vccz .LBB0_736
	s_barrier

; #define PG8_STAGE(bufoff, gbase, voff) do { _Pragma("unroll") for (int _i = 0; _i < 2; ++_i) \
;         __builtin_amdgcn_global_load_lds((const unsigned*)((const char*)(gbase) + (voff)[_i]), (PG8_LAS unsigned*)(lds + (bufoff) + ldsw + _i * 8192), 16, 0, 0); } while (0)
; #define PG8_LDA(dst, b, h) do { _Pragma("unroll") for (int m = 0; m < 4; ++m) _Pragma("unroll") for (int k = 0; k < 2; ++k) dst[m][k] = *(const PG8_LAS bf16x8*)(lds + PG8_SA(b, h) + aoff + m * 2048 + k * 1024); } while (0)
; #define PG8_LDB(dst, b, h) do { _Pragma("unroll") for (int n = 0; n < 2; ++n) _Pragma("unroll") for (int k = 0; k < 2; ++k) dst[n][k] = *(const PG8_LAS bf16x8*)(lds + PG8_SB(b, h) + boff + n * 2048 + k * 1024); } while (0)
; #define PG8_WAIT_V(n) asm volatile("s_waitcnt vmcnt(" #n ")" ::: "memory")
; #define PG8_WAIT_L(n) asm volatile("s_waitcnt lgkmcnt(" #n ")" ::: "memory")
; #define PG8_BAR __builtin_amdgcn_s_barrier()
; #define PG8_SCHED __builtin_amdgcn_sched_barrier(0)
; template <class Epi, class Sched, bool ALIGN_EPI = false, bool SP2 = false>
; __device__ __forceinline__ void gemm_phase(PG8_LAS unsigned char* lds, const Gemm g, const Sched& S, const Epi& E) {
;     ...
;         const char* nA = has_next ? (const char*)g.A + (size_t)nxt.pm * tstepA : cA; const char* nB = has_next ? (const char*)g.Bt + (size_t)nxt.pn * tstep : cB;
;         for (int t = 0; t < nt; t += 2) {
;             const bool last = (t == nt - 2);
;             const char* a1 = cA + (size_t)(t + 1) * kstepA;
;             const char* a2 = last ? nA : cA + (size_t)(t + 2) * kstepA; const char* b2 = last ? nB : cB + (size_t)(t + 2) * kstep;
;             const char* a3 = a2 + kstepA; const char* b3 = b2 + kstep;
;             if (last && has_next) S.a_ready(nxt);
;             if constexpr (SP2) {
;             PG8_LDB(B0, 0, 0); PG8_LDB(B1, 0, 1); PG8_SCHED; PG8_LDA(At, 0, 0); PG8_STAGE(PG8_SA(1, 1), a1 + hstepA, voffA);
;             PG8_WAIT_V(8); PG8_WAIT_L(0); PG8_BAR; PG8_MMA(0, 0, At, B0); PG8_MMA(0, 1, At, B1); PG8_BAR; PG8_SCHED;
;             PG8_LDA(At, 0, 1); PG8_STAGE(PG8_SB(0, 0), b2, voffB); PG8_STAGE(PG8_SB(0, 1), b2 + hstep, voffB); PG8_STAGE(PG8_SA(0, 0), a2, voffA);
;             PG8_WAIT_V(8); PG8_WAIT_L(0); PG8_BAR; PG8_MMA(1, 0, At, B0); PG8_MMA(1, 1, At, B1); PG8_BAR; PG8_SCHED;
.LBB0_835:
	s_ashr_i32 s43, s42, 31
	s_lshl_b64 s[44:45], s[42:43], 19
	s_add_u32 s44, s20, s44
	s_addc_u32 s45, s21, s45
	s_and_b64 s[46:47], s[38:39], exec
	s_cselect_b32 s43, s45, s51
	s_cselect_b32 s61, s44, s50
	s_ashr_i32 s41, s40, 31
	s_lshl_b64 s[46:47], s[40:41], 19
	s_add_u32 s46, s2, s46
	s_addc_u32 s47, s3, s47
	s_and_b64 s[52:53], s[38:39], exec
	s_cselect_b32 s41, s47, s49
	s_cselect_b32 s64, s46, s48
	s_add_u32 s65, s48, 0x100
	s_addc_u32 s69, s49, 0
	s_add_u32 s48, s50, 0x40080
	s_addc_u32 s49, s51, 0
	s_mov_b32 s73, -2
	s_add_u32 s50, s48, 0xfffc0080
	s_addc_u32 s51, s49, -1
	s_add_i32 s74, 0, 0x10000
	s_cmp_eq_u32 s73, 12
	s_cselect_b32 s53, s43, s51
	s_cselect_b32 s52, s61, s50
	s_cselect_b32 s51, s41, s69
	s_cselect_b32 s50, s64, s65
	s_add_i32 s80, 0, 0x14000
	v_add_u32_e32 v156, s74, v142
	v_add_u32_e32 v178, s80, v142
	ds_read_b128 v[144:147], v156
	ds_read_b128 v[148:151], v156 offset:1024
	ds_read_b128 v[152:155], v156 offset:2048
	ds_read_b128 v[156:159], v156 offset:3072
	ds_read_b128 v[160:163], v178
	ds_read_b128 v[164:167], v178 offset:1024
	ds_read_b128 v[170:173], v178 offset:2048
	ds_read_b128 v[188:191], v178 offset:3072
	v_lshl_add_u64 v[178:179], s[48:49], 0, v[140:141]
	s_add_i32 m0, s7, 0xc000
	ds_read_b128 v[192:195], v143
	ds_read_b128 v[196:199], v143 offset:1024
	ds_read_b128 v[200:203], v143 offset:2048
	ds_read_b128 v[204:207], v143 offset:3072
	ds_read_b128 v[208:211], v143 offset:4096
	ds_read_b128 v[212:215], v143 offset:5120
	ds_read_b128 v[216:219], v143 offset:6144
	ds_read_b128 v[220:223], v143 offset:7168
	global_load_lds_dwordx4 v[178:179], off
	v_lshl_add_u64 v[178:179], s[48:49], 0, v[138:139]
	s_add_i32 m0, s7, 0xe000
	s_nop 0
	global_load_lds_dwordx4 v[178:179], off
	s_waitcnt vmcnt(8)
	s_waitcnt lgkmcnt(0)
	s_barrier
	s_setprio 1
	s_waitcnt lgkmcnt(0)
	v_mfma_f32_16x16x32_bf16 v[124:127], v[144:147], v[192:195], 0
	v_mfma_f32_16x16x32_bf16 v[116:119], v[152:155], v[192:195], 0
	v_mfma_f32_16x16x32_bf16 v[108:111], v[144:147], v[200:203], 0
	v_mfma_f32_16x16x32_bf16 v[100:103], v[152:155], v[200:203], 0
	v_mfma_f32_16x16x32_bf16 v[92:95], v[144:147], v[208:211], 0
	v_mfma_f32_16x16x32_bf16 v[84:87], v[152:155], v[208:211], 0
	v_mfma_f32_16x16x32_bf16 v[76:79], v[144:147], v[216:219], 0
	v_mfma_f32_16x16x32_bf16 v[68:71], v[152:155], v[216:219], 0
	v_mfma_f32_16x16x32_bf16 v[124:127], v[148:151], v[196:199], v[124:127]
	v_mfma_f32_16x16x32_bf16 v[116:119], v[156:159], v[196:199], v[116:119]
	v_mfma_f32_16x16x32_bf16 v[108:111], v[148:151], v[204:207], v[108:111]
	v_mfma_f32_16x16x32_bf16 v[100:103], v[156:159], v[204:207], v[100:103]
	v_mfma_f32_16x16x32_bf16 v[92:95], v[148:151], v[212:215], v[92:95]
	v_mfma_f32_16x16x32_bf16 v[84:87], v[156:159], v[212:215], v[84:87]
	v_mfma_f32_16x16x32_bf16 v[76:79], v[148:151], v[220:223], v[76:79]
	v_mfma_f32_16x16x32_bf16 v[68:71], v[156:159], v[220:223], v[68:71]
	s_setprio 0
	s_setprio 1
	v_mfma_f32_16x16x32_bf16 v[120:123], v[160:163], v[192:195], 0
	v_mfma_f32_16x16x32_bf16 v[112:115], v[170:173], v[192:195], 0
	v_mfma_f32_16x16x32_bf16 v[104:107], v[160:163], v[200:203], 0
	v_mfma_f32_16x16x32_bf16 v[96:99], v[170:173], v[200:203], 0
	v_mfma_f32_16x16x32_bf16 v[88:91], v[160:163], v[208:211], 0
	v_mfma_f32_16x16x32_bf16 v[80:83], v[170:173], v[208:211], 0
	v_mfma_f32_16x16x32_bf16 v[72:75], v[160:163], v[216:219], 0
	v_mfma_f32_16x16x32_bf16 v[64:67], v[170:173], v[216:219], 0
	v_mfma_f32_16x16x32_bf16 v[120:123], v[164:167], v[196:199], v[120:123]
	v_mfma_f32_16x16x32_bf16 v[112:115], v[188:191], v[196:199], v[112:115]
	v_mfma_f32_16x16x32_bf16 v[104:107], v[164:167], v[204:207], v[104:107]
	v_mfma_f32_16x16x32_bf16 v[96:99], v[188:191], v[204:207], v[96:99]
	v_mfma_f32_16x16x32_bf16 v[88:91], v[164:167], v[212:215], v[88:91]
	s_add_i32 s74, s74, s6
	v_mfma_f32_16x16x32_bf16 v[80:83], v[188:191], v[212:215], v[80:83]
	v_lshl_add_u64 v[178:179], s[50:51], 0, v[132:133]
	v_mfma_f32_16x16x32_bf16 v[72:75], v[164:167], v[220:223], v[72:75]
	s_mov_b32 m0, s74
	v_mfma_f32_16x16x32_bf16 v[64:67], v[188:191], v[220:223], v[64:67]
	s_setprio 0
	s_barrier
	ds_read_b128 v[192:195], v143 offset:16384
	ds_read_b128 v[196:199], v143 offset:17408
	ds_read_b128 v[200:203], v143 offset:18432
	ds_read_b128 v[204:207], v143 offset:19456
	ds_read_b128 v[208:211], v143 offset:20480
	ds_read_b128 v[212:215], v143 offset:21504
	ds_read_b128 v[216:219], v143 offset:22528
	ds_read_b128 v[220:223], v143 offset:23552
	global_load_lds_dwordx4 v[178:179], off
	s_add_i32 m0, s74, 0x2000
	s_add_u32 s74, s50, 0x40000
	v_lshl_add_u64 v[224:225], s[50:51], 0, v[128:129]
	s_addc_u32 s75, s51, 0
	s_add_i32 s80, s80, s6
	global_load_lds_dwordx4 v[224:225], off
	v_lshl_add_u64 v[234:235], s[74:75], 0, v[132:133]
	s_mov_b32 m0, s80
	v_lshl_add_u64 v[236:237], s[52:53], 0, v[130:131]
	global_load_lds_dwordx4 v[234:235], off
	v_lshl_add_u64 v[234:235], s[74:75], 0, v[128:129]
	s_add_i32 m0, s80, 0x2000
	s_nop 0
	global_load_lds_dwordx4 v[234:235], off
	v_lshl_add_u64 v[234:235], s[52:53], 0, v[134:135]
	s_mov_b32 m0, s7
	s_nop 0
	global_load_lds_dwordx4 v[234:235], off
	s_mov_b32 m0, s34
	s_nop 0
	global_load_lds_dwordx4 v[236:237], off
	s_waitcnt vmcnt(8)
	s_waitcnt lgkmcnt(0)
	s_barrier
; #define PG8_STAGE(bufoff, gbase, voff) do { _Pragma("unroll") for (int _i = 0; _i < 2; ++_i) \
;         __builtin_amdgcn_global_load_lds((const unsigned*)((const char*)(gbase) + (voff)[_i]), (PG8_LAS unsigned*)(lds + (bufoff) + ldsw + _i * 8192), 16, 0, 0); } while (0)
; #define PG8_LDA(dst, b, h) do { _Pragma("unroll") for (int m = 0; m < 4; ++m) _Pragma("unroll") for (int k = 0; k < 2; ++k) dst[m][k] = *(const PG8_LAS bf16x8*)(lds + PG8_SA(b, h) + aoff + m * 2048 + k * 1024); } while (0)
; #define PG8_LDB(dst, b, h) do { _Pragma("unroll") for (int n = 0; n < 2; ++n) _Pragma("unroll") for (int k = 0; k < 2; ++k) dst[n][k] = *(const PG8_LAS bf16x8*)(lds + PG8_SB(b, h) + boff + n * 2048 + k * 1024); } while (0)
; #define PG8_MMA(ai, bj, At, Bt) do { __builtin_amdgcn_s_setprio(1); _Pragma("unroll") for (int m = 0; m < 4; ++m) _Pragma("unroll") for (int n = 0; n < 2; ++n) _Pragma("unroll") for (int k = 0; k < 2; ++k) \
;         acc[ai][bj][m][n] = __builtin_amdgcn_mfma_f32_16x16x32_bf16(Bt[n][k], At[m][k], acc[ai][bj][m][n], 0, 0, 0); __builtin_amdgcn_s_setprio(0); } while (0)
; #define PG8_WAIT_V(n) asm volatile("s_waitcnt vmcnt(" #n ")" ::: "memory")
; #define PG8_WAIT_L(n) asm volatile("s_waitcnt lgkmcnt(" #n ")" ::: "memory")
; #define PG8_BAR __builtin_amdgcn_s_barrier()
; #define PG8_SCHED __builtin_amdgcn_sched_barrier(0)
; template <class Epi, class Sched, bool ALIGN_EPI = false, bool SP2 = false>
; __device__ __forceinline__ void gemm_phase(PG8_LAS unsigned char* lds, const Gemm g, const Sched& S, const Epi& E) {
;     ...
;             PG8_WAIT_V(8); PG8_WAIT_L(0); PG8_BAR; PG8_MMA(0, 0, At, B0); PG8_MMA(0, 1, At, B1); PG8_BAR; PG8_SCHED;
;             PG8_LDA(At, 0, 1); PG8_STAGE(PG8_SB(0, 0), b2, voffB); PG8_STAGE(PG8_SB(0, 1), b2 + hstep, voffB); PG8_STAGE(PG8_SA(0, 0), a2, voffA);
;             PG8_WAIT_V(8); PG8_WAIT_L(0); PG8_BAR; PG8_MMA(1, 0, At, B0); PG8_MMA(1, 1, At, B1); PG8_BAR; PG8_SCHED;
;             PG8_LDB(B0, 1, 0); PG8_LDB(B1, 1, 1); PG8_SCHED; PG8_LDA(At, 1, 0); PG8_STAGE(PG8_SA(0, 1), a2 + hstepA, voffA);
;             PG8_WAIT_V(8); PG8_WAIT_L(0); PG8_BAR; PG8_MMA(0, 0, At, B0); PG8_MMA(0, 1, At, B1); PG8_BAR; PG8_SCHED;
	s_setprio 1
	s_waitcnt lgkmcnt(0)
	v_mfma_f32_16x16x32_bf16 v[60:63], v[144:147], v[192:195], 0
	v_mfma_f32_16x16x32_bf16 v[52:55], v[152:155], v[192:195], 0
	v_mfma_f32_16x16x32_bf16 v[44:47], v[144:147], v[200:203], 0
	v_mfma_f32_16x16x32_bf16 v[36:39], v[152:155], v[200:203], 0
	v_mfma_f32_16x16x32_bf16 v[28:31], v[144:147], v[208:211], 0
	v_mfma_f32_16x16x32_bf16 v[20:23], v[152:155], v[208:211], 0
	v_mfma_f32_16x16x32_bf16 v[12:15], v[144:147], v[216:219], 0
	v_mfma_f32_16x16x32_bf16 v[4:7], v[152:155], v[216:219], 0
	v_mfma_f32_16x16x32_bf16 v[60:63], v[148:151], v[196:199], v[60:63]
	v_mfma_f32_16x16x32_bf16 v[52:55], v[156:159], v[196:199], v[52:55]
	v_mfma_f32_16x16x32_bf16 v[44:47], v[148:151], v[204:207], v[44:47]
	v_mfma_f32_16x16x32_bf16 v[36:39], v[156:159], v[204:207], v[36:39]
	v_mfma_f32_16x16x32_bf16 v[28:31], v[148:151], v[212:215], v[28:31]
	v_mfma_f32_16x16x32_bf16 v[20:23], v[156:159], v[212:215], v[20:23]
	v_mfma_f32_16x16x32_bf16 v[12:15], v[148:151], v[220:223], v[12:15]
	v_mfma_f32_16x16x32_bf16 v[4:7], v[156:159], v[220:223], v[4:7]
	s_setprio 0
	s_setprio 1
	v_mfma_f32_16x16x32_bf16 v[56:59], v[160:163], v[192:195], 0
	v_mfma_f32_16x16x32_bf16 v[48:51], v[170:173], v[192:195], 0
	v_mfma_f32_16x16x32_bf16 v[40:43], v[160:163], v[200:203], 0
	v_mfma_f32_16x16x32_bf16 v[32:35], v[170:173], v[200:203], 0
	v_mfma_f32_16x16x32_bf16 v[24:27], v[160:163], v[208:211], 0
	v_mfma_f32_16x16x32_bf16 v[16:19], v[170:173], v[208:211], 0
	v_mfma_f32_16x16x32_bf16 v[8:11], v[160:163], v[216:219], 0
	v_mfma_f32_16x16x32_bf16 v[0:3], v[170:173], v[216:219], 0
	v_mfma_f32_16x16x32_bf16 v[56:59], v[164:167], v[196:199], v[56:59]
	v_mfma_f32_16x16x32_bf16 v[48:51], v[188:191], v[196:199], v[48:51]
	v_mfma_f32_16x16x32_bf16 v[40:43], v[164:167], v[204:207], v[40:43]
	v_mfma_f32_16x16x32_bf16 v[32:35], v[188:191], v[204:207], v[32:35]
	s_add_i32 s74, 0, 0x18000
	v_mfma_f32_16x16x32_bf16 v[24:27], v[164:167], v[212:215], v[24:27]
	s_add_i32 s75, 0, 0x1c000
	v_mfma_f32_16x16x32_bf16 v[16:19], v[188:191], v[212:215], v[16:19]
	v_add_u32_e32 v240, s74, v142
	v_mfma_f32_16x16x32_bf16 v[8:11], v[164:167], v[220:223], v[8:11]
	v_add_u32_e32 v241, s75, v142
	v_mfma_f32_16x16x32_bf16 v[0:3], v[188:191], v[220:223], v[0:3]
	s_setprio 0
	s_barrier
	ds_read_b128 v[144:147], v240
	ds_read_b128 v[148:151], v240 offset:1024
	ds_read_b128 v[152:155], v240 offset:2048
	ds_read_b128 v[156:159], v240 offset:3072
	ds_read_b128 v[160:163], v241
	ds_read_b128 v[164:167], v241 offset:1024
	ds_read_b128 v[170:173], v241 offset:2048
	ds_read_b128 v[188:191], v241 offset:3072
	s_add_u32 s52, s52, 0x40000
	s_addc_u32 s53, s53, 0
	s_mov_b32 m0, s35
	v_lshl_add_u64 v[238:239], s[52:53], 0, v[134:135]
	ds_read_b128 v[192:195], v143 offset:32768
	ds_read_b128 v[196:199], v143 offset:33792
	ds_read_b128 v[200:203], v143 offset:34816
	ds_read_b128 v[204:207], v143 offset:35840
	ds_read_b128 v[208:211], v143 offset:36864
	ds_read_b128 v[212:215], v143 offset:37888
	ds_read_b128 v[216:219], v143 offset:38912
	ds_read_b128 v[220:223], v143 offset:39936
	global_load_lds_dwordx4 v[238:239], off
	v_lshl_add_u64 v[238:239], s[52:53], 0, v[130:131]
	s_mov_b32 m0, s54
	s_nop 0
	global_load_lds_dwordx4 v[238:239], off
	s_waitcnt vmcnt(8)
	s_waitcnt lgkmcnt(0)
	s_barrier
	s_setprio 1
	s_waitcnt lgkmcnt(0)
	v_mfma_f32_16x16x32_bf16 v[124:127], v[144:147], v[192:195], v[124:127]
	v_mfma_f32_16x16x32_bf16 v[116:119], v[152:155], v[192:195], v[116:119]
	v_mfma_f32_16x16x32_bf16 v[108:111], v[144:147], v[200:203], v[108:111]
	v_mfma_f32_16x16x32_bf16 v[100:103], v[152:155], v[200:203], v[100:103]
	v_mfma_f32_16x16x32_bf16 v[92:95], v[144:147], v[208:211], v[92:95]
	v_mfma_f32_16x16x32_bf16 v[84:87], v[152:155], v[208:211], v[84:87]
	v_mfma_f32_16x16x32_bf16 v[76:79], v[144:147], v[216:219], v[76:79]
	v_mfma_f32_16x16x32_bf16 v[68:71], v[152:155], v[216:219], v[68:71]
	v_mfma_f32_16x16x32_bf16 v[124:127], v[148:151], v[196:199], v[124:127]
	v_mfma_f32_16x16x32_bf16 v[116:119], v[156:159], v[196:199], v[116:119]
	v_mfma_f32_16x16x32_bf16 v[108:111], v[148:151], v[204:207], v[108:111]
	v_mfma_f32_16x16x32_bf16 v[100:103], v[156:159], v[204:207], v[100:103]
	v_mfma_f32_16x16x32_bf16 v[92:95], v[148:151], v[212:215], v[92:95]
	v_mfma_f32_16x16x32_bf16 v[84:87], v[156:159], v[212:215], v[84:87]
	v_mfma_f32_16x16x32_bf16 v[76:79], v[148:151], v[220:223], v[76:79]
	v_mfma_f32_16x16x32_bf16 v[68:71], v[156:159], v[220:223], v[68:71]
	s_setprio 0
	s_setprio 1
	v_mfma_f32_16x16x32_bf16 v[120:123], v[160:163], v[192:195], v[120:123]
	v_mfma_f32_16x16x32_bf16 v[112:115], v[170:173], v[192:195], v[112:115]
	v_mfma_f32_16x16x32_bf16 v[104:107], v[160:163], v[200:203], v[104:107]
	v_mfma_f32_16x16x32_bf16 v[96:99], v[170:173], v[200:203], v[96:99]
	v_mfma_f32_16x16x32_bf16 v[88:91], v[160:163], v[208:211], v[88:91]
	v_mfma_f32_16x16x32_bf16 v[80:83], v[170:173], v[208:211], v[80:83]
	v_mfma_f32_16x16x32_bf16 v[72:75], v[160:163], v[216:219], v[72:75]
	v_mfma_f32_16x16x32_bf16 v[64:67], v[170:173], v[216:219], v[64:67]
	v_mfma_f32_16x16x32_bf16 v[120:123], v[164:167], v[196:199], v[120:123]
	v_mfma_f32_16x16x32_bf16 v[112:115], v[188:191], v[196:199], v[112:115]
	v_mfma_f32_16x16x32_bf16 v[104:107], v[164:167], v[204:207], v[104:107]
	v_mfma_f32_16x16x32_bf16 v[96:99], v[188:191], v[204:207], v[96:99]
	v_mfma_f32_16x16x32_bf16 v[88:91], v[164:167], v[212:215], v[88:91]
	s_add_i32 s52, s74, s6
	v_mfma_f32_16x16x32_bf16 v[80:83], v[188:191], v[212:215], v[80:83]
	v_lshl_add_u64 v[178:179], v[178:179], 0, s[30:31]
	v_mfma_f32_16x16x32_bf16 v[72:75], v[164:167], v[220:223], v[72:75]
	s_mov_b32 m0, s52
	v_mfma_f32_16x16x32_bf16 v[64:67], v[188:191], v[220:223], v[64:67]
	s_setprio 0
	s_barrier
; #define PG8_STAGE(bufoff, gbase, voff) do { _Pragma("unroll") for (int _i = 0; _i < 2; ++_i) \
;         __builtin_amdgcn_global_load_lds((const unsigned*)((const char*)(gbase) + (voff)[_i]), (PG8_LAS unsigned*)(lds + (bufoff) + ldsw + _i * 8192), 16, 0, 0); } while (0)
; #define PG8_LDA(dst, b, h) do { _Pragma("unroll") for (int m = 0; m < 4; ++m) _Pragma("unroll") for (int k = 0; k < 2; ++k) dst[m][k] = *(const PG8_LAS bf16x8*)(lds + PG8_SA(b, h) + aoff + m * 2048 + k * 1024); } while (0)
; #define PG8_LDB(dst, b, h) do { _Pragma("unroll") for (int n = 0; n < 2; ++n) _Pragma("unroll") for (int k = 0; k < 2; ++k) dst[n][k] = *(const PG8_LAS bf16x8*)(lds + PG8_SB(b, h) + boff + n * 2048 + k * 1024); } while (0)
; template <class Epi, class Sched, bool ALIGN_EPI = false, bool SP2 = false>
; __device__ __forceinline__ void gemm_phase(PG8_LAS unsigned char* lds, const Gemm g, const Sched& S, const Epi& E) {
;     ...
;         for (int t = 0; t < nt; t += 2) {
;             const bool last = (t == nt - 2);
;             const char* a1 = cA + (size_t)(t + 1) * kstepA;
;             const char* a2 = last ? nA : cA + (size_t)(t + 2) * kstepA; const char* b2 = last ? nB : cB + (size_t)(t + 2) * kstep;
;             const char* a3 = a2 + kstepA; const char* b3 = b2 + kstep;
;             if (last && has_next) S.a_ready(nxt);
;             if constexpr (SP2) {
;             PG8_LDB(B0, 0, 0); PG8_LDB(B1, 0, 1); PG8_SCHED; PG8_LDA(At, 0, 0); PG8_STAGE(PG8_SA(1, 1), a1 + hstepA, voffA);
;             PG8_WAIT_V(8); PG8_WAIT_L(0); PG8_BAR; PG8_MMA(0, 0, At, B0); PG8_MMA(0, 1, At, B1); PG8_BAR; PG8_SCHED;
;             PG8_LDA(At, 0, 1); PG8_STAGE(PG8_SB(0, 0), b2, voffB); PG8_STAGE(PG8_SB(0, 1), b2 + hstep, voffB); PG8_STAGE(PG8_SA(0, 0), a2, voffA);
;             PG8_WAIT_V(8); PG8_WAIT_L(0); PG8_BAR; PG8_MMA(1, 0, At, B0); PG8_MMA(1, 1, At, B1); PG8_BAR; PG8_SCHED;
;             PG8_LDB(B0, 1, 0); PG8_LDB(B1, 1, 1); PG8_SCHED; PG8_LDA(At, 1, 0); PG8_STAGE(PG8_SA(0, 1), a2 + hstepA, voffA);
;             PG8_WAIT_V(8); PG8_WAIT_L(0); PG8_BAR; PG8_MMA(0, 0, At, B0); PG8_MMA(0, 1, At, B1); PG8_BAR; PG8_SCHED;
;             PG8_LDA(At, 1, 1); PG8_STAGE(PG8_SB(1, 0), b3, voffB); PG8_STAGE(PG8_SB(1, 1), b3 + hstep, voffB); PG8_STAGE(PG8_SA(1, 0), a3, voffA);
;             PG8_WAIT_V(8); PG8_WAIT_L(0); PG8_BAR; PG8_MMA(1, 0, At, B0); PG8_MMA(1, 1, At, B1); PG8_BAR; PG8_SCHED;
	ds_read_b128 v[192:195], v143 offset:49152
	ds_read_b128 v[196:199], v143 offset:50176
	ds_read_b128 v[200:203], v143 offset:51200
	ds_read_b128 v[204:207], v143 offset:52224
	ds_read_b128 v[208:211], v143 offset:53248
	ds_read_b128 v[212:215], v143 offset:54272
	ds_read_b128 v[216:219], v143 offset:55296
	ds_read_b128 v[220:223], v143 offset:56320
	global_load_lds_dwordx4 v[178:179], off
	s_add_i32 m0, s52, 0x2000
	s_add_u32 s50, s50, 0x40080
	v_lshl_add_u64 v[178:179], v[224:225], 0, s[30:31]
	s_addc_u32 s51, s51, 0
	s_add_i32 s52, s75, s6
	global_load_lds_dwordx4 v[178:179], off
	v_lshl_add_u64 v[178:179], s[50:51], 0, v[132:133]
	s_mov_b32 m0, s52
	s_nop 0
	global_load_lds_dwordx4 v[178:179], off
	v_lshl_add_u64 v[178:179], s[50:51], 0, v[128:129]
	s_add_i32 m0, s52, 0x2000
	s_nop 0
	global_load_lds_dwordx4 v[178:179], off
	v_lshl_add_u64 v[178:179], v[234:235], 0, s[30:31]
	s_mov_b32 m0, s55
	s_nop 0
	global_load_lds_dwordx4 v[178:179], off
	v_lshl_add_u64 v[178:179], v[236:237], 0, s[30:31]
	s_mov_b32 m0, s56
	s_nop 0
	global_load_lds_dwordx4 v[178:179], off
	s_waitcnt vmcnt(8)
	s_waitcnt lgkmcnt(0)
	s_barrier
	s_setprio 1
	s_waitcnt lgkmcnt(0)
	v_mfma_f32_16x16x32_bf16 v[60:63], v[144:147], v[192:195], v[60:63]
	v_mfma_f32_16x16x32_bf16 v[52:55], v[152:155], v[192:195], v[52:55]
	v_mfma_f32_16x16x32_bf16 v[44:47], v[144:147], v[200:203], v[44:47]
	v_mfma_f32_16x16x32_bf16 v[36:39], v[152:155], v[200:203], v[36:39]
	v_mfma_f32_16x16x32_bf16 v[28:31], v[144:147], v[208:211], v[28:31]
	v_mfma_f32_16x16x32_bf16 v[20:23], v[152:155], v[208:211], v[20:23]
	v_mfma_f32_16x16x32_bf16 v[12:15], v[144:147], v[216:219], v[12:15]
	v_mfma_f32_16x16x32_bf16 v[4:7], v[152:155], v[216:219], v[4:7]
	v_mfma_f32_16x16x32_bf16 v[60:63], v[148:151], v[196:199], v[60:63]
	v_mfma_f32_16x16x32_bf16 v[52:55], v[156:159], v[196:199], v[52:55]
	v_mfma_f32_16x16x32_bf16 v[44:47], v[148:151], v[204:207], v[44:47]
	v_mfma_f32_16x16x32_bf16 v[36:39], v[156:159], v[204:207], v[36:39]
	v_mfma_f32_16x16x32_bf16 v[28:31], v[148:151], v[212:215], v[28:31]
	v_mfma_f32_16x16x32_bf16 v[20:23], v[156:159], v[212:215], v[20:23]
	v_mfma_f32_16x16x32_bf16 v[12:15], v[148:151], v[220:223], v[12:15]
	v_mfma_f32_16x16x32_bf16 v[4:7], v[156:159], v[220:223], v[4:7]
	s_add_i32 s73, s73, 2
	s_setprio 0
	s_setprio 1
	v_mfma_f32_16x16x32_bf16 v[56:59], v[160:163], v[192:195], v[56:59]
	s_add_u32 s65, s65, 0x100
	v_mfma_f32_16x16x32_bf16 v[48:51], v[170:173], v[192:195], v[48:51]
	s_addc_u32 s69, s69, 0
	v_mfma_f32_16x16x32_bf16 v[40:43], v[160:163], v[200:203], v[40:43]
	s_add_u32 s48, s48, 0x100
	v_mfma_f32_16x16x32_bf16 v[32:35], v[170:173], v[200:203], v[32:35]
	s_addc_u32 s49, s49, 0
	v_mfma_f32_16x16x32_bf16 v[24:27], v[160:163], v[208:211], v[24:27]
	s_add_u32 s50, s48, 0xfffc0080
	v_mfma_f32_16x16x32_bf16 v[16:19], v[170:173], v[208:211], v[16:19]
	s_addc_u32 s51, s49, -1
	v_mfma_f32_16x16x32_bf16 v[8:11], v[160:163], v[216:219], v[8:11]
	s_add_i32 s74, 0, 0x10000
	v_mfma_f32_16x16x32_bf16 v[0:3], v[170:173], v[216:219], v[0:3]
	s_cmp_eq_u32 s73, 12
	v_mfma_f32_16x16x32_bf16 v[56:59], v[164:167], v[196:199], v[56:59]
	s_cselect_b32 s53, s43, s51
	v_mfma_f32_16x16x32_bf16 v[48:51], v[188:191], v[196:199], v[48:51]
	s_cselect_b32 s52, s61, s50
	v_mfma_f32_16x16x32_bf16 v[40:43], v[164:167], v[204:207], v[40:43]
	s_cselect_b32 s51, s41, s69
	v_mfma_f32_16x16x32_bf16 v[32:35], v[188:191], v[204:207], v[32:35]
	s_cselect_b32 s50, s64, s65
	v_mfma_f32_16x16x32_bf16 v[24:27], v[164:167], v[212:215], v[24:27]
	s_add_i32 s80, 0, 0x14000
	v_mfma_f32_16x16x32_bf16 v[16:19], v[188:191], v[212:215], v[16:19]
	v_add_u32_e32 v242, s74, v142
	v_mfma_f32_16x16x32_bf16 v[8:11], v[164:167], v[220:223], v[8:11]
	v_add_u32_e32 v178, s80, v142
	v_mfma_f32_16x16x32_bf16 v[0:3], v[188:191], v[220:223], v[0:3]
	s_setprio 0
	s_barrier
.LBB0_836:
	ds_read_b128 v[144:147], v242
	ds_read_b128 v[148:151], v242 offset:1024
	ds_read_b128 v[152:155], v242 offset:2048
	ds_read_b128 v[156:159], v242 offset:3072
	ds_read_b128 v[160:163], v178
	ds_read_b128 v[164:167], v178 offset:1024
	ds_read_b128 v[170:173], v178 offset:2048
	ds_read_b128 v[188:191], v178 offset:3072
	v_lshl_add_u64 v[178:179], s[48:49], 0, v[140:141]
	s_add_i32 m0, s7, 0xc000
	ds_read_b128 v[192:195], v143
	ds_read_b128 v[196:199], v143 offset:1024
	ds_read_b128 v[200:203], v143 offset:2048
	ds_read_b128 v[204:207], v143 offset:3072
	ds_read_b128 v[208:211], v143 offset:4096
	ds_read_b128 v[212:215], v143 offset:5120
	ds_read_b128 v[216:219], v143 offset:6144
	ds_read_b128 v[220:223], v143 offset:7168
	global_load_lds_dwordx4 v[178:179], off
	v_lshl_add_u64 v[178:179], s[48:49], 0, v[138:139]
	s_add_i32 m0, s7, 0xe000
	s_nop 0
	global_load_lds_dwordx4 v[178:179], off
	s_waitcnt vmcnt(8)
	s_waitcnt lgkmcnt(0)
	s_barrier
; #define PG8_STAGE(bufoff, gbase, voff) do { _Pragma("unroll") for (int _i = 0; _i < 2; ++_i) \
;         __builtin_amdgcn_global_load_lds((const unsigned*)((const char*)(gbase) + (voff)[_i]), (PG8_LAS unsigned*)(lds + (bufoff) + ldsw + _i * 8192), 16, 0, 0); } while (0)
; #define PG8_LDA(dst, b, h) do { _Pragma("unroll") for (int m = 0; m < 4; ++m) _Pragma("unroll") for (int k = 0; k < 2; ++k) dst[m][k] = *(const PG8_LAS bf16x8*)(lds + PG8_SA(b, h) + aoff + m * 2048 + k * 1024); } while (0)
; #define PG8_LDB(dst, b, h) do { _Pragma("unroll") for (int n = 0; n < 2; ++n) _Pragma("unroll") for (int k = 0; k < 2; ++k) dst[n][k] = *(const PG8_LAS bf16x8*)(lds + PG8_SB(b, h) + boff + n * 2048 + k * 1024); } while (0)
; #define PG8_MMA(ai, bj, At, Bt) do { __builtin_amdgcn_s_setprio(1); _Pragma("unroll") for (int m = 0; m < 4; ++m) _Pragma("unroll") for (int n = 0; n < 2; ++n) _Pragma("unroll") for (int k = 0; k < 2; ++k) \
;         acc[ai][bj][m][n] = __builtin_amdgcn_mfma_f32_16x16x32_bf16(Bt[n][k], At[m][k], acc[ai][bj][m][n], 0, 0, 0); __builtin_amdgcn_s_setprio(0); } while (0)
; #define PG8_WAIT_V(n) asm volatile("s_waitcnt vmcnt(" #n ")" ::: "memory")
; #define PG8_WAIT_L(n) asm volatile("s_waitcnt lgkmcnt(" #n ")" ::: "memory")
; #define PG8_BAR __builtin_amdgcn_s_barrier()
; #define PG8_SCHED __builtin_amdgcn_sched_barrier(0)
; template <class Epi, class Sched, bool ALIGN_EPI = false, bool SP2 = false>
; __device__ __forceinline__ void gemm_phase(PG8_LAS unsigned char* lds, const Gemm g, const Sched& S, const Epi& E) {
;     ...
;             PG8_LDB(B0, 0, 0); PG8_LDB(B1, 0, 1); PG8_SCHED; PG8_LDA(At, 0, 0); PG8_STAGE(PG8_SA(1, 1), a1 + hstepA, voffA);
;             PG8_WAIT_V(8); PG8_WAIT_L(0); PG8_BAR; PG8_MMA(0, 0, At, B0); PG8_MMA(0, 1, At, B1); PG8_BAR; PG8_SCHED;
;             PG8_LDA(At, 0, 1); PG8_STAGE(PG8_SB(0, 0), b2, voffB); PG8_STAGE(PG8_SB(0, 1), b2 + hstep, voffB); PG8_STAGE(PG8_SA(0, 0), a2, voffA);
;             PG8_WAIT_V(8); PG8_WAIT_L(0); PG8_BAR; PG8_MMA(1, 0, At, B0); PG8_MMA(1, 1, At, B1); PG8_BAR; PG8_SCHED;
	s_setprio 1
	s_waitcnt lgkmcnt(0)
	v_mfma_f32_16x16x32_bf16 v[124:127], v[144:147], v[192:195], v[124:127]
	v_mfma_f32_16x16x32_bf16 v[116:119], v[152:155], v[192:195], v[116:119]
	v_mfma_f32_16x16x32_bf16 v[108:111], v[144:147], v[200:203], v[108:111]
	v_mfma_f32_16x16x32_bf16 v[100:103], v[152:155], v[200:203], v[100:103]
	v_mfma_f32_16x16x32_bf16 v[92:95], v[144:147], v[208:211], v[92:95]
	v_mfma_f32_16x16x32_bf16 v[84:87], v[152:155], v[208:211], v[84:87]
	v_mfma_f32_16x16x32_bf16 v[76:79], v[144:147], v[216:219], v[76:79]
	v_mfma_f32_16x16x32_bf16 v[68:71], v[152:155], v[216:219], v[68:71]
	v_mfma_f32_16x16x32_bf16 v[124:127], v[148:151], v[196:199], v[124:127]
	v_mfma_f32_16x16x32_bf16 v[116:119], v[156:159], v[196:199], v[116:119]
	v_mfma_f32_16x16x32_bf16 v[108:111], v[148:151], v[204:207], v[108:111]
	v_mfma_f32_16x16x32_bf16 v[100:103], v[156:159], v[204:207], v[100:103]
	v_mfma_f32_16x16x32_bf16 v[92:95], v[148:151], v[212:215], v[92:95]
	v_mfma_f32_16x16x32_bf16 v[84:87], v[156:159], v[212:215], v[84:87]
	v_mfma_f32_16x16x32_bf16 v[76:79], v[148:151], v[220:223], v[76:79]
	v_mfma_f32_16x16x32_bf16 v[68:71], v[156:159], v[220:223], v[68:71]
	s_setprio 0
	s_setprio 1
	v_mfma_f32_16x16x32_bf16 v[120:123], v[160:163], v[192:195], v[120:123]
	v_mfma_f32_16x16x32_bf16 v[112:115], v[170:173], v[192:195], v[112:115]
	v_mfma_f32_16x16x32_bf16 v[104:107], v[160:163], v[200:203], v[104:107]
	v_mfma_f32_16x16x32_bf16 v[96:99], v[170:173], v[200:203], v[96:99]
	v_mfma_f32_16x16x32_bf16 v[88:91], v[160:163], v[208:211], v[88:91]
	v_mfma_f32_16x16x32_bf16 v[80:83], v[170:173], v[208:211], v[80:83]
	v_mfma_f32_16x16x32_bf16 v[72:75], v[160:163], v[216:219], v[72:75]
	v_mfma_f32_16x16x32_bf16 v[64:67], v[170:173], v[216:219], v[64:67]
	v_mfma_f32_16x16x32_bf16 v[120:123], v[164:167], v[196:199], v[120:123]
	v_mfma_f32_16x16x32_bf16 v[112:115], v[188:191], v[196:199], v[112:115]
	v_mfma_f32_16x16x32_bf16 v[104:107], v[164:167], v[204:207], v[104:107]
	v_mfma_f32_16x16x32_bf16 v[96:99], v[188:191], v[204:207], v[96:99]
	v_mfma_f32_16x16x32_bf16 v[88:91], v[164:167], v[212:215], v[88:91]
	s_add_i32 s74, s74, s6
	v_mfma_f32_16x16x32_bf16 v[80:83], v[188:191], v[212:215], v[80:83]
	v_lshl_add_u64 v[178:179], s[50:51], 0, v[132:133]
	v_mfma_f32_16x16x32_bf16 v[72:75], v[164:167], v[220:223], v[72:75]
	s_mov_b32 m0, s74
	v_mfma_f32_16x16x32_bf16 v[64:67], v[188:191], v[220:223], v[64:67]
	s_setprio 0
	s_barrier
	ds_read_b128 v[192:195], v143 offset:16384
	ds_read_b128 v[196:199], v143 offset:17408
	ds_read_b128 v[200:203], v143 offset:18432
	ds_read_b128 v[204:207], v143 offset:19456
	ds_read_b128 v[208:211], v143 offset:20480
	ds_read_b128 v[212:215], v143 offset:21504
	ds_read_b128 v[216:219], v143 offset:22528
	ds_read_b128 v[220:223], v143 offset:23552
	global_load_lds_dwordx4 v[178:179], off
	s_add_i32 m0, s74, 0x2000
	s_add_u32 s74, s50, 0x40000
	v_lshl_add_u64 v[224:225], s[50:51], 0, v[128:129]
	s_addc_u32 s75, s51, 0
	s_add_i32 s80, s80, s6
	global_load_lds_dwordx4 v[224:225], off
	v_lshl_add_u64 v[234:235], s[74:75], 0, v[132:133]
	s_mov_b32 m0, s80
	v_lshl_add_u64 v[236:237], s[52:53], 0, v[130:131]
	global_load_lds_dwordx4 v[234:235], off
	v_lshl_add_u64 v[234:235], s[74:75], 0, v[128:129]
	s_add_i32 m0, s80, 0x2000
	s_nop 0
	global_load_lds_dwordx4 v[234:235], off
	v_lshl_add_u64 v[234:235], s[52:53], 0, v[134:135]
	s_mov_b32 m0, s7
	s_nop 0
	global_load_lds_dwordx4 v[234:235], off
	s_mov_b32 m0, s34
	s_nop 0
	global_load_lds_dwordx4 v[236:237], off
	s_waitcnt vmcnt(8)
	s_waitcnt lgkmcnt(0)
	s_barrier
	s_setprio 1
	s_waitcnt lgkmcnt(0)
	v_mfma_f32_16x16x32_bf16 v[60:63], v[144:147], v[192:195], v[60:63]
	v_mfma_f32_16x16x32_bf16 v[52:55], v[152:155], v[192:195], v[52:55]
	v_mfma_f32_16x16x32_bf16 v[44:47], v[144:147], v[200:203], v[44:47]
	v_mfma_f32_16x16x32_bf16 v[36:39], v[152:155], v[200:203], v[36:39]
	v_mfma_f32_16x16x32_bf16 v[28:31], v[144:147], v[208:211], v[28:31]
	v_mfma_f32_16x16x32_bf16 v[20:23], v[152:155], v[208:211], v[20:23]
	v_mfma_f32_16x16x32_bf16 v[12:15], v[144:147], v[216:219], v[12:15]
	v_mfma_f32_16x16x32_bf16 v[4:7], v[152:155], v[216:219], v[4:7]
	v_mfma_f32_16x16x32_bf16 v[60:63], v[148:151], v[196:199], v[60:63]
	v_mfma_f32_16x16x32_bf16 v[52:55], v[156:159], v[196:199], v[52:55]
	v_mfma_f32_16x16x32_bf16 v[44:47], v[148:151], v[204:207], v[44:47]
	v_mfma_f32_16x16x32_bf16 v[36:39], v[156:159], v[204:207], v[36:39]
	v_mfma_f32_16x16x32_bf16 v[28:31], v[148:151], v[212:215], v[28:31]
	v_mfma_f32_16x16x32_bf16 v[20:23], v[156:159], v[212:215], v[20:23]
	v_mfma_f32_16x16x32_bf16 v[12:15], v[148:151], v[220:223], v[12:15]
	v_mfma_f32_16x16x32_bf16 v[4:7], v[156:159], v[220:223], v[4:7]
	s_setprio 0
	s_setprio 1
	v_mfma_f32_16x16x32_bf16 v[56:59], v[160:163], v[192:195], v[56:59]
	v_mfma_f32_16x16x32_bf16 v[48:51], v[170:173], v[192:195], v[48:51]
	v_mfma_f32_16x16x32_bf16 v[40:43], v[160:163], v[200:203], v[40:43]
	v_mfma_f32_16x16x32_bf16 v[32:35], v[170:173], v[200:203], v[32:35]
	v_mfma_f32_16x16x32_bf16 v[24:27], v[160:163], v[208:211], v[24:27]
	v_mfma_f32_16x16x32_bf16 v[16:19], v[170:173], v[208:211], v[16:19]
	v_mfma_f32_16x16x32_bf16 v[8:11], v[160:163], v[216:219], v[8:11]
	v_mfma_f32_16x16x32_bf16 v[0:3], v[170:173], v[216:219], v[0:3]
	v_mfma_f32_16x16x32_bf16 v[56:59], v[164:167], v[196:199], v[56:59]
	v_mfma_f32_16x16x32_bf16 v[48:51], v[188:191], v[196:199], v[48:51]
	v_mfma_f32_16x16x32_bf16 v[40:43], v[164:167], v[204:207], v[40:43]
	v_mfma_f32_16x16x32_bf16 v[32:35], v[188:191], v[204:207], v[32:35]
	s_add_i32 s74, 0, 0x18000
	v_mfma_f32_16x16x32_bf16 v[24:27], v[164:167], v[212:215], v[24:27]
	s_add_i32 s75, 0, 0x1c000
	v_mfma_f32_16x16x32_bf16 v[16:19], v[188:191], v[212:215], v[16:19]
	v_add_u32_e32 v240, s74, v142
	v_mfma_f32_16x16x32_bf16 v[8:11], v[164:167], v[220:223], v[8:11]
	v_add_u32_e32 v241, s75, v142
	v_mfma_f32_16x16x32_bf16 v[0:3], v[188:191], v[220:223], v[0:3]
	s_setprio 0
	s_barrier
; #define PG8_STAGE(bufoff, gbase, voff) do { _Pragma("unroll") for (int _i = 0; _i < 2; ++_i) \
;         __builtin_amdgcn_global_load_lds((const unsigned*)((const char*)(gbase) + (voff)[_i]), (PG8_LAS unsigned*)(lds + (bufoff) + ldsw + _i * 8192), 16, 0, 0); } while (0)
; #define PG8_LDA(dst, b, h) do { _Pragma("unroll") for (int m = 0; m < 4; ++m) _Pragma("unroll") for (int k = 0; k < 2; ++k) dst[m][k] = *(const PG8_LAS bf16x8*)(lds + PG8_SA(b, h) + aoff + m * 2048 + k * 1024); } while (0)
; #define PG8_LDB(dst, b, h) do { _Pragma("unroll") for (int n = 0; n < 2; ++n) _Pragma("unroll") for (int k = 0; k < 2; ++k) dst[n][k] = *(const PG8_LAS bf16x8*)(lds + PG8_SB(b, h) + boff + n * 2048 + k * 1024); } while (0)
; #define PG8_MMA(ai, bj, At, Bt) do { __builtin_amdgcn_s_setprio(1); _Pragma("unroll") for (int m = 0; m < 4; ++m) _Pragma("unroll") for (int n = 0; n < 2; ++n) _Pragma("unroll") for (int k = 0; k < 2; ++k) \
;         acc[ai][bj][m][n] = __builtin_amdgcn_mfma_f32_16x16x32_bf16(Bt[n][k], At[m][k], acc[ai][bj][m][n], 0, 0, 0); __builtin_amdgcn_s_setprio(0); } while (0)
; #define PG8_WAIT_V(n) asm volatile("s_waitcnt vmcnt(" #n ")" ::: "memory")
; #define PG8_WAIT_L(n) asm volatile("s_waitcnt lgkmcnt(" #n ")" ::: "memory")
; #define PG8_BAR __builtin_amdgcn_s_barrier()
; #define PG8_SCHED __builtin_amdgcn_sched_barrier(0)
; template <class Epi, class Sched, bool ALIGN_EPI = false, bool SP2 = false>
; __device__ __forceinline__ void gemm_phase(PG8_LAS unsigned char* lds, const Gemm g, const Sched& S, const Epi& E) {
;     ...
;             PG8_LDB(B0, 1, 0); PG8_LDB(B1, 1, 1); PG8_SCHED; PG8_LDA(At, 1, 0); PG8_STAGE(PG8_SA(0, 1), a2 + hstepA, voffA);
;             PG8_WAIT_V(8); PG8_WAIT_L(0); PG8_BAR; PG8_MMA(0, 0, At, B0); PG8_MMA(0, 1, At, B1); PG8_BAR; PG8_SCHED;
;             PG8_LDA(At, 1, 1); PG8_STAGE(PG8_SB(1, 0), b3, voffB); PG8_STAGE(PG8_SB(1, 1), b3 + hstep, voffB); PG8_STAGE(PG8_SA(1, 0), a3, voffA);
	ds_read_b128 v[144:147], v240
	ds_read_b128 v[148:151], v240 offset:1024
	ds_read_b128 v[152:155], v240 offset:2048
	ds_read_b128 v[156:159], v240 offset:3072
	ds_read_b128 v[160:163], v241
	ds_read_b128 v[164:167], v241 offset:1024
	ds_read_b128 v[170:173], v241 offset:2048
	ds_read_b128 v[188:191], v241 offset:3072
	s_add_u32 s52, s52, 0x40000
	s_addc_u32 s53, s53, 0
	s_mov_b32 m0, s35
	v_lshl_add_u64 v[238:239], s[52:53], 0, v[134:135]
	ds_read_b128 v[192:195], v143 offset:32768
	ds_read_b128 v[196:199], v143 offset:33792
	ds_read_b128 v[200:203], v143 offset:34816
	ds_read_b128 v[204:207], v143 offset:35840
	ds_read_b128 v[208:211], v143 offset:36864
	ds_read_b128 v[212:215], v143 offset:37888
	ds_read_b128 v[216:219], v143 offset:38912
	ds_read_b128 v[220:223], v143 offset:39936
	global_load_lds_dwordx4 v[238:239], off
	v_lshl_add_u64 v[238:239], s[52:53], 0, v[130:131]
	s_mov_b32 m0, s54
	s_nop 0
	global_load_lds_dwordx4 v[238:239], off
	s_waitcnt vmcnt(8)
	s_waitcnt lgkmcnt(0)
	s_barrier
	s_setprio 1
	s_waitcnt lgkmcnt(0)
	v_mfma_f32_16x16x32_bf16 v[124:127], v[144:147], v[192:195], v[124:127]
	v_mfma_f32_16x16x32_bf16 v[116:119], v[152:155], v[192:195], v[116:119]
	v_mfma_f32_16x16x32_bf16 v[108:111], v[144:147], v[200:203], v[108:111]
	v_mfma_f32_16x16x32_bf16 v[100:103], v[152:155], v[200:203], v[100:103]
	v_mfma_f32_16x16x32_bf16 v[92:95], v[144:147], v[208:211], v[92:95]
	v_mfma_f32_16x16x32_bf16 v[84:87], v[152:155], v[208:211], v[84:87]
	v_mfma_f32_16x16x32_bf16 v[76:79], v[144:147], v[216:219], v[76:79]
	v_mfma_f32_16x16x32_bf16 v[68:71], v[152:155], v[216:219], v[68:71]
	v_mfma_f32_16x16x32_bf16 v[124:127], v[148:151], v[196:199], v[124:127]
	v_mfma_f32_16x16x32_bf16 v[116:119], v[156:159], v[196:199], v[116:119]
	v_mfma_f32_16x16x32_bf16 v[108:111], v[148:151], v[204:207], v[108:111]
	v_mfma_f32_16x16x32_bf16 v[100:103], v[156:159], v[204:207], v[100:103]
	v_mfma_f32_16x16x32_bf16 v[92:95], v[148:151], v[212:215], v[92:95]
	v_mfma_f32_16x16x32_bf16 v[84:87], v[156:159], v[212:215], v[84:87]
	v_mfma_f32_16x16x32_bf16 v[76:79], v[148:151], v[220:223], v[76:79]
	v_mfma_f32_16x16x32_bf16 v[68:71], v[156:159], v[220:223], v[68:71]
	s_setprio 0
	s_setprio 1
	v_mfma_f32_16x16x32_bf16 v[120:123], v[160:163], v[192:195], v[120:123]
	v_mfma_f32_16x16x32_bf16 v[112:115], v[170:173], v[192:195], v[112:115]
	v_mfma_f32_16x16x32_bf16 v[104:107], v[160:163], v[200:203], v[104:107]
	v_mfma_f32_16x16x32_bf16 v[96:99], v[170:173], v[200:203], v[96:99]
	v_mfma_f32_16x16x32_bf16 v[88:91], v[160:163], v[208:211], v[88:91]
	v_mfma_f32_16x16x32_bf16 v[80:83], v[170:173], v[208:211], v[80:83]
	v_mfma_f32_16x16x32_bf16 v[72:75], v[160:163], v[216:219], v[72:75]
	v_mfma_f32_16x16x32_bf16 v[64:67], v[170:173], v[216:219], v[64:67]
	v_mfma_f32_16x16x32_bf16 v[120:123], v[164:167], v[196:199], v[120:123]
	v_mfma_f32_16x16x32_bf16 v[112:115], v[188:191], v[196:199], v[112:115]
	v_mfma_f32_16x16x32_bf16 v[104:107], v[164:167], v[204:207], v[104:107]
	v_mfma_f32_16x16x32_bf16 v[96:99], v[188:191], v[204:207], v[96:99]
	v_mfma_f32_16x16x32_bf16 v[88:91], v[164:167], v[212:215], v[88:91]
	s_add_i32 s52, s74, s6
	v_mfma_f32_16x16x32_bf16 v[80:83], v[188:191], v[212:215], v[80:83]
	v_lshl_add_u64 v[178:179], v[178:179], 0, s[30:31]
	v_mfma_f32_16x16x32_bf16 v[72:75], v[164:167], v[220:223], v[72:75]
	s_mov_b32 m0, s52
	v_mfma_f32_16x16x32_bf16 v[64:67], v[188:191], v[220:223], v[64:67]
	s_setprio 0
	s_barrier
; #define PG8_STAGE(bufoff, gbase, voff) do { _Pragma("unroll") for (int _i = 0; _i < 2; ++_i) \
;         __builtin_amdgcn_global_load_lds((const unsigned*)((const char*)(gbase) + (voff)[_i]), (PG8_LAS unsigned*)(lds + (bufoff) + ldsw + _i * 8192), 16, 0, 0); } while (0)
; #define PG8_LDA(dst, b, h) do { _Pragma("unroll") for (int m = 0; m < 4; ++m) _Pragma("unroll") for (int k = 0; k < 2; ++k) dst[m][k] = *(const PG8_LAS bf16x8*)(lds + PG8_SA(b, h) + aoff + m * 2048 + k * 1024); } while (0)
; #define PG8_LDB(dst, b, h) do { _Pragma("unroll") for (int n = 0; n < 2; ++n) _Pragma("unroll") for (int k = 0; k < 2; ++k) dst[n][k] = *(const PG8_LAS bf16x8*)(lds + PG8_SB(b, h) + boff + n * 2048 + k * 1024); } while (0)
; template <class Epi, class Sched, bool ALIGN_EPI = false, bool SP2 = false>
; __device__ __forceinline__ void gemm_phase(PG8_LAS unsigned char* lds, const Gemm g, const Sched& S, const Epi& E) {
;     ...
;         for (int t = 0; t < nt; t += 2) {
;             const bool last = (t == nt - 2);
;             const char* a1 = cA + (size_t)(t + 1) * kstepA;
;             const char* a2 = last ? nA : cA + (size_t)(t + 2) * kstepA; const char* b2 = last ? nB : cB + (size_t)(t + 2) * kstep;
;             const char* a3 = a2 + kstepA; const char* b3 = b2 + kstep;
;             if (last && has_next) S.a_ready(nxt);
;             if constexpr (SP2) {
;             PG8_LDB(B0, 0, 0); PG8_LDB(B1, 0, 1); PG8_SCHED; PG8_LDA(At, 0, 0); PG8_STAGE(PG8_SA(1, 1), a1 + hstepA, voffA);
;             PG8_WAIT_V(8); PG8_WAIT_L(0); PG8_BAR; PG8_MMA(0, 0, At, B0); PG8_MMA(0, 1, At, B1); PG8_BAR; PG8_SCHED;
;             PG8_LDA(At, 0, 1); PG8_STAGE(PG8_SB(0, 0), b2, voffB); PG8_STAGE(PG8_SB(0, 1), b2 + hstep, voffB); PG8_STAGE(PG8_SA(0, 0), a2, voffA);
;             PG8_WAIT_V(8); PG8_WAIT_L(0); PG8_BAR; PG8_MMA(1, 0, At, B0); PG8_MMA(1, 1, At, B1); PG8_BAR; PG8_SCHED;
;             PG8_LDB(B0, 1, 0); PG8_LDB(B1, 1, 1); PG8_SCHED; PG8_LDA(At, 1, 0); PG8_STAGE(PG8_SA(0, 1), a2 + hstepA, voffA);
;             PG8_WAIT_V(8); PG8_WAIT_L(0); PG8_BAR; PG8_MMA(0, 0, At, B0); PG8_MMA(0, 1, At, B1); PG8_BAR; PG8_SCHED;
;             PG8_LDA(At, 1, 1); PG8_STAGE(PG8_SB(1, 0), b3, voffB); PG8_STAGE(PG8_SB(1, 1), b3 + hstep, voffB); PG8_STAGE(PG8_SA(1, 0), a3, voffA);
;             PG8_WAIT_V(8); PG8_WAIT_L(0); PG8_BAR; PG8_MMA(1, 0, At, B0); PG8_MMA(1, 1, At, B1); PG8_BAR; PG8_SCHED;
	ds_read_b128 v[192:195], v143 offset:49152
	ds_read_b128 v[196:199], v143 offset:50176
	ds_read_b128 v[200:203], v143 offset:51200
	ds_read_b128 v[204:207], v143 offset:52224
	ds_read_b128 v[208:211], v143 offset:53248
	ds_read_b128 v[212:215], v143 offset:54272
	ds_read_b128 v[216:219], v143 offset:55296
	ds_read_b128 v[220:223], v143 offset:56320
	global_load_lds_dwordx4 v[178:179], off
	s_add_i32 m0, s52, 0x2000
	s_add_u32 s50, s50, 0x40080
	v_lshl_add_u64 v[178:179], v[224:225], 0, s[30:31]
	s_addc_u32 s51, s51, 0
	s_add_i32 s52, s75, s6
	global_load_lds_dwordx4 v[178:179], off
	v_lshl_add_u64 v[178:179], s[50:51], 0, v[132:133]
	s_mov_b32 m0, s52
	s_nop 0
	global_load_lds_dwordx4 v[178:179], off
	v_lshl_add_u64 v[178:179], s[50:51], 0, v[128:129]
	s_add_i32 m0, s52, 0x2000
	s_nop 0
	global_load_lds_dwordx4 v[178:179], off
	v_lshl_add_u64 v[178:179], v[234:235], 0, s[30:31]
	s_mov_b32 m0, s55
	s_nop 0
	global_load_lds_dwordx4 v[178:179], off
	v_lshl_add_u64 v[178:179], v[236:237], 0, s[30:31]
	s_mov_b32 m0, s56
	s_nop 0
	global_load_lds_dwordx4 v[178:179], off
	s_waitcnt vmcnt(8)
	s_waitcnt lgkmcnt(0)
	s_barrier
	s_setprio 1
	s_waitcnt lgkmcnt(0)
	v_mfma_f32_16x16x32_bf16 v[60:63], v[144:147], v[192:195], v[60:63]
	v_mfma_f32_16x16x32_bf16 v[52:55], v[152:155], v[192:195], v[52:55]
	v_mfma_f32_16x16x32_bf16 v[44:47], v[144:147], v[200:203], v[44:47]
	v_mfma_f32_16x16x32_bf16 v[36:39], v[152:155], v[200:203], v[36:39]
	v_mfma_f32_16x16x32_bf16 v[28:31], v[144:147], v[208:211], v[28:31]
	v_mfma_f32_16x16x32_bf16 v[20:23], v[152:155], v[208:211], v[20:23]
	v_mfma_f32_16x16x32_bf16 v[12:15], v[144:147], v[216:219], v[12:15]
	v_mfma_f32_16x16x32_bf16 v[4:7], v[152:155], v[216:219], v[4:7]
	v_mfma_f32_16x16x32_bf16 v[60:63], v[148:151], v[196:199], v[60:63]
	v_mfma_f32_16x16x32_bf16 v[52:55], v[156:159], v[196:199], v[52:55]
	v_mfma_f32_16x16x32_bf16 v[44:47], v[148:151], v[204:207], v[44:47]
	v_mfma_f32_16x16x32_bf16 v[36:39], v[156:159], v[204:207], v[36:39]
	v_mfma_f32_16x16x32_bf16 v[28:31], v[148:151], v[212:215], v[28:31]
	v_mfma_f32_16x16x32_bf16 v[20:23], v[156:159], v[212:215], v[20:23]
	v_mfma_f32_16x16x32_bf16 v[12:15], v[148:151], v[220:223], v[12:15]
	s_add_i32 s73, s73, 2
	v_mfma_f32_16x16x32_bf16 v[4:7], v[156:159], v[220:223], v[4:7]
	s_add_u32 s65, s65, 0x100
	s_setprio 0
	s_setprio 1
	v_mfma_f32_16x16x32_bf16 v[56:59], v[160:163], v[192:195], v[56:59]
	s_addc_u32 s69, s69, 0
	v_mfma_f32_16x16x32_bf16 v[48:51], v[170:173], v[192:195], v[48:51]
	s_add_u32 s48, s48, 0x100
	v_mfma_f32_16x16x32_bf16 v[40:43], v[160:163], v[200:203], v[40:43]
	s_addc_u32 s49, s49, 0
	v_mfma_f32_16x16x32_bf16 v[32:35], v[170:173], v[200:203], v[32:35]
	s_add_u32 s50, s48, 0xfffc0080
	v_mfma_f32_16x16x32_bf16 v[24:27], v[160:163], v[208:211], v[24:27]
	s_addc_u32 s51, s49, -1
	v_mfma_f32_16x16x32_bf16 v[16:19], v[170:173], v[208:211], v[16:19]
	s_add_i32 s74, 0, 0x10000
	v_mfma_f32_16x16x32_bf16 v[8:11], v[160:163], v[216:219], v[8:11]
	s_cmp_eq_u32 s73, 12
	v_mfma_f32_16x16x32_bf16 v[0:3], v[170:173], v[216:219], v[0:3]
	s_cselect_b32 s53, s43, s51
	v_mfma_f32_16x16x32_bf16 v[56:59], v[164:167], v[196:199], v[56:59]
	s_cselect_b32 s52, s61, s50
	v_mfma_f32_16x16x32_bf16 v[48:51], v[188:191], v[196:199], v[48:51]
	s_cselect_b32 s51, s41, s69
	v_mfma_f32_16x16x32_bf16 v[40:43], v[164:167], v[204:207], v[40:43]
	s_cselect_b32 s50, s64, s65
	v_mfma_f32_16x16x32_bf16 v[32:35], v[188:191], v[204:207], v[32:35]
	s_add_i32 s80, 0, 0x14000
	v_mfma_f32_16x16x32_bf16 v[24:27], v[164:167], v[212:215], v[24:27]
	v_add_u32_e32 v242, s74, v142
	v_mfma_f32_16x16x32_bf16 v[16:19], v[188:191], v[212:215], v[16:19]
	v_add_u32_e32 v178, s80, v142
	v_mfma_f32_16x16x32_bf16 v[8:11], v[164:167], v[220:223], v[8:11]
	s_cmp_gt_u32 s73, 13
	v_mfma_f32_16x16x32_bf16 v[0:3], v[188:191], v[220:223], v[0:3]
	s_setprio 0
	s_barrier
	s_cbranch_scc0 .LBB0_836
	s_and_b64 vcc, exec, s[26:27]
	s_cbranch_vccz .LBB0_839
	s_barrier

; #define PG8_STAGE(bufoff, gbase, voff) do { _Pragma("unroll") for (int _i = 0; _i < 2; ++_i) \
;         __builtin_amdgcn_global_load_lds((const unsigned*)((const char*)(gbase) + (voff)[_i]), (PG8_LAS unsigned*)(lds + (bufoff) + ldsw + _i * 8192), 16, 0, 0); } while (0)
; #define PG8_LDA(dst, b, h) do { _Pragma("unroll") for (int m = 0; m < 4; ++m) _Pragma("unroll") for (int k = 0; k < 2; ++k) dst[m][k] = *(const PG8_LAS bf16x8*)(lds + PG8_SA(b, h) + aoff + m * 2048 + k * 1024); } while (0)
; #define PG8_LDB(dst, b, h) do { _Pragma("unroll") for (int n = 0; n < 2; ++n) _Pragma("unroll") for (int k = 0; k < 2; ++k) dst[n][k] = *(const PG8_LAS bf16x8*)(lds + PG8_SB(b, h) + boff + n * 2048 + k * 1024); } while (0)
; #define PG8_WAIT_V(n) asm volatile("s_waitcnt vmcnt(" #n ")" ::: "memory")
; #define PG8_WAIT_L(n) asm volatile("s_waitcnt lgkmcnt(" #n ")" ::: "memory")
; #define PG8_BAR __builtin_amdgcn_s_barrier()
; #define PG8_SCHED __builtin_amdgcn_sched_barrier(0)
; template <class Epi, class Sched, bool ALIGN_EPI = false, bool SP2 = false>
; __device__ __forceinline__ void gemm_phase(PG8_LAS unsigned char* lds, const Gemm g, const Sched& S, const Epi& E) {
;     ...
;         const char* nA = has_next ? (const char*)g.A + (size_t)nxt.pm * tstepA : cA; const char* nB = has_next ? (const char*)g.Bt + (size_t)nxt.pn * tstep : cB;
;         for (int t = 0; t < nt; t += 2) {
;             const bool last = (t == nt - 2);
;             const char* a1 = cA + (size_t)(t + 1) * kstepA;
;             const char* a2 = last ? nA : cA + (size_t)(t + 2) * kstepA; const char* b2 = last ? nB : cB + (size_t)(t + 2) * kstep;
;             const char* a3 = a2 + kstepA; const char* b3 = b2 + kstep;
;             if (last && has_next) S.a_ready(nxt);
;             if constexpr (SP2) {
;             PG8_LDB(B0, 0, 0); PG8_LDB(B1, 0, 1); PG8_SCHED; PG8_LDA(At, 0, 0); PG8_STAGE(PG8_SA(1, 1), a1 + hstepA, voffA);
;             PG8_WAIT_V(8); PG8_WAIT_L(0); PG8_BAR; PG8_MMA(0, 0, At, B0); PG8_MMA(0, 1, At, B1); PG8_BAR; PG8_SCHED;
;             PG8_LDA(At, 0, 1); PG8_STAGE(PG8_SB(0, 0), b2, voffB); PG8_STAGE(PG8_SB(0, 1), b2 + hstep, voffB); PG8_STAGE(PG8_SA(0, 0), a2, voffA);
;             PG8_WAIT_V(8); PG8_WAIT_L(0); PG8_BAR; PG8_MMA(1, 0, At, B0); PG8_MMA(1, 1, At, B1); PG8_BAR; PG8_SCHED;
.LBB0_912:
	s_add_u32 s5, s52, 0x100
	s_addc_u32 s6, s53, 0
	s_add_u32 s40, s54, 0xb4000
	s_addc_u32 s41, s55, 0
	s_mov_b32 s7, -2
	s_add_u32 s52, s40, 0xfff54000
	s_addc_u32 s53, s41, -1
	s_cmp_eq_u32 s7, 40
	s_cselect_b32 s56, s48, s52
	s_cselect_b32 s57, s49, s53
	s_cselect_b32 s54, s50, s5
	s_cselect_b32 s55, s51, s6
	s_add_u32 s52, s56, 0x4000
	s_addc_u32 s53, s57, 0
	s_add_i32 s64, 0, 0x10000
	s_add_i32 s74, 0, 0x14000
	v_add_u32_e32 v140, s64, v224
	v_add_u32_e32 v156, s74, v224
	ds_read_b128 v[128:131], v140
	ds_read_b128 v[132:135], v140 offset:1024
	ds_read_b128 v[136:139], v140 offset:2048
	ds_read_b128 v[140:143], v140 offset:3072
	ds_read_b128 v[144:147], v156
	ds_read_b128 v[148:151], v156 offset:1024
	ds_read_b128 v[152:155], v156 offset:2048
	ds_read_b128 v[156:159], v156 offset:3072
	v_lshl_add_u64 v[178:179], s[40:41], 0, v[196:197]
	s_add_i32 m0, s3, 0xc000
	ds_read_b128 v[160:163], v225
	ds_read_b128 v[164:167], v225 offset:1024
	ds_read_b128 v[170:173], v225 offset:2048
	ds_read_b128 v[198:201], v225 offset:3072
	ds_read_b128 v[202:205], v225 offset:4096
	ds_read_b128 v[206:209], v225 offset:5120
	ds_read_b128 v[210:213], v225 offset:6144
	ds_read_b128 v[214:217], v225 offset:7168
	global_load_lds_dwordx4 v[178:179], off
	v_lshl_add_u64 v[178:179], s[40:41], 0, v[194:195]
	s_add_i32 m0, s3, 0xe000
	s_nop 0
	global_load_lds_dwordx4 v[178:179], off
	s_waitcnt vmcnt(8)
	s_waitcnt lgkmcnt(0)
	s_barrier
	s_setprio 1
	s_waitcnt lgkmcnt(0)
	v_mfma_f32_16x16x32_bf16 v[124:127], v[128:131], v[160:163], 0
	v_mfma_f32_16x16x32_bf16 v[120:123], v[136:139], v[160:163], 0
	v_mfma_f32_16x16x32_bf16 v[108:111], v[128:131], v[170:173], 0
	v_mfma_f32_16x16x32_bf16 v[104:107], v[136:139], v[170:173], 0
	v_mfma_f32_16x16x32_bf16 v[92:95], v[128:131], v[202:205], 0
	v_mfma_f32_16x16x32_bf16 v[88:91], v[136:139], v[202:205], 0
	v_mfma_f32_16x16x32_bf16 v[76:79], v[128:131], v[210:213], 0
	v_mfma_f32_16x16x32_bf16 v[72:75], v[136:139], v[210:213], 0
	v_mfma_f32_16x16x32_bf16 v[124:127], v[132:135], v[164:167], v[124:127]
	v_mfma_f32_16x16x32_bf16 v[120:123], v[140:143], v[164:167], v[120:123]
	v_mfma_f32_16x16x32_bf16 v[108:111], v[132:135], v[198:201], v[108:111]
	v_mfma_f32_16x16x32_bf16 v[104:107], v[140:143], v[198:201], v[104:107]
	v_mfma_f32_16x16x32_bf16 v[92:95], v[132:135], v[206:209], v[92:95]
	v_mfma_f32_16x16x32_bf16 v[88:91], v[140:143], v[206:209], v[88:91]
	v_mfma_f32_16x16x32_bf16 v[76:79], v[132:135], v[214:217], v[76:79]
	v_mfma_f32_16x16x32_bf16 v[72:75], v[140:143], v[214:217], v[72:75]
	s_setprio 0
	s_setprio 1
	v_mfma_f32_16x16x32_bf16 v[116:119], v[144:147], v[160:163], 0
	v_mfma_f32_16x16x32_bf16 v[112:115], v[152:155], v[160:163], 0
	v_mfma_f32_16x16x32_bf16 v[100:103], v[144:147], v[170:173], 0
	v_mfma_f32_16x16x32_bf16 v[96:99], v[152:155], v[170:173], 0
	v_mfma_f32_16x16x32_bf16 v[84:87], v[144:147], v[202:205], 0
	v_mfma_f32_16x16x32_bf16 v[80:83], v[152:155], v[202:205], 0
	v_mfma_f32_16x16x32_bf16 v[68:71], v[144:147], v[210:213], 0
	v_mfma_f32_16x16x32_bf16 v[64:67], v[152:155], v[210:213], 0
	v_mfma_f32_16x16x32_bf16 v[116:119], v[148:151], v[164:167], v[116:119]
	v_mfma_f32_16x16x32_bf16 v[112:115], v[156:159], v[164:167], v[112:115]
	v_mfma_f32_16x16x32_bf16 v[100:103], v[148:151], v[198:201], v[100:103]
	v_mfma_f32_16x16x32_bf16 v[96:99], v[156:159], v[198:201], v[96:99]
	v_mfma_f32_16x16x32_bf16 v[84:87], v[148:151], v[206:209], v[84:87]
	s_add_i32 s64, s64, s2
	v_mfma_f32_16x16x32_bf16 v[80:83], v[156:159], v[206:209], v[80:83]
	v_lshl_add_u64 v[178:179], s[54:55], 0, v[168:169]
	v_mfma_f32_16x16x32_bf16 v[68:71], v[148:151], v[214:217], v[68:71]
	s_mov_b32 m0, s64
	v_mfma_f32_16x16x32_bf16 v[64:67], v[156:159], v[214:217], v[64:67]
	s_setprio 0
	s_barrier
	ds_read_b128 v[160:163], v225 offset:16384
	ds_read_b128 v[164:167], v225 offset:17408
	ds_read_b128 v[170:173], v225 offset:18432
	ds_read_b128 v[198:201], v225 offset:19456
	ds_read_b128 v[202:205], v225 offset:20480
	ds_read_b128 v[206:209], v225 offset:21504
	ds_read_b128 v[210:213], v225 offset:22528
	ds_read_b128 v[214:217], v225 offset:23552
	global_load_lds_dwordx4 v[178:179], off
	s_add_i32 m0, s64, 0x2000
	s_add_u32 s64, s54, 0xb0000
	v_lshl_add_u64 v[218:219], s[54:55], 0, v[188:189]
	s_addc_u32 s65, s55, 0
	s_add_i32 s74, s74, s2
	global_load_lds_dwordx4 v[218:219], off
	v_lshl_add_u64 v[220:221], s[64:65], 0, v[168:169]
	s_mov_b32 m0, s74
	s_nop 0
	global_load_lds_dwordx4 v[220:221], off
	v_lshl_add_u64 v[220:221], s[64:65], 0, v[188:189]
	s_add_i32 m0, s74, 0x2000
	s_nop 0
	global_load_lds_dwordx4 v[220:221], off
	v_lshl_add_u64 v[220:221], s[56:57], 0, v[192:193]
	s_mov_b32 m0, s3
	s_nop 0
	global_load_lds_dwordx4 v[220:221], off
	v_lshl_add_u64 v[220:221], s[56:57], 0, v[190:191]
	s_mov_b32 m0, s34
	s_nop 0
	global_load_lds_dwordx4 v[220:221], off
	s_waitcnt vmcnt(8)
	s_waitcnt lgkmcnt(0)
	s_barrier
; #define PG8_STAGE(bufoff, gbase, voff) do { _Pragma("unroll") for (int _i = 0; _i < 2; ++_i) \
;         __builtin_amdgcn_global_load_lds((const unsigned*)((const char*)(gbase) + (voff)[_i]), (PG8_LAS unsigned*)(lds + (bufoff) + ldsw + _i * 8192), 16, 0, 0); } while (0)
; #define PG8_LDA(dst, b, h) do { _Pragma("unroll") for (int m = 0; m < 4; ++m) _Pragma("unroll") for (int k = 0; k < 2; ++k) dst[m][k] = *(const PG8_LAS bf16x8*)(lds + PG8_SA(b, h) + aoff + m * 2048 + k * 1024); } while (0)
; #define PG8_LDB(dst, b, h) do { _Pragma("unroll") for (int n = 0; n < 2; ++n) _Pragma("unroll") for (int k = 0; k < 2; ++k) dst[n][k] = *(const PG8_LAS bf16x8*)(lds + PG8_SB(b, h) + boff + n * 2048 + k * 1024); } while (0)
; #define PG8_MMA(ai, bj, At, Bt) do { __builtin_amdgcn_s_setprio(1); _Pragma("unroll") for (int m = 0; m < 4; ++m) _Pragma("unroll") for (int n = 0; n < 2; ++n) _Pragma("unroll") for (int k = 0; k < 2; ++k) \
;         acc[ai][bj][m][n] = __builtin_amdgcn_mfma_f32_16x16x32_bf16(Bt[n][k], At[m][k], acc[ai][bj][m][n], 0, 0, 0); __builtin_amdgcn_s_setprio(0); } while (0)
; #define PG8_WAIT_V(n) asm volatile("s_waitcnt vmcnt(" #n ")" ::: "memory")
; #define PG8_WAIT_L(n) asm volatile("s_waitcnt lgkmcnt(" #n ")" ::: "memory")
; #define PG8_BAR __builtin_amdgcn_s_barrier()
; #define PG8_SCHED __builtin_amdgcn_sched_barrier(0)
; template <class Epi, class Sched, bool ALIGN_EPI = false, bool SP2 = false>
; __device__ __forceinline__ void gemm_phase(PG8_LAS unsigned char* lds, const Gemm g, const Sched& S, const Epi& E) {
;     ...
;             PG8_WAIT_V(8); PG8_WAIT_L(0); PG8_BAR; PG8_MMA(0, 0, At, B0); PG8_MMA(0, 1, At, B1); PG8_BAR; PG8_SCHED;
;             PG8_LDA(At, 0, 1); PG8_STAGE(PG8_SB(0, 0), b2, voffB); PG8_STAGE(PG8_SB(0, 1), b2 + hstep, voffB); PG8_STAGE(PG8_SA(0, 0), a2, voffA);
;             PG8_WAIT_V(8); PG8_WAIT_L(0); PG8_BAR; PG8_MMA(1, 0, At, B0); PG8_MMA(1, 1, At, B1); PG8_BAR; PG8_SCHED;
;             PG8_LDB(B0, 1, 0); PG8_LDB(B1, 1, 1); PG8_SCHED; PG8_LDA(At, 1, 0); PG8_STAGE(PG8_SA(0, 1), a2 + hstepA, voffA);
;             PG8_WAIT_V(8); PG8_WAIT_L(0); PG8_BAR; PG8_MMA(0, 0, At, B0); PG8_MMA(0, 1, At, B1); PG8_BAR; PG8_SCHED;
	s_setprio 1
	s_waitcnt lgkmcnt(0)
	v_mfma_f32_16x16x32_bf16 v[60:63], v[128:131], v[160:163], 0
	v_mfma_f32_16x16x32_bf16 v[56:59], v[136:139], v[160:163], 0
	v_mfma_f32_16x16x32_bf16 v[44:47], v[128:131], v[170:173], 0
	v_mfma_f32_16x16x32_bf16 v[40:43], v[136:139], v[170:173], 0
	v_mfma_f32_16x16x32_bf16 v[28:31], v[128:131], v[202:205], 0
	v_mfma_f32_16x16x32_bf16 v[24:27], v[136:139], v[202:205], 0
	v_mfma_f32_16x16x32_bf16 v[12:15], v[128:131], v[210:213], 0
	v_mfma_f32_16x16x32_bf16 v[8:11], v[136:139], v[210:213], 0
	v_mfma_f32_16x16x32_bf16 v[60:63], v[132:135], v[164:167], v[60:63]
	v_mfma_f32_16x16x32_bf16 v[56:59], v[140:143], v[164:167], v[56:59]
	v_mfma_f32_16x16x32_bf16 v[44:47], v[132:135], v[198:201], v[44:47]
	v_mfma_f32_16x16x32_bf16 v[40:43], v[140:143], v[198:201], v[40:43]
	v_mfma_f32_16x16x32_bf16 v[28:31], v[132:135], v[206:209], v[28:31]
	v_mfma_f32_16x16x32_bf16 v[24:27], v[140:143], v[206:209], v[24:27]
	v_mfma_f32_16x16x32_bf16 v[12:15], v[132:135], v[214:217], v[12:15]
	v_mfma_f32_16x16x32_bf16 v[8:11], v[140:143], v[214:217], v[8:11]
	s_setprio 0
	s_setprio 1
	v_mfma_f32_16x16x32_bf16 v[52:55], v[144:147], v[160:163], 0
	v_mfma_f32_16x16x32_bf16 v[48:51], v[152:155], v[160:163], 0
	v_mfma_f32_16x16x32_bf16 v[36:39], v[144:147], v[170:173], 0
	v_mfma_f32_16x16x32_bf16 v[32:35], v[152:155], v[170:173], 0
	v_mfma_f32_16x16x32_bf16 v[20:23], v[144:147], v[202:205], 0
	v_mfma_f32_16x16x32_bf16 v[16:19], v[152:155], v[202:205], 0
	v_mfma_f32_16x16x32_bf16 v[4:7], v[144:147], v[210:213], 0
	v_mfma_f32_16x16x32_bf16 v[0:3], v[152:155], v[210:213], 0
	v_mfma_f32_16x16x32_bf16 v[52:55], v[148:151], v[164:167], v[52:55]
	v_mfma_f32_16x16x32_bf16 v[48:51], v[156:159], v[164:167], v[48:51]
	v_mfma_f32_16x16x32_bf16 v[36:39], v[148:151], v[198:201], v[36:39]
	v_mfma_f32_16x16x32_bf16 v[32:35], v[156:159], v[198:201], v[32:35]
	s_add_i32 s64, 0, 0x18000
	v_mfma_f32_16x16x32_bf16 v[20:23], v[148:151], v[206:209], v[20:23]
	s_add_i32 s65, 0, 0x1c000
	v_mfma_f32_16x16x32_bf16 v[16:19], v[156:159], v[206:209], v[16:19]
	v_add_u32_e32 v240, s64, v224
	v_mfma_f32_16x16x32_bf16 v[4:7], v[148:151], v[214:217], v[4:7]
	v_add_u32_e32 v241, s65, v224
	v_mfma_f32_16x16x32_bf16 v[0:3], v[156:159], v[214:217], v[0:3]
	s_setprio 0
	s_barrier
	ds_read_b128 v[128:131], v240
	ds_read_b128 v[132:135], v240 offset:1024
	ds_read_b128 v[136:139], v240 offset:2048
	ds_read_b128 v[140:143], v240 offset:3072
	ds_read_b128 v[144:147], v241
	ds_read_b128 v[148:151], v241 offset:1024
	ds_read_b128 v[152:155], v241 offset:2048
	ds_read_b128 v[156:159], v241 offset:3072
	s_add_u32 s56, s56, 0xb0000
	s_addc_u32 s57, s57, 0
	s_mov_b32 m0, s35
	v_lshl_add_u64 v[220:221], s[56:57], 0, v[192:193]
	ds_read_b128 v[160:163], v225 offset:32768
	ds_read_b128 v[164:167], v225 offset:33792
	ds_read_b128 v[170:173], v225 offset:34816
	ds_read_b128 v[198:201], v225 offset:35840
	ds_read_b128 v[202:205], v225 offset:36864
	ds_read_b128 v[206:209], v225 offset:37888
	ds_read_b128 v[210:213], v225 offset:38912
	ds_read_b128 v[214:217], v225 offset:39936
	global_load_lds_dwordx4 v[220:221], off
	v_lshl_add_u64 v[220:221], s[56:57], 0, v[190:191]
	s_mov_b32 m0, s60
	s_nop 0
	global_load_lds_dwordx4 v[220:221], off
	s_waitcnt vmcnt(8)
	s_waitcnt lgkmcnt(0)
	s_barrier
	s_setprio 1
	s_waitcnt lgkmcnt(0)
	v_mfma_f32_16x16x32_bf16 v[124:127], v[128:131], v[160:163], v[124:127]
	v_mfma_f32_16x16x32_bf16 v[120:123], v[136:139], v[160:163], v[120:123]
	v_mfma_f32_16x16x32_bf16 v[108:111], v[128:131], v[170:173], v[108:111]
	v_mfma_f32_16x16x32_bf16 v[104:107], v[136:139], v[170:173], v[104:107]
	v_mfma_f32_16x16x32_bf16 v[92:95], v[128:131], v[202:205], v[92:95]
	v_mfma_f32_16x16x32_bf16 v[88:91], v[136:139], v[202:205], v[88:91]
	v_mfma_f32_16x16x32_bf16 v[76:79], v[128:131], v[210:213], v[76:79]
	v_mfma_f32_16x16x32_bf16 v[72:75], v[136:139], v[210:213], v[72:75]
	v_mfma_f32_16x16x32_bf16 v[124:127], v[132:135], v[164:167], v[124:127]
	v_mfma_f32_16x16x32_bf16 v[120:123], v[140:143], v[164:167], v[120:123]
	v_mfma_f32_16x16x32_bf16 v[108:111], v[132:135], v[198:201], v[108:111]
	v_mfma_f32_16x16x32_bf16 v[104:107], v[140:143], v[198:201], v[104:107]
	v_mfma_f32_16x16x32_bf16 v[92:95], v[132:135], v[206:209], v[92:95]
	v_mfma_f32_16x16x32_bf16 v[88:91], v[140:143], v[206:209], v[88:91]
	v_mfma_f32_16x16x32_bf16 v[76:79], v[132:135], v[214:217], v[76:79]
	v_mfma_f32_16x16x32_bf16 v[72:75], v[140:143], v[214:217], v[72:75]
	s_setprio 0
	s_setprio 1
	v_mfma_f32_16x16x32_bf16 v[116:119], v[144:147], v[160:163], v[116:119]
	v_mfma_f32_16x16x32_bf16 v[112:115], v[152:155], v[160:163], v[112:115]
	v_mfma_f32_16x16x32_bf16 v[100:103], v[144:147], v[170:173], v[100:103]
	v_mfma_f32_16x16x32_bf16 v[96:99], v[152:155], v[170:173], v[96:99]
	v_mfma_f32_16x16x32_bf16 v[84:87], v[144:147], v[202:205], v[84:87]
	v_mfma_f32_16x16x32_bf16 v[80:83], v[152:155], v[202:205], v[80:83]
	v_mfma_f32_16x16x32_bf16 v[68:71], v[144:147], v[210:213], v[68:71]
	v_mfma_f32_16x16x32_bf16 v[64:67], v[152:155], v[210:213], v[64:67]
	v_mfma_f32_16x16x32_bf16 v[116:119], v[148:151], v[164:167], v[116:119]
	v_mfma_f32_16x16x32_bf16 v[112:115], v[156:159], v[164:167], v[112:115]
	v_mfma_f32_16x16x32_bf16 v[100:103], v[148:151], v[198:201], v[100:103]
	v_mfma_f32_16x16x32_bf16 v[96:99], v[156:159], v[198:201], v[96:99]
	v_mfma_f32_16x16x32_bf16 v[84:87], v[148:151], v[206:209], v[84:87]
	s_add_i32 s56, s64, s2
	v_mfma_f32_16x16x32_bf16 v[80:83], v[156:159], v[206:209], v[80:83]
	v_lshl_add_u64 v[178:179], v[178:179], 0, s[30:31]
	v_mfma_f32_16x16x32_bf16 v[68:71], v[148:151], v[214:217], v[68:71]
	s_mov_b32 m0, s56
	v_mfma_f32_16x16x32_bf16 v[64:67], v[156:159], v[214:217], v[64:67]
	s_setprio 0
	s_barrier
; #define PG8_STAGE(bufoff, gbase, voff) do { _Pragma("unroll") for (int _i = 0; _i < 2; ++_i) \
;         __builtin_amdgcn_global_load_lds((const unsigned*)((const char*)(gbase) + (voff)[_i]), (PG8_LAS unsigned*)(lds + (bufoff) + ldsw + _i * 8192), 16, 0, 0); } while (0)
; #define PG8_LDA(dst, b, h) do { _Pragma("unroll") for (int m = 0; m < 4; ++m) _Pragma("unroll") for (int k = 0; k < 2; ++k) dst[m][k] = *(const PG8_LAS bf16x8*)(lds + PG8_SA(b, h) + aoff + m * 2048 + k * 1024); } while (0)
; #define PG8_LDB(dst, b, h) do { _Pragma("unroll") for (int n = 0; n < 2; ++n) _Pragma("unroll") for (int k = 0; k < 2; ++k) dst[n][k] = *(const PG8_LAS bf16x8*)(lds + PG8_SB(b, h) + boff + n * 2048 + k * 1024); } while (0)
; template <class Epi, class Sched, bool ALIGN_EPI = false, bool SP2 = false>
; __device__ __forceinline__ void gemm_phase(PG8_LAS unsigned char* lds, const Gemm g, const Sched& S, const Epi& E) {
;     ...
;         for (int t = 0; t < nt; t += 2) {
;             const bool last = (t == nt - 2);
;             const char* a1 = cA + (size_t)(t + 1) * kstepA;
;             const char* a2 = last ? nA : cA + (size_t)(t + 2) * kstepA; const char* b2 = last ? nB : cB + (size_t)(t + 2) * kstep;
;             const char* a3 = a2 + kstepA; const char* b3 = b2 + kstep;
;             if (last && has_next) S.a_ready(nxt);
;             if constexpr (SP2) {
;             PG8_LDB(B0, 0, 0); PG8_LDB(B1, 0, 1); PG8_SCHED; PG8_LDA(At, 0, 0); PG8_STAGE(PG8_SA(1, 1), a1 + hstepA, voffA);
;             PG8_WAIT_V(8); PG8_WAIT_L(0); PG8_BAR; PG8_MMA(0, 0, At, B0); PG8_MMA(0, 1, At, B1); PG8_BAR; PG8_SCHED;
;             PG8_LDA(At, 0, 1); PG8_STAGE(PG8_SB(0, 0), b2, voffB); PG8_STAGE(PG8_SB(0, 1), b2 + hstep, voffB); PG8_STAGE(PG8_SA(0, 0), a2, voffA);
;             PG8_WAIT_V(8); PG8_WAIT_L(0); PG8_BAR; PG8_MMA(1, 0, At, B0); PG8_MMA(1, 1, At, B1); PG8_BAR; PG8_SCHED;
;             PG8_LDB(B0, 1, 0); PG8_LDB(B1, 1, 1); PG8_SCHED; PG8_LDA(At, 1, 0); PG8_STAGE(PG8_SA(0, 1), a2 + hstepA, voffA);
;             PG8_WAIT_V(8); PG8_WAIT_L(0); PG8_BAR; PG8_MMA(0, 0, At, B0); PG8_MMA(0, 1, At, B1); PG8_BAR; PG8_SCHED;
;             PG8_LDA(At, 1, 1); PG8_STAGE(PG8_SB(1, 0), b3, voffB); PG8_STAGE(PG8_SB(1, 1), b3 + hstep, voffB); PG8_STAGE(PG8_SA(1, 0), a3, voffA);
;             PG8_WAIT_V(8); PG8_WAIT_L(0); PG8_BAR; PG8_MMA(1, 0, At, B0); PG8_MMA(1, 1, At, B1); PG8_BAR; PG8_SCHED;
	ds_read_b128 v[160:163], v225 offset:49152
	ds_read_b128 v[164:167], v225 offset:50176
	ds_read_b128 v[170:173], v225 offset:51200
	ds_read_b128 v[198:201], v225 offset:52224
	ds_read_b128 v[202:205], v225 offset:53248
	ds_read_b128 v[206:209], v225 offset:54272
	ds_read_b128 v[210:213], v225 offset:55296
	ds_read_b128 v[214:217], v225 offset:56320
	global_load_lds_dwordx4 v[178:179], off
	s_add_i32 m0, s56, 0x2000
	s_add_u32 s54, s54, 0xb0080
	v_lshl_add_u64 v[178:179], v[218:219], 0, s[30:31]
	s_addc_u32 s55, s55, 0
	s_add_i32 s56, s65, s2
	global_load_lds_dwordx4 v[178:179], off
	v_lshl_add_u64 v[178:179], s[54:55], 0, v[168:169]
	s_mov_b32 m0, s56
	s_nop 0
	global_load_lds_dwordx4 v[178:179], off
	v_lshl_add_u64 v[178:179], s[54:55], 0, v[188:189]
	s_add_i32 m0, s56, 0x2000
	s_nop 0
	global_load_lds_dwordx4 v[178:179], off
	v_lshl_add_u64 v[178:179], s[52:53], 0, v[192:193]
	s_mov_b32 m0, s69
	s_nop 0
	global_load_lds_dwordx4 v[178:179], off
	v_lshl_add_u64 v[178:179], s[52:53], 0, v[190:191]
	s_mov_b32 m0, s73
	s_nop 0
	global_load_lds_dwordx4 v[178:179], off
	s_waitcnt vmcnt(8)
	s_waitcnt lgkmcnt(0)
	s_barrier
	s_setprio 1
	s_waitcnt lgkmcnt(0)
	v_mfma_f32_16x16x32_bf16 v[60:63], v[128:131], v[160:163], v[60:63]
	v_mfma_f32_16x16x32_bf16 v[56:59], v[136:139], v[160:163], v[56:59]
	v_mfma_f32_16x16x32_bf16 v[44:47], v[128:131], v[170:173], v[44:47]
	v_mfma_f32_16x16x32_bf16 v[40:43], v[136:139], v[170:173], v[40:43]
	v_mfma_f32_16x16x32_bf16 v[28:31], v[128:131], v[202:205], v[28:31]
	v_mfma_f32_16x16x32_bf16 v[24:27], v[136:139], v[202:205], v[24:27]
	v_mfma_f32_16x16x32_bf16 v[12:15], v[128:131], v[210:213], v[12:15]
	v_mfma_f32_16x16x32_bf16 v[8:11], v[136:139], v[210:213], v[8:11]
	v_mfma_f32_16x16x32_bf16 v[60:63], v[132:135], v[164:167], v[60:63]
	v_mfma_f32_16x16x32_bf16 v[56:59], v[140:143], v[164:167], v[56:59]
	v_mfma_f32_16x16x32_bf16 v[44:47], v[132:135], v[198:201], v[44:47]
	v_mfma_f32_16x16x32_bf16 v[40:43], v[140:143], v[198:201], v[40:43]
	v_mfma_f32_16x16x32_bf16 v[28:31], v[132:135], v[206:209], v[28:31]
	v_mfma_f32_16x16x32_bf16 v[24:27], v[140:143], v[206:209], v[24:27]
	s_add_i32 s7, s7, 2
	v_mfma_f32_16x16x32_bf16 v[12:15], v[132:135], v[214:217], v[12:15]
	s_add_u32 s5, s5, 0x100
	v_mfma_f32_16x16x32_bf16 v[8:11], v[140:143], v[214:217], v[8:11]
	s_addc_u32 s6, s6, 0
	s_setprio 0
	s_setprio 1
	v_mfma_f32_16x16x32_bf16 v[52:55], v[144:147], v[160:163], v[52:55]
	s_add_u32 s40, s40, 0x8000
	v_mfma_f32_16x16x32_bf16 v[48:51], v[152:155], v[160:163], v[48:51]
	s_addc_u32 s41, s41, 0
	v_mfma_f32_16x16x32_bf16 v[36:39], v[144:147], v[170:173], v[36:39]
	s_add_u32 s52, s40, 0xfff54000
	v_mfma_f32_16x16x32_bf16 v[32:35], v[152:155], v[170:173], v[32:35]
	s_addc_u32 s53, s41, -1
	v_mfma_f32_16x16x32_bf16 v[20:23], v[144:147], v[202:205], v[20:23]
	s_cmp_eq_u32 s7, 40
	v_mfma_f32_16x16x32_bf16 v[16:19], v[152:155], v[202:205], v[16:19]
	s_cselect_b32 s56, s48, s52
	v_mfma_f32_16x16x32_bf16 v[4:7], v[144:147], v[210:213], v[4:7]
	s_cselect_b32 s57, s49, s53
	v_mfma_f32_16x16x32_bf16 v[0:3], v[152:155], v[210:213], v[0:3]
	s_cselect_b32 s54, s50, s5
	v_mfma_f32_16x16x32_bf16 v[52:55], v[148:151], v[164:167], v[52:55]
	s_cselect_b32 s55, s51, s6
	v_mfma_f32_16x16x32_bf16 v[48:51], v[156:159], v[164:167], v[48:51]
	s_add_u32 s52, s56, 0x4000
	v_mfma_f32_16x16x32_bf16 v[36:39], v[148:151], v[198:201], v[36:39]
	s_addc_u32 s53, s57, 0
	v_mfma_f32_16x16x32_bf16 v[32:35], v[156:159], v[198:201], v[32:35]
	s_add_i32 s64, 0, 0x10000
	v_mfma_f32_16x16x32_bf16 v[20:23], v[148:151], v[206:209], v[20:23]
	s_add_i32 s74, 0, 0x14000
	v_mfma_f32_16x16x32_bf16 v[16:19], v[156:159], v[206:209], v[16:19]
	v_add_u32_e32 v242, s64, v224
	v_mfma_f32_16x16x32_bf16 v[4:7], v[148:151], v[214:217], v[4:7]
	v_add_u32_e32 v243, s74, v224
	v_mfma_f32_16x16x32_bf16 v[0:3], v[156:159], v[214:217], v[0:3]
	s_setprio 0
	s_barrier
.LBB0_913:
	ds_read_b128 v[128:131], v242
	ds_read_b128 v[132:135], v242 offset:1024
	ds_read_b128 v[136:139], v242 offset:2048
	ds_read_b128 v[140:143], v242 offset:3072
	ds_read_b128 v[144:147], v243
	ds_read_b128 v[148:151], v243 offset:1024
	ds_read_b128 v[152:155], v243 offset:2048
	ds_read_b128 v[156:159], v243 offset:3072
	v_lshl_add_u64 v[178:179], s[40:41], 0, v[196:197]
	s_add_i32 m0, s3, 0xc000
	ds_read_b128 v[160:163], v225
	ds_read_b128 v[164:167], v225 offset:1024
	ds_read_b128 v[170:173], v225 offset:2048
	ds_read_b128 v[198:201], v225 offset:3072
	ds_read_b128 v[202:205], v225 offset:4096
	ds_read_b128 v[206:209], v225 offset:5120
	ds_read_b128 v[210:213], v225 offset:6144
	ds_read_b128 v[214:217], v225 offset:7168
	global_load_lds_dwordx4 v[178:179], off
	v_lshl_add_u64 v[178:179], s[40:41], 0, v[194:195]
	s_add_i32 m0, s3, 0xe000
	s_nop 0
	global_load_lds_dwordx4 v[178:179], off
	s_waitcnt vmcnt(8)
	s_waitcnt lgkmcnt(0)
	s_barrier
; #define PG8_STAGE(bufoff, gbase, voff) do { _Pragma("unroll") for (int _i = 0; _i < 2; ++_i) \
;         __builtin_amdgcn_global_load_lds((const unsigned*)((const char*)(gbase) + (voff)[_i]), (PG8_LAS unsigned*)(lds + (bufoff) + ldsw + _i * 8192), 16, 0, 0); } while (0)
; #define PG8_LDA(dst, b, h) do { _Pragma("unroll") for (int m = 0; m < 4; ++m) _Pragma("unroll") for (int k = 0; k < 2; ++k) dst[m][k] = *(const PG8_LAS bf16x8*)(lds + PG8_SA(b, h) + aoff + m * 2048 + k * 1024); } while (0)
; #define PG8_LDB(dst, b, h) do { _Pragma("unroll") for (int n = 0; n < 2; ++n) _Pragma("unroll") for (int k = 0; k < 2; ++k) dst[n][k] = *(const PG8_LAS bf16x8*)(lds + PG8_SB(b, h) + boff + n * 2048 + k * 1024); } while (0)
; #define PG8_MMA(ai, bj, At, Bt) do { __builtin_amdgcn_s_setprio(1); _Pragma("unroll") for (int m = 0; m < 4; ++m) _Pragma("unroll") for (int n = 0; n < 2; ++n) _Pragma("unroll") for (int k = 0; k < 2; ++k) \
;         acc[ai][bj][m][n] = __builtin_amdgcn_mfma_f32_16x16x32_bf16(Bt[n][k], At[m][k], acc[ai][bj][m][n], 0, 0, 0); __builtin_amdgcn_s_setprio(0); } while (0)
; #define PG8_WAIT_V(n) asm volatile("s_waitcnt vmcnt(" #n ")" ::: "memory")
; #define PG8_WAIT_L(n) asm volatile("s_waitcnt lgkmcnt(" #n ")" ::: "memory")
; #define PG8_BAR __builtin_amdgcn_s_barrier()
; #define PG8_SCHED __builtin_amdgcn_sched_barrier(0)
; template <class Epi, class Sched, bool ALIGN_EPI = false, bool SP2 = false>
; __device__ __forceinline__ void gemm_phase(PG8_LAS unsigned char* lds, const Gemm g, const Sched& S, const Epi& E) {
;     ...
;             PG8_LDB(B0, 0, 0); PG8_LDB(B1, 0, 1); PG8_SCHED; PG8_LDA(At, 0, 0); PG8_STAGE(PG8_SA(1, 1), a1 + hstepA, voffA);
;             PG8_WAIT_V(8); PG8_WAIT_L(0); PG8_BAR; PG8_MMA(0, 0, At, B0); PG8_MMA(0, 1, At, B1); PG8_BAR; PG8_SCHED;
;             PG8_LDA(At, 0, 1); PG8_STAGE(PG8_SB(0, 0), b2, voffB); PG8_STAGE(PG8_SB(0, 1), b2 + hstep, voffB); PG8_STAGE(PG8_SA(0, 0), a2, voffA);
;             PG8_WAIT_V(8); PG8_WAIT_L(0); PG8_BAR; PG8_MMA(1, 0, At, B0); PG8_MMA(1, 1, At, B1); PG8_BAR; PG8_SCHED;
	s_setprio 1
	s_waitcnt lgkmcnt(0)
	v_mfma_f32_16x16x32_bf16 v[124:127], v[128:131], v[160:163], v[124:127]
	v_mfma_f32_16x16x32_bf16 v[120:123], v[136:139], v[160:163], v[120:123]
	v_mfma_f32_16x16x32_bf16 v[108:111], v[128:131], v[170:173], v[108:111]
	v_mfma_f32_16x16x32_bf16 v[104:107], v[136:139], v[170:173], v[104:107]
	v_mfma_f32_16x16x32_bf16 v[92:95], v[128:131], v[202:205], v[92:95]
	v_mfma_f32_16x16x32_bf16 v[88:91], v[136:139], v[202:205], v[88:91]
	v_mfma_f32_16x16x32_bf16 v[76:79], v[128:131], v[210:213], v[76:79]
	v_mfma_f32_16x16x32_bf16 v[72:75], v[136:139], v[210:213], v[72:75]
	v_mfma_f32_16x16x32_bf16 v[124:127], v[132:135], v[164:167], v[124:127]
	v_mfma_f32_16x16x32_bf16 v[120:123], v[140:143], v[164:167], v[120:123]
	v_mfma_f32_16x16x32_bf16 v[108:111], v[132:135], v[198:201], v[108:111]
	v_mfma_f32_16x16x32_bf16 v[104:107], v[140:143], v[198:201], v[104:107]
	v_mfma_f32_16x16x32_bf16 v[92:95], v[132:135], v[206:209], v[92:95]
	v_mfma_f32_16x16x32_bf16 v[88:91], v[140:143], v[206:209], v[88:91]
	v_mfma_f32_16x16x32_bf16 v[76:79], v[132:135], v[214:217], v[76:79]
	v_mfma_f32_16x16x32_bf16 v[72:75], v[140:143], v[214:217], v[72:75]
	s_setprio 0
	s_setprio 1
	v_mfma_f32_16x16x32_bf16 v[116:119], v[144:147], v[160:163], v[116:119]
	v_mfma_f32_16x16x32_bf16 v[112:115], v[152:155], v[160:163], v[112:115]
	v_mfma_f32_16x16x32_bf16 v[100:103], v[144:147], v[170:173], v[100:103]
	v_mfma_f32_16x16x32_bf16 v[96:99], v[152:155], v[170:173], v[96:99]
	v_mfma_f32_16x16x32_bf16 v[84:87], v[144:147], v[202:205], v[84:87]
	v_mfma_f32_16x16x32_bf16 v[80:83], v[152:155], v[202:205], v[80:83]
	v_mfma_f32_16x16x32_bf16 v[68:71], v[144:147], v[210:213], v[68:71]
	v_mfma_f32_16x16x32_bf16 v[64:67], v[152:155], v[210:213], v[64:67]
	v_mfma_f32_16x16x32_bf16 v[116:119], v[148:151], v[164:167], v[116:119]
	v_mfma_f32_16x16x32_bf16 v[112:115], v[156:159], v[164:167], v[112:115]
	v_mfma_f32_16x16x32_bf16 v[100:103], v[148:151], v[198:201], v[100:103]
	v_mfma_f32_16x16x32_bf16 v[96:99], v[156:159], v[198:201], v[96:99]
	v_mfma_f32_16x16x32_bf16 v[84:87], v[148:151], v[206:209], v[84:87]
	s_add_i32 s64, s64, s2
	v_mfma_f32_16x16x32_bf16 v[80:83], v[156:159], v[206:209], v[80:83]
	v_lshl_add_u64 v[178:179], s[54:55], 0, v[168:169]
	v_mfma_f32_16x16x32_bf16 v[68:71], v[148:151], v[214:217], v[68:71]
	s_mov_b32 m0, s64
	v_mfma_f32_16x16x32_bf16 v[64:67], v[156:159], v[214:217], v[64:67]
	s_setprio 0
	s_barrier
	ds_read_b128 v[160:163], v225 offset:16384
	ds_read_b128 v[164:167], v225 offset:17408
	ds_read_b128 v[170:173], v225 offset:18432
	ds_read_b128 v[198:201], v225 offset:19456
	ds_read_b128 v[202:205], v225 offset:20480
	ds_read_b128 v[206:209], v225 offset:21504
	ds_read_b128 v[210:213], v225 offset:22528
	ds_read_b128 v[214:217], v225 offset:23552
	global_load_lds_dwordx4 v[178:179], off
	s_add_i32 m0, s64, 0x2000
	s_add_u32 s64, s54, 0xb0000
	v_lshl_add_u64 v[218:219], s[54:55], 0, v[188:189]
	s_addc_u32 s65, s55, 0
	s_add_i32 s74, s74, s2
	global_load_lds_dwordx4 v[218:219], off
	v_lshl_add_u64 v[220:221], s[64:65], 0, v[168:169]
	s_mov_b32 m0, s74
	s_nop 0
	global_load_lds_dwordx4 v[220:221], off
	v_lshl_add_u64 v[220:221], s[64:65], 0, v[188:189]
	s_add_i32 m0, s74, 0x2000
	s_nop 0
	global_load_lds_dwordx4 v[220:221], off
	v_lshl_add_u64 v[220:221], s[56:57], 0, v[192:193]
	s_mov_b32 m0, s3
	s_nop 0
	global_load_lds_dwordx4 v[220:221], off
	v_lshl_add_u64 v[220:221], s[56:57], 0, v[190:191]
	s_mov_b32 m0, s34
	s_nop 0
	global_load_lds_dwordx4 v[220:221], off
	s_waitcnt vmcnt(8)
	s_waitcnt lgkmcnt(0)
	s_barrier
	s_setprio 1
	s_waitcnt lgkmcnt(0)
	v_mfma_f32_16x16x32_bf16 v[60:63], v[128:131], v[160:163], v[60:63]
	v_mfma_f32_16x16x32_bf16 v[56:59], v[136:139], v[160:163], v[56:59]
	v_mfma_f32_16x16x32_bf16 v[44:47], v[128:131], v[170:173], v[44:47]
	v_mfma_f32_16x16x32_bf16 v[40:43], v[136:139], v[170:173], v[40:43]
	v_mfma_f32_16x16x32_bf16 v[28:31], v[128:131], v[202:205], v[28:31]
	v_mfma_f32_16x16x32_bf16 v[24:27], v[136:139], v[202:205], v[24:27]
	v_mfma_f32_16x16x32_bf16 v[12:15], v[128:131], v[210:213], v[12:15]
	v_mfma_f32_16x16x32_bf16 v[8:11], v[136:139], v[210:213], v[8:11]
	v_mfma_f32_16x16x32_bf16 v[60:63], v[132:135], v[164:167], v[60:63]
	v_mfma_f32_16x16x32_bf16 v[56:59], v[140:143], v[164:167], v[56:59]
	v_mfma_f32_16x16x32_bf16 v[44:47], v[132:135], v[198:201], v[44:47]
	v_mfma_f32_16x16x32_bf16 v[40:43], v[140:143], v[198:201], v[40:43]
	v_mfma_f32_16x16x32_bf16 v[28:31], v[132:135], v[206:209], v[28:31]
	v_mfma_f32_16x16x32_bf16 v[24:27], v[140:143], v[206:209], v[24:27]
	v_mfma_f32_16x16x32_bf16 v[12:15], v[132:135], v[214:217], v[12:15]
	v_mfma_f32_16x16x32_bf16 v[8:11], v[140:143], v[214:217], v[8:11]
	s_setprio 0
	s_setprio 1
	v_mfma_f32_16x16x32_bf16 v[52:55], v[144:147], v[160:163], v[52:55]
	v_mfma_f32_16x16x32_bf16 v[48:51], v[152:155], v[160:163], v[48:51]
	v_mfma_f32_16x16x32_bf16 v[36:39], v[144:147], v[170:173], v[36:39]
	v_mfma_f32_16x16x32_bf16 v[32:35], v[152:155], v[170:173], v[32:35]
	v_mfma_f32_16x16x32_bf16 v[20:23], v[144:147], v[202:205], v[20:23]
	v_mfma_f32_16x16x32_bf16 v[16:19], v[152:155], v[202:205], v[16:19]
	v_mfma_f32_16x16x32_bf16 v[4:7], v[144:147], v[210:213], v[4:7]
	v_mfma_f32_16x16x32_bf16 v[0:3], v[152:155], v[210:213], v[0:3]
	v_mfma_f32_16x16x32_bf16 v[52:55], v[148:151], v[164:167], v[52:55]
	v_mfma_f32_16x16x32_bf16 v[48:51], v[156:159], v[164:167], v[48:51]
	v_mfma_f32_16x16x32_bf16 v[36:39], v[148:151], v[198:201], v[36:39]
	v_mfma_f32_16x16x32_bf16 v[32:35], v[156:159], v[198:201], v[32:35]
	s_add_i32 s64, 0, 0x18000
	v_mfma_f32_16x16x32_bf16 v[20:23], v[148:151], v[206:209], v[20:23]
	s_add_i32 s65, 0, 0x1c000
	v_mfma_f32_16x16x32_bf16 v[16:19], v[156:159], v[206:209], v[16:19]
	v_add_u32_e32 v240, s64, v224
	v_mfma_f32_16x16x32_bf16 v[4:7], v[148:151], v[214:217], v[4:7]
	v_add_u32_e32 v241, s65, v224
	v_mfma_f32_16x16x32_bf16 v[0:3], v[156:159], v[214:217], v[0:3]
	s_setprio 0
	s_barrier
; #define PG8_STAGE(bufoff, gbase, voff) do { _Pragma("unroll") for (int _i = 0; _i < 2; ++_i) \
;         __builtin_amdgcn_global_load_lds((const unsigned*)((const char*)(gbase) + (voff)[_i]), (PG8_LAS unsigned*)(lds + (bufoff) + ldsw + _i * 8192), 16, 0, 0); } while (0)
; #define PG8_LDA(dst, b, h) do { _Pragma("unroll") for (int m = 0; m < 4; ++m) _Pragma("unroll") for (int k = 0; k < 2; ++k) dst[m][k] = *(const PG8_LAS bf16x8*)(lds + PG8_SA(b, h) + aoff + m * 2048 + k * 1024); } while (0)
; #define PG8_LDB(dst, b, h) do { _Pragma("unroll") for (int n = 0; n < 2; ++n) _Pragma("unroll") for (int k = 0; k < 2; ++k) dst[n][k] = *(const PG8_LAS bf16x8*)(lds + PG8_SB(b, h) + boff + n * 2048 + k * 1024); } while (0)
; #define PG8_MMA(ai, bj, At, Bt) do { __builtin_amdgcn_s_setprio(1); _Pragma("unroll") for (int m = 0; m < 4; ++m) _Pragma("unroll") for (int n = 0; n < 2; ++n) _Pragma("unroll") for (int k = 0; k < 2; ++k) \
;         acc[ai][bj][m][n] = __builtin_amdgcn_mfma_f32_16x16x32_bf16(Bt[n][k], At[m][k], acc[ai][bj][m][n], 0, 0, 0); __builtin_amdgcn_s_setprio(0); } while (0)
; #define PG8_WAIT_V(n) asm volatile("s_waitcnt vmcnt(" #n ")" ::: "memory")
; #define PG8_WAIT_L(n) asm volatile("s_waitcnt lgkmcnt(" #n ")" ::: "memory")
; #define PG8_BAR __builtin_amdgcn_s_barrier()
; #define PG8_SCHED __builtin_amdgcn_sched_barrier(0)
; template <class Epi, class Sched, bool ALIGN_EPI = false, bool SP2 = false>
; __device__ __forceinline__ void gemm_phase(PG8_LAS unsigned char* lds, const Gemm g, const Sched& S, const Epi& E) {
;     ...
;             PG8_LDB(B0, 1, 0); PG8_LDB(B1, 1, 1); PG8_SCHED; PG8_LDA(At, 1, 0); PG8_STAGE(PG8_SA(0, 1), a2 + hstepA, voffA);
;             PG8_WAIT_V(8); PG8_WAIT_L(0); PG8_BAR; PG8_MMA(0, 0, At, B0); PG8_MMA(0, 1, At, B1); PG8_BAR; PG8_SCHED;
;             PG8_LDA(At, 1, 1); PG8_STAGE(PG8_SB(1, 0), b3, voffB); PG8_STAGE(PG8_SB(1, 1), b3 + hstep, voffB); PG8_STAGE(PG8_SA(1, 0), a3, voffA);
	ds_read_b128 v[128:131], v240
	ds_read_b128 v[132:135], v240 offset:1024
	ds_read_b128 v[136:139], v240 offset:2048
	ds_read_b128 v[140:143], v240 offset:3072
	ds_read_b128 v[144:147], v241
	ds_read_b128 v[148:151], v241 offset:1024
	ds_read_b128 v[152:155], v241 offset:2048
	ds_read_b128 v[156:159], v241 offset:3072
	s_add_u32 s56, s56, 0xb0000
	s_addc_u32 s57, s57, 0
	s_mov_b32 m0, s35
	v_lshl_add_u64 v[220:221], s[56:57], 0, v[192:193]
	ds_read_b128 v[160:163], v225 offset:32768
	ds_read_b128 v[164:167], v225 offset:33792
	ds_read_b128 v[170:173], v225 offset:34816
	ds_read_b128 v[198:201], v225 offset:35840
	ds_read_b128 v[202:205], v225 offset:36864
	ds_read_b128 v[206:209], v225 offset:37888
	ds_read_b128 v[210:213], v225 offset:38912
	ds_read_b128 v[214:217], v225 offset:39936
	global_load_lds_dwordx4 v[220:221], off
	v_lshl_add_u64 v[220:221], s[56:57], 0, v[190:191]
	s_mov_b32 m0, s60
	s_nop 0
	global_load_lds_dwordx4 v[220:221], off
	s_waitcnt vmcnt(8)
	s_waitcnt lgkmcnt(0)
	s_barrier
	s_setprio 1
	s_waitcnt lgkmcnt(0)
	v_mfma_f32_16x16x32_bf16 v[124:127], v[128:131], v[160:163], v[124:127]
	v_mfma_f32_16x16x32_bf16 v[120:123], v[136:139], v[160:163], v[120:123]
	v_mfma_f32_16x16x32_bf16 v[108:111], v[128:131], v[170:173], v[108:111]
	v_mfma_f32_16x16x32_bf16 v[104:107], v[136:139], v[170:173], v[104:107]
	v_mfma_f32_16x16x32_bf16 v[92:95], v[128:131], v[202:205], v[92:95]
	v_mfma_f32_16x16x32_bf16 v[88:91], v[136:139], v[202:205], v[88:91]
	v_mfma_f32_16x16x32_bf16 v[76:79], v[128:131], v[210:213], v[76:79]
	v_mfma_f32_16x16x32_bf16 v[72:75], v[136:139], v[210:213], v[72:75]
	v_mfma_f32_16x16x32_bf16 v[124:127], v[132:135], v[164:167], v[124:127]
	v_mfma_f32_16x16x32_bf16 v[120:123], v[140:143], v[164:167], v[120:123]
	v_mfma_f32_16x16x32_bf16 v[108:111], v[132:135], v[198:201], v[108:111]
	v_mfma_f32_16x16x32_bf16 v[104:107], v[140:143], v[198:201], v[104:107]
	v_mfma_f32_16x16x32_bf16 v[92:95], v[132:135], v[206:209], v[92:95]
	v_mfma_f32_16x16x32_bf16 v[88:91], v[140:143], v[206:209], v[88:91]
	v_mfma_f32_16x16x32_bf16 v[76:79], v[132:135], v[214:217], v[76:79]
	v_mfma_f32_16x16x32_bf16 v[72:75], v[140:143], v[214:217], v[72:75]
	s_setprio 0
	s_setprio 1
	v_mfma_f32_16x16x32_bf16 v[116:119], v[144:147], v[160:163], v[116:119]
	v_mfma_f32_16x16x32_bf16 v[112:115], v[152:155], v[160:163], v[112:115]
	v_mfma_f32_16x16x32_bf16 v[100:103], v[144:147], v[170:173], v[100:103]
	v_mfma_f32_16x16x32_bf16 v[96:99], v[152:155], v[170:173], v[96:99]
	v_mfma_f32_16x16x32_bf16 v[84:87], v[144:147], v[202:205], v[84:87]
	v_mfma_f32_16x16x32_bf16 v[80:83], v[152:155], v[202:205], v[80:83]
	v_mfma_f32_16x16x32_bf16 v[68:71], v[144:147], v[210:213], v[68:71]
	v_mfma_f32_16x16x32_bf16 v[64:67], v[152:155], v[210:213], v[64:67]
	v_mfma_f32_16x16x32_bf16 v[116:119], v[148:151], v[164:167], v[116:119]
	v_mfma_f32_16x16x32_bf16 v[112:115], v[156:159], v[164:167], v[112:115]
	v_mfma_f32_16x16x32_bf16 v[100:103], v[148:151], v[198:201], v[100:103]
	v_mfma_f32_16x16x32_bf16 v[96:99], v[156:159], v[198:201], v[96:99]
	v_mfma_f32_16x16x32_bf16 v[84:87], v[148:151], v[206:209], v[84:87]
	s_add_i32 s56, s64, s2
	v_mfma_f32_16x16x32_bf16 v[80:83], v[156:159], v[206:209], v[80:83]
	v_lshl_add_u64 v[178:179], v[178:179], 0, s[30:31]
	v_mfma_f32_16x16x32_bf16 v[68:71], v[148:151], v[214:217], v[68:71]
	s_mov_b32 m0, s56
	v_mfma_f32_16x16x32_bf16 v[64:67], v[156:159], v[214:217], v[64:67]
	s_setprio 0
	s_barrier
; #define PG8_STAGE(bufoff, gbase, voff) do { _Pragma("unroll") for (int _i = 0; _i < 2; ++_i) \
;         __builtin_amdgcn_global_load_lds((const unsigned*)((const char*)(gbase) + (voff)[_i]), (PG8_LAS unsigned*)(lds + (bufoff) + ldsw + _i * 8192), 16, 0, 0); } while (0)
; #define PG8_LDA(dst, b, h) do { _Pragma("unroll") for (int m = 0; m < 4; ++m) _Pragma("unroll") for (int k = 0; k < 2; ++k) dst[m][k] = *(const PG8_LAS bf16x8*)(lds + PG8_SA(b, h) + aoff + m * 2048 + k * 1024); } while (0)
; #define PG8_LDB(dst, b, h) do { _Pragma("unroll") for (int n = 0; n < 2; ++n) _Pragma("unroll") for (int k = 0; k < 2; ++k) dst[n][k] = *(const PG8_LAS bf16x8*)(lds + PG8_SB(b, h) + boff + n * 2048 + k * 1024); } while (0)
; template <class Epi, class Sched, bool ALIGN_EPI = false, bool SP2 = false>
; __device__ __forceinline__ void gemm_phase(PG8_LAS unsigned char* lds, const Gemm g, const Sched& S, const Epi& E) {
;     ...
;         for (int t = 0; t < nt; t += 2) {
;             const bool last = (t == nt - 2);
;             const char* a1 = cA + (size_t)(t + 1) * kstepA;
;             const char* a2 = last ? nA : cA + (size_t)(t + 2) * kstepA; const char* b2 = last ? nB : cB + (size_t)(t + 2) * kstep;
;             const char* a3 = a2 + kstepA; const char* b3 = b2 + kstep;
;             if (last && has_next) S.a_ready(nxt);
;             if constexpr (SP2) {
;             PG8_LDB(B0, 0, 0); PG8_LDB(B1, 0, 1); PG8_SCHED; PG8_LDA(At, 0, 0); PG8_STAGE(PG8_SA(1, 1), a1 + hstepA, voffA);
;             PG8_WAIT_V(8); PG8_WAIT_L(0); PG8_BAR; PG8_MMA(0, 0, At, B0); PG8_MMA(0, 1, At, B1); PG8_BAR; PG8_SCHED;
;             PG8_LDA(At, 0, 1); PG8_STAGE(PG8_SB(0, 0), b2, voffB); PG8_STAGE(PG8_SB(0, 1), b2 + hstep, voffB); PG8_STAGE(PG8_SA(0, 0), a2, voffA);
;             PG8_WAIT_V(8); PG8_WAIT_L(0); PG8_BAR; PG8_MMA(1, 0, At, B0); PG8_MMA(1, 1, At, B1); PG8_BAR; PG8_SCHED;
;             PG8_LDB(B0, 1, 0); PG8_LDB(B1, 1, 1); PG8_SCHED; PG8_LDA(At, 1, 0); PG8_STAGE(PG8_SA(0, 1), a2 + hstepA, voffA);
;             PG8_WAIT_V(8); PG8_WAIT_L(0); PG8_BAR; PG8_MMA(0, 0, At, B0); PG8_MMA(0, 1, At, B1); PG8_BAR; PG8_SCHED;
;             PG8_LDA(At, 1, 1); PG8_STAGE(PG8_SB(1, 0), b3, voffB); PG8_STAGE(PG8_SB(1, 1), b3 + hstep, voffB); PG8_STAGE(PG8_SA(1, 0), a3, voffA);
;             PG8_WAIT_V(8); PG8_WAIT_L(0); PG8_BAR; PG8_MMA(1, 0, At, B0); PG8_MMA(1, 1, At, B1); PG8_BAR; PG8_SCHED;
	ds_read_b128 v[160:163], v225 offset:49152
	ds_read_b128 v[164:167], v225 offset:50176
	ds_read_b128 v[170:173], v225 offset:51200
	ds_read_b128 v[198:201], v225 offset:52224
	ds_read_b128 v[202:205], v225 offset:53248
	ds_read_b128 v[206:209], v225 offset:54272
	ds_read_b128 v[210:213], v225 offset:55296
	ds_read_b128 v[214:217], v225 offset:56320
	global_load_lds_dwordx4 v[178:179], off
	s_add_i32 m0, s56, 0x2000
	s_add_u32 s54, s54, 0xb0080
	v_lshl_add_u64 v[178:179], v[218:219], 0, s[30:31]
	s_addc_u32 s55, s55, 0
	s_add_i32 s56, s65, s2
	global_load_lds_dwordx4 v[178:179], off
	v_lshl_add_u64 v[178:179], s[54:55], 0, v[168:169]
	s_mov_b32 m0, s56
	s_nop 0
	global_load_lds_dwordx4 v[178:179], off
	v_lshl_add_u64 v[178:179], s[54:55], 0, v[188:189]
	s_add_i32 m0, s56, 0x2000
	s_nop 0
	global_load_lds_dwordx4 v[178:179], off
	v_lshl_add_u64 v[178:179], s[52:53], 0, v[192:193]
	s_mov_b32 m0, s69
	s_nop 0
	global_load_lds_dwordx4 v[178:179], off
	v_lshl_add_u64 v[178:179], s[52:53], 0, v[190:191]
	s_mov_b32 m0, s73
	s_nop 0
	global_load_lds_dwordx4 v[178:179], off
	s_waitcnt vmcnt(8)
	s_waitcnt lgkmcnt(0)
	s_barrier
	s_setprio 1
	s_waitcnt lgkmcnt(0)
	v_mfma_f32_16x16x32_bf16 v[60:63], v[128:131], v[160:163], v[60:63]
	v_mfma_f32_16x16x32_bf16 v[56:59], v[136:139], v[160:163], v[56:59]
	v_mfma_f32_16x16x32_bf16 v[44:47], v[128:131], v[170:173], v[44:47]
	v_mfma_f32_16x16x32_bf16 v[40:43], v[136:139], v[170:173], v[40:43]
	v_mfma_f32_16x16x32_bf16 v[28:31], v[128:131], v[202:205], v[28:31]
	v_mfma_f32_16x16x32_bf16 v[24:27], v[136:139], v[202:205], v[24:27]
	v_mfma_f32_16x16x32_bf16 v[12:15], v[128:131], v[210:213], v[12:15]
	v_mfma_f32_16x16x32_bf16 v[8:11], v[136:139], v[210:213], v[8:11]
	v_mfma_f32_16x16x32_bf16 v[60:63], v[132:135], v[164:167], v[60:63]
	v_mfma_f32_16x16x32_bf16 v[56:59], v[140:143], v[164:167], v[56:59]
	v_mfma_f32_16x16x32_bf16 v[44:47], v[132:135], v[198:201], v[44:47]
	v_mfma_f32_16x16x32_bf16 v[40:43], v[140:143], v[198:201], v[40:43]
	v_mfma_f32_16x16x32_bf16 v[28:31], v[132:135], v[206:209], v[28:31]
	s_add_i32 s7, s7, 2
	v_mfma_f32_16x16x32_bf16 v[24:27], v[140:143], v[206:209], v[24:27]
	s_add_u32 s5, s5, 0x100
	v_mfma_f32_16x16x32_bf16 v[12:15], v[132:135], v[214:217], v[12:15]
	s_addc_u32 s6, s6, 0
	v_mfma_f32_16x16x32_bf16 v[8:11], v[140:143], v[214:217], v[8:11]
	s_add_u32 s40, s40, 0x8000
	s_setprio 0
	s_setprio 1
	v_mfma_f32_16x16x32_bf16 v[52:55], v[144:147], v[160:163], v[52:55]
	s_addc_u32 s41, s41, 0
	v_mfma_f32_16x16x32_bf16 v[48:51], v[152:155], v[160:163], v[48:51]
	s_add_u32 s52, s40, 0xfff54000
	v_mfma_f32_16x16x32_bf16 v[36:39], v[144:147], v[170:173], v[36:39]
	s_addc_u32 s53, s41, -1
	v_mfma_f32_16x16x32_bf16 v[32:35], v[152:155], v[170:173], v[32:35]
	s_cmp_eq_u32 s7, 40
	v_mfma_f32_16x16x32_bf16 v[20:23], v[144:147], v[202:205], v[20:23]
	s_cselect_b32 s56, s48, s52
	v_mfma_f32_16x16x32_bf16 v[16:19], v[152:155], v[202:205], v[16:19]
	s_cselect_b32 s57, s49, s53
	v_mfma_f32_16x16x32_bf16 v[4:7], v[144:147], v[210:213], v[4:7]
	s_cselect_b32 s54, s50, s5
	v_mfma_f32_16x16x32_bf16 v[0:3], v[152:155], v[210:213], v[0:3]
	s_cselect_b32 s55, s51, s6
	v_mfma_f32_16x16x32_bf16 v[52:55], v[148:151], v[164:167], v[52:55]
	s_add_u32 s52, s56, 0x4000
	v_mfma_f32_16x16x32_bf16 v[48:51], v[156:159], v[164:167], v[48:51]
	s_addc_u32 s53, s57, 0
	v_mfma_f32_16x16x32_bf16 v[36:39], v[148:151], v[198:201], v[36:39]
	s_add_i32 s64, 0, 0x10000
	v_mfma_f32_16x16x32_bf16 v[32:35], v[156:159], v[198:201], v[32:35]
	s_add_i32 s74, 0, 0x14000
	v_mfma_f32_16x16x32_bf16 v[20:23], v[148:151], v[206:209], v[20:23]
	v_add_u32_e32 v242, s64, v224
	v_mfma_f32_16x16x32_bf16 v[16:19], v[156:159], v[206:209], v[16:19]
	v_add_u32_e32 v243, s74, v224
	v_mfma_f32_16x16x32_bf16 v[4:7], v[148:151], v[214:217], v[4:7]
	s_cmp_gt_u32 s7, 41
	v_mfma_f32_16x16x32_bf16 v[0:3], v[156:159], v[214:217], v[0:3]
	s_setprio 0
	s_barrier
	s_cbranch_scc0 .LBB0_913
	s_and_b64 vcc, exec, s[42:43]
	s_cbranch_vccz .LBB0_916
	s_barrier

; #define PG8_STAGE(bufoff, gbase, voff) do { _Pragma("unroll") for (int _i = 0; _i < 2; ++_i) \
;         __builtin_amdgcn_global_load_lds((const unsigned*)((const char*)(gbase) + (voff)[_i]), (PG8_LAS unsigned*)(lds + (bufoff) + ldsw + _i * 8192), 16, 0, 0); } while (0)
; #define PG8_LDA(dst, b, h) do { _Pragma("unroll") for (int m = 0; m < 4; ++m) _Pragma("unroll") for (int k = 0; k < 2; ++k) dst[m][k] = *(const PG8_LAS bf16x8*)(lds + PG8_SA(b, h) + aoff + m * 2048 + k * 1024); } while (0)
; #define PG8_LDB(dst, b, h) do { _Pragma("unroll") for (int n = 0; n < 2; ++n) _Pragma("unroll") for (int k = 0; k < 2; ++k) dst[n][k] = *(const PG8_LAS bf16x8*)(lds + PG8_SB(b, h) + boff + n * 2048 + k * 1024); } while (0)
; #define PG8_WAIT_V(n) asm volatile("s_waitcnt vmcnt(" #n ")" ::: "memory")
; #define PG8_WAIT_L(n) asm volatile("s_waitcnt lgkmcnt(" #n ")" ::: "memory")
; #define PG8_BAR __builtin_amdgcn_s_barrier()
; #define PG8_SCHED __builtin_amdgcn_sched_barrier(0)
; template <class Epi, class Sched, bool ALIGN_EPI = false, bool SP2 = false>
; __device__ __forceinline__ void gemm_phase(PG8_LAS unsigned char* lds, const Gemm g, const Sched& S, const Epi& E) {
;     ...
;         const char* nA = has_next ? (const char*)g.A + (size_t)nxt.pm * tstepA : cA; const char* nB = has_next ? (const char*)g.Bt + (size_t)nxt.pn * tstep : cB;
;         for (int t = 0; t < nt; t += 2) {
;             const bool last = (t == nt - 2);
;             const char* a1 = cA + (size_t)(t + 1) * kstepA;
;             const char* a2 = last ? nA : cA + (size_t)(t + 2) * kstepA; const char* b2 = last ? nB : cB + (size_t)(t + 2) * kstep;
;             const char* a3 = a2 + kstepA; const char* b3 = b2 + kstep;
;             if (last && has_next) S.a_ready(nxt);
;             if constexpr (SP2) {
;             PG8_LDB(B0, 0, 0); PG8_LDB(B1, 0, 1); PG8_SCHED; PG8_LDA(At, 0, 0); PG8_STAGE(PG8_SA(1, 1), a1 + hstepA, voffA);
;             PG8_WAIT_V(8); PG8_WAIT_L(0); PG8_BAR; PG8_MMA(0, 0, At, B0); PG8_MMA(0, 1, At, B1); PG8_BAR; PG8_SCHED;
;             PG8_LDA(At, 0, 1); PG8_STAGE(PG8_SB(0, 0), b2, voffB); PG8_STAGE(PG8_SB(0, 1), b2 + hstep, voffB); PG8_STAGE(PG8_SA(0, 0), a2, voffA);
;             PG8_WAIT_V(8); PG8_WAIT_L(0); PG8_BAR; PG8_MMA(1, 0, At, B0); PG8_MMA(1, 1, At, B1); PG8_BAR; PG8_SCHED;
.LBB0_973:
	s_add_u32 s5, s48, 0x100
	s_addc_u32 s6, s49, 0
	s_add_u32 s38, s50, 0xb4000
	s_addc_u32 s39, s51, 0
	s_mov_b32 s7, -2
	s_add_u32 s48, s38, 0xfff54000
	s_addc_u32 s49, s39, -1
	s_cmp_eq_u32 s7, 40
	s_cselect_b32 s52, s44, s48
	s_cselect_b32 s53, s45, s49
	s_cselect_b32 s50, s46, s5
	s_cselect_b32 s51, s47, s6
	s_add_u32 s48, s52, 0x4000
	s_addc_u32 s49, s53, 0
	s_add_i32 s64, 0, 0x10000
	s_add_i32 s74, 0, 0x14000
	v_add_u32_e32 v140, s64, v236
	v_add_u32_e32 v156, s74, v236
	ds_read_b128 v[128:131], v140
	ds_read_b128 v[132:135], v140 offset:1024
	ds_read_b128 v[136:139], v140 offset:2048
	ds_read_b128 v[140:143], v140 offset:3072
	ds_read_b128 v[144:147], v156
	ds_read_b128 v[148:151], v156 offset:1024
	ds_read_b128 v[152:155], v156 offset:2048
	ds_read_b128 v[156:159], v156 offset:3072
	v_lshl_add_u64 v[178:179], s[38:39], 0, v[196:197]
	s_add_i32 m0, s3, 0xc000
	ds_read_b128 v[160:163], v237
	ds_read_b128 v[164:167], v237 offset:1024
	ds_read_b128 v[170:173], v237 offset:2048
	ds_read_b128 v[198:201], v237 offset:3072
	ds_read_b128 v[202:205], v237 offset:4096
	ds_read_b128 v[206:209], v237 offset:5120
	ds_read_b128 v[210:213], v237 offset:6144
	ds_read_b128 v[214:217], v237 offset:7168
	global_load_lds_dwordx4 v[178:179], off
	v_lshl_add_u64 v[178:179], s[38:39], 0, v[194:195]
	s_add_i32 m0, s3, 0xe000
	s_nop 0
	global_load_lds_dwordx4 v[178:179], off
	s_waitcnt vmcnt(8)
	s_waitcnt lgkmcnt(0)
	s_barrier
	s_setprio 1
	s_waitcnt lgkmcnt(0)
	v_mfma_f32_16x16x32_bf16 v[124:127], v[128:131], v[160:163], 0
	v_mfma_f32_16x16x32_bf16 v[120:123], v[136:139], v[160:163], 0
	v_mfma_f32_16x16x32_bf16 v[108:111], v[128:131], v[170:173], 0
	v_mfma_f32_16x16x32_bf16 v[104:107], v[136:139], v[170:173], 0
	v_mfma_f32_16x16x32_bf16 v[92:95], v[128:131], v[202:205], 0
	v_mfma_f32_16x16x32_bf16 v[88:91], v[136:139], v[202:205], 0
	v_mfma_f32_16x16x32_bf16 v[76:79], v[128:131], v[210:213], 0
	v_mfma_f32_16x16x32_bf16 v[72:75], v[136:139], v[210:213], 0
	v_mfma_f32_16x16x32_bf16 v[124:127], v[132:135], v[164:167], v[124:127]
	v_mfma_f32_16x16x32_bf16 v[120:123], v[140:143], v[164:167], v[120:123]
	v_mfma_f32_16x16x32_bf16 v[108:111], v[132:135], v[198:201], v[108:111]
	v_mfma_f32_16x16x32_bf16 v[104:107], v[140:143], v[198:201], v[104:107]
	v_mfma_f32_16x16x32_bf16 v[92:95], v[132:135], v[206:209], v[92:95]
	v_mfma_f32_16x16x32_bf16 v[88:91], v[140:143], v[206:209], v[88:91]
	v_mfma_f32_16x16x32_bf16 v[76:79], v[132:135], v[214:217], v[76:79]
	v_mfma_f32_16x16x32_bf16 v[72:75], v[140:143], v[214:217], v[72:75]
	s_setprio 0
	s_setprio 1
	v_mfma_f32_16x16x32_bf16 v[116:119], v[144:147], v[160:163], 0
	v_mfma_f32_16x16x32_bf16 v[112:115], v[152:155], v[160:163], 0
	v_mfma_f32_16x16x32_bf16 v[100:103], v[144:147], v[170:173], 0
	v_mfma_f32_16x16x32_bf16 v[96:99], v[152:155], v[170:173], 0
	v_mfma_f32_16x16x32_bf16 v[84:87], v[144:147], v[202:205], 0
	v_mfma_f32_16x16x32_bf16 v[80:83], v[152:155], v[202:205], 0
	v_mfma_f32_16x16x32_bf16 v[68:71], v[144:147], v[210:213], 0
	v_mfma_f32_16x16x32_bf16 v[64:67], v[152:155], v[210:213], 0
	v_mfma_f32_16x16x32_bf16 v[116:119], v[148:151], v[164:167], v[116:119]
	v_mfma_f32_16x16x32_bf16 v[112:115], v[156:159], v[164:167], v[112:115]
	v_mfma_f32_16x16x32_bf16 v[100:103], v[148:151], v[198:201], v[100:103]
	v_mfma_f32_16x16x32_bf16 v[96:99], v[156:159], v[198:201], v[96:99]
	v_mfma_f32_16x16x32_bf16 v[84:87], v[148:151], v[206:209], v[84:87]
	s_add_i32 s64, s64, s2
	v_mfma_f32_16x16x32_bf16 v[80:83], v[156:159], v[206:209], v[80:83]
	v_lshl_add_u64 v[178:179], s[50:51], 0, v[168:169]
	v_mfma_f32_16x16x32_bf16 v[68:71], v[148:151], v[214:217], v[68:71]
	s_mov_b32 m0, s64
	v_mfma_f32_16x16x32_bf16 v[64:67], v[156:159], v[214:217], v[64:67]
	s_setprio 0
	s_barrier
	ds_read_b128 v[160:163], v237 offset:16384
	ds_read_b128 v[164:167], v237 offset:17408
	ds_read_b128 v[170:173], v237 offset:18432
	ds_read_b128 v[198:201], v237 offset:19456
	ds_read_b128 v[202:205], v237 offset:20480
	ds_read_b128 v[206:209], v237 offset:21504
	ds_read_b128 v[210:213], v237 offset:22528
	ds_read_b128 v[214:217], v237 offset:23552
	global_load_lds_dwordx4 v[178:179], off
	s_add_i32 m0, s64, 0x2000
	s_add_u32 s64, s50, 0xb0000
	v_lshl_add_u64 v[218:219], s[50:51], 0, v[188:189]
	s_addc_u32 s65, s51, 0
	s_add_i32 s74, s74, s2
	global_load_lds_dwordx4 v[218:219], off
	v_lshl_add_u64 v[220:221], s[64:65], 0, v[168:169]
	s_mov_b32 m0, s74
	s_nop 0
	global_load_lds_dwordx4 v[220:221], off
	v_lshl_add_u64 v[220:221], s[64:65], 0, v[188:189]
	s_add_i32 m0, s74, 0x2000
	s_nop 0
	global_load_lds_dwordx4 v[220:221], off
	v_lshl_add_u64 v[220:221], s[52:53], 0, v[192:193]
	s_mov_b32 m0, s3
	s_nop 0
	global_load_lds_dwordx4 v[220:221], off
	v_lshl_add_u64 v[220:221], s[52:53], 0, v[190:191]
	s_mov_b32 m0, s34
	s_nop 0
	global_load_lds_dwordx4 v[220:221], off
	s_waitcnt vmcnt(8)
	s_waitcnt lgkmcnt(0)
	s_barrier
; #define PG8_STAGE(bufoff, gbase, voff) do { _Pragma("unroll") for (int _i = 0; _i < 2; ++_i) \
;         __builtin_amdgcn_global_load_lds((const unsigned*)((const char*)(gbase) + (voff)[_i]), (PG8_LAS unsigned*)(lds + (bufoff) + ldsw + _i * 8192), 16, 0, 0); } while (0)
; #define PG8_LDA(dst, b, h) do { _Pragma("unroll") for (int m = 0; m < 4; ++m) _Pragma("unroll") for (int k = 0; k < 2; ++k) dst[m][k] = *(const PG8_LAS bf16x8*)(lds + PG8_SA(b, h) + aoff + m * 2048 + k * 1024); } while (0)
; #define PG8_LDB(dst, b, h) do { _Pragma("unroll") for (int n = 0; n < 2; ++n) _Pragma("unroll") for (int k = 0; k < 2; ++k) dst[n][k] = *(const PG8_LAS bf16x8*)(lds + PG8_SB(b, h) + boff + n * 2048 + k * 1024); } while (0)
; #define PG8_MMA(ai, bj, At, Bt) do { __builtin_amdgcn_s_setprio(1); _Pragma("unroll") for (int m = 0; m < 4; ++m) _Pragma("unroll") for (int n = 0; n < 2; ++n) _Pragma("unroll") for (int k = 0; k < 2; ++k) \
;         acc[ai][bj][m][n] = __builtin_amdgcn_mfma_f32_16x16x32_bf16(Bt[n][k], At[m][k], acc[ai][bj][m][n], 0, 0, 0); __builtin_amdgcn_s_setprio(0); } while (0)
; #define PG8_WAIT_V(n) asm volatile("s_waitcnt vmcnt(" #n ")" ::: "memory")
; #define PG8_WAIT_L(n) asm volatile("s_waitcnt lgkmcnt(" #n ")" ::: "memory")
; #define PG8_BAR __builtin_amdgcn_s_barrier()
; #define PG8_SCHED __builtin_amdgcn_sched_barrier(0)
; template <class Epi, class Sched, bool ALIGN_EPI = false, bool SP2 = false>
; __device__ __forceinline__ void gemm_phase(PG8_LAS unsigned char* lds, const Gemm g, const Sched& S, const Epi& E) {
;     ...
;             PG8_WAIT_V(8); PG8_WAIT_L(0); PG8_BAR; PG8_MMA(0, 0, At, B0); PG8_MMA(0, 1, At, B1); PG8_BAR; PG8_SCHED;
;             PG8_LDA(At, 0, 1); PG8_STAGE(PG8_SB(0, 0), b2, voffB); PG8_STAGE(PG8_SB(0, 1), b2 + hstep, voffB); PG8_STAGE(PG8_SA(0, 0), a2, voffA);
;             PG8_WAIT_V(8); PG8_WAIT_L(0); PG8_BAR; PG8_MMA(1, 0, At, B0); PG8_MMA(1, 1, At, B1); PG8_BAR; PG8_SCHED;
;             PG8_LDB(B0, 1, 0); PG8_LDB(B1, 1, 1); PG8_SCHED; PG8_LDA(At, 1, 0); PG8_STAGE(PG8_SA(0, 1), a2 + hstepA, voffA);
;             PG8_WAIT_V(8); PG8_WAIT_L(0); PG8_BAR; PG8_MMA(0, 0, At, B0); PG8_MMA(0, 1, At, B1); PG8_BAR; PG8_SCHED;
	s_setprio 1
	s_waitcnt lgkmcnt(0)
	v_mfma_f32_16x16x32_bf16 v[60:63], v[128:131], v[160:163], 0
	v_mfma_f32_16x16x32_bf16 v[56:59], v[136:139], v[160:163], 0
	v_mfma_f32_16x16x32_bf16 v[44:47], v[128:131], v[170:173], 0
	v_mfma_f32_16x16x32_bf16 v[40:43], v[136:139], v[170:173], 0
	v_mfma_f32_16x16x32_bf16 v[28:31], v[128:131], v[202:205], 0
	v_mfma_f32_16x16x32_bf16 v[24:27], v[136:139], v[202:205], 0
	v_mfma_f32_16x16x32_bf16 v[12:15], v[128:131], v[210:213], 0
	v_mfma_f32_16x16x32_bf16 v[8:11], v[136:139], v[210:213], 0
	v_mfma_f32_16x16x32_bf16 v[60:63], v[132:135], v[164:167], v[60:63]
	v_mfma_f32_16x16x32_bf16 v[56:59], v[140:143], v[164:167], v[56:59]
	v_mfma_f32_16x16x32_bf16 v[44:47], v[132:135], v[198:201], v[44:47]
	v_mfma_f32_16x16x32_bf16 v[40:43], v[140:143], v[198:201], v[40:43]
	v_mfma_f32_16x16x32_bf16 v[28:31], v[132:135], v[206:209], v[28:31]
	v_mfma_f32_16x16x32_bf16 v[24:27], v[140:143], v[206:209], v[24:27]
	v_mfma_f32_16x16x32_bf16 v[12:15], v[132:135], v[214:217], v[12:15]
	v_mfma_f32_16x16x32_bf16 v[8:11], v[140:143], v[214:217], v[8:11]
	s_setprio 0
	s_setprio 1
	v_mfma_f32_16x16x32_bf16 v[52:55], v[144:147], v[160:163], 0
	v_mfma_f32_16x16x32_bf16 v[48:51], v[152:155], v[160:163], 0
	v_mfma_f32_16x16x32_bf16 v[36:39], v[144:147], v[170:173], 0
	v_mfma_f32_16x16x32_bf16 v[32:35], v[152:155], v[170:173], 0
	v_mfma_f32_16x16x32_bf16 v[20:23], v[144:147], v[202:205], 0
	v_mfma_f32_16x16x32_bf16 v[16:19], v[152:155], v[202:205], 0
	v_mfma_f32_16x16x32_bf16 v[4:7], v[144:147], v[210:213], 0
	v_mfma_f32_16x16x32_bf16 v[0:3], v[152:155], v[210:213], 0
	v_mfma_f32_16x16x32_bf16 v[52:55], v[148:151], v[164:167], v[52:55]
	v_mfma_f32_16x16x32_bf16 v[48:51], v[156:159], v[164:167], v[48:51]
	v_mfma_f32_16x16x32_bf16 v[36:39], v[148:151], v[198:201], v[36:39]
	v_mfma_f32_16x16x32_bf16 v[32:35], v[156:159], v[198:201], v[32:35]
	s_add_i32 s64, 0, 0x18000
	v_mfma_f32_16x16x32_bf16 v[20:23], v[148:151], v[206:209], v[20:23]
	s_add_i32 s65, 0, 0x1c000
	v_mfma_f32_16x16x32_bf16 v[16:19], v[156:159], v[206:209], v[16:19]
	v_add_u32_e32 v240, s64, v236
	v_mfma_f32_16x16x32_bf16 v[4:7], v[148:151], v[214:217], v[4:7]
	v_add_u32_e32 v241, s65, v236
	v_mfma_f32_16x16x32_bf16 v[0:3], v[156:159], v[214:217], v[0:3]
	s_setprio 0
	s_barrier
	ds_read_b128 v[128:131], v240
	ds_read_b128 v[132:135], v240 offset:1024
	ds_read_b128 v[136:139], v240 offset:2048
	ds_read_b128 v[140:143], v240 offset:3072
	ds_read_b128 v[144:147], v241
	ds_read_b128 v[148:151], v241 offset:1024
	ds_read_b128 v[152:155], v241 offset:2048
	ds_read_b128 v[156:159], v241 offset:3072
	s_add_u32 s52, s52, 0xb0000
	s_addc_u32 s53, s53, 0
	s_mov_b32 m0, s35
	v_lshl_add_u64 v[220:221], s[52:53], 0, v[192:193]
	ds_read_b128 v[160:163], v237 offset:32768
	ds_read_b128 v[164:167], v237 offset:33792
	ds_read_b128 v[170:173], v237 offset:34816
	ds_read_b128 v[198:201], v237 offset:35840
	ds_read_b128 v[202:205], v237 offset:36864
	ds_read_b128 v[206:209], v237 offset:37888
	ds_read_b128 v[210:213], v237 offset:38912
	ds_read_b128 v[214:217], v237 offset:39936
	global_load_lds_dwordx4 v[220:221], off
	v_lshl_add_u64 v[220:221], s[52:53], 0, v[190:191]
	s_mov_b32 m0, s54
	s_nop 0
	global_load_lds_dwordx4 v[220:221], off
	s_waitcnt vmcnt(8)
	s_waitcnt lgkmcnt(0)
	s_barrier
	s_setprio 1
	s_waitcnt lgkmcnt(0)
	v_mfma_f32_16x16x32_bf16 v[124:127], v[128:131], v[160:163], v[124:127]
	v_mfma_f32_16x16x32_bf16 v[120:123], v[136:139], v[160:163], v[120:123]
	v_mfma_f32_16x16x32_bf16 v[108:111], v[128:131], v[170:173], v[108:111]
	v_mfma_f32_16x16x32_bf16 v[104:107], v[136:139], v[170:173], v[104:107]
	v_mfma_f32_16x16x32_bf16 v[92:95], v[128:131], v[202:205], v[92:95]
	v_mfma_f32_16x16x32_bf16 v[88:91], v[136:139], v[202:205], v[88:91]
	v_mfma_f32_16x16x32_bf16 v[76:79], v[128:131], v[210:213], v[76:79]
	v_mfma_f32_16x16x32_bf16 v[72:75], v[136:139], v[210:213], v[72:75]
	v_mfma_f32_16x16x32_bf16 v[124:127], v[132:135], v[164:167], v[124:127]
	v_mfma_f32_16x16x32_bf16 v[120:123], v[140:143], v[164:167], v[120:123]
	v_mfma_f32_16x16x32_bf16 v[108:111], v[132:135], v[198:201], v[108:111]
	v_mfma_f32_16x16x32_bf16 v[104:107], v[140:143], v[198:201], v[104:107]
	v_mfma_f32_16x16x32_bf16 v[92:95], v[132:135], v[206:209], v[92:95]
	v_mfma_f32_16x16x32_bf16 v[88:91], v[140:143], v[206:209], v[88:91]
	v_mfma_f32_16x16x32_bf16 v[76:79], v[132:135], v[214:217], v[76:79]
	v_mfma_f32_16x16x32_bf16 v[72:75], v[140:143], v[214:217], v[72:75]
	s_setprio 0
	s_setprio 1
	v_mfma_f32_16x16x32_bf16 v[116:119], v[144:147], v[160:163], v[116:119]
	v_mfma_f32_16x16x32_bf16 v[112:115], v[152:155], v[160:163], v[112:115]
	v_mfma_f32_16x16x32_bf16 v[100:103], v[144:147], v[170:173], v[100:103]
	v_mfma_f32_16x16x32_bf16 v[96:99], v[152:155], v[170:173], v[96:99]
	v_mfma_f32_16x16x32_bf16 v[84:87], v[144:147], v[202:205], v[84:87]
	v_mfma_f32_16x16x32_bf16 v[80:83], v[152:155], v[202:205], v[80:83]
	v_mfma_f32_16x16x32_bf16 v[68:71], v[144:147], v[210:213], v[68:71]
	v_mfma_f32_16x16x32_bf16 v[64:67], v[152:155], v[210:213], v[64:67]
	v_mfma_f32_16x16x32_bf16 v[116:119], v[148:151], v[164:167], v[116:119]
	v_mfma_f32_16x16x32_bf16 v[112:115], v[156:159], v[164:167], v[112:115]
	v_mfma_f32_16x16x32_bf16 v[100:103], v[148:151], v[198:201], v[100:103]
	v_mfma_f32_16x16x32_bf16 v[96:99], v[156:159], v[198:201], v[96:99]
	v_mfma_f32_16x16x32_bf16 v[84:87], v[148:151], v[206:209], v[84:87]
	s_add_i32 s52, s64, s2
	v_mfma_f32_16x16x32_bf16 v[80:83], v[156:159], v[206:209], v[80:83]
	v_lshl_add_u64 v[178:179], v[178:179], 0, s[30:31]
	v_mfma_f32_16x16x32_bf16 v[68:71], v[148:151], v[214:217], v[68:71]
	s_mov_b32 m0, s52
	v_mfma_f32_16x16x32_bf16 v[64:67], v[156:159], v[214:217], v[64:67]
	s_setprio 0
	s_barrier
; #define PG8_STAGE(bufoff, gbase, voff) do { _Pragma("unroll") for (int _i = 0; _i < 2; ++_i) \
;         __builtin_amdgcn_global_load_lds((const unsigned*)((const char*)(gbase) + (voff)[_i]), (PG8_LAS unsigned*)(lds + (bufoff) + ldsw + _i * 8192), 16, 0, 0); } while (0)
; #define PG8_LDA(dst, b, h) do { _Pragma("unroll") for (int m = 0; m < 4; ++m) _Pragma("unroll") for (int k = 0; k < 2; ++k) dst[m][k] = *(const PG8_LAS bf16x8*)(lds + PG8_SA(b, h) + aoff + m * 2048 + k * 1024); } while (0)
; #define PG8_LDB(dst, b, h) do { _Pragma("unroll") for (int n = 0; n < 2; ++n) _Pragma("unroll") for (int k = 0; k < 2; ++k) dst[n][k] = *(const PG8_LAS bf16x8*)(lds + PG8_SB(b, h) + boff + n * 2048 + k * 1024); } while (0)
; template <class Epi, class Sched, bool ALIGN_EPI = false, bool SP2 = false>
; __device__ __forceinline__ void gemm_phase(PG8_LAS unsigned char* lds, const Gemm g, const Sched& S, const Epi& E) {
;     ...
;         for (int t = 0; t < nt; t += 2) {
;             const bool last = (t == nt - 2);
;             const char* a1 = cA + (size_t)(t + 1) * kstepA;
;             const char* a2 = last ? nA : cA + (size_t)(t + 2) * kstepA; const char* b2 = last ? nB : cB + (size_t)(t + 2) * kstep;
;             const char* a3 = a2 + kstepA; const char* b3 = b2 + kstep;
;             if (last && has_next) S.a_ready(nxt);
;             if constexpr (SP2) {
;             PG8_LDB(B0, 0, 0); PG8_LDB(B1, 0, 1); PG8_SCHED; PG8_LDA(At, 0, 0); PG8_STAGE(PG8_SA(1, 1), a1 + hstepA, voffA);
;             PG8_WAIT_V(8); PG8_WAIT_L(0); PG8_BAR; PG8_MMA(0, 0, At, B0); PG8_MMA(0, 1, At, B1); PG8_BAR; PG8_SCHED;
;             PG8_LDA(At, 0, 1); PG8_STAGE(PG8_SB(0, 0), b2, voffB); PG8_STAGE(PG8_SB(0, 1), b2 + hstep, voffB); PG8_STAGE(PG8_SA(0, 0), a2, voffA);
;             PG8_WAIT_V(8); PG8_WAIT_L(0); PG8_BAR; PG8_MMA(1, 0, At, B0); PG8_MMA(1, 1, At, B1); PG8_BAR; PG8_SCHED;
;             PG8_LDB(B0, 1, 0); PG8_LDB(B1, 1, 1); PG8_SCHED; PG8_LDA(At, 1, 0); PG8_STAGE(PG8_SA(0, 1), a2 + hstepA, voffA);
;             PG8_WAIT_V(8); PG8_WAIT_L(0); PG8_BAR; PG8_MMA(0, 0, At, B0); PG8_MMA(0, 1, At, B1); PG8_BAR; PG8_SCHED;
;             PG8_LDA(At, 1, 1); PG8_STAGE(PG8_SB(1, 0), b3, voffB); PG8_STAGE(PG8_SB(1, 1), b3 + hstep, voffB); PG8_STAGE(PG8_SA(1, 0), a3, voffA);
;             PG8_WAIT_V(8); PG8_WAIT_L(0); PG8_BAR; PG8_MMA(1, 0, At, B0); PG8_MMA(1, 1, At, B1); PG8_BAR; PG8_SCHED;
	ds_read_b128 v[160:163], v237 offset:49152
	ds_read_b128 v[164:167], v237 offset:50176
	ds_read_b128 v[170:173], v237 offset:51200
	ds_read_b128 v[198:201], v237 offset:52224
	ds_read_b128 v[202:205], v237 offset:53248
	ds_read_b128 v[206:209], v237 offset:54272
	ds_read_b128 v[210:213], v237 offset:55296
	ds_read_b128 v[214:217], v237 offset:56320
	global_load_lds_dwordx4 v[178:179], off
	s_add_i32 m0, s52, 0x2000
	s_add_u32 s50, s50, 0xb0080
	v_lshl_add_u64 v[178:179], v[218:219], 0, s[30:31]
	s_addc_u32 s51, s51, 0
	s_add_i32 s52, s65, s2
	global_load_lds_dwordx4 v[178:179], off
	v_lshl_add_u64 v[178:179], s[50:51], 0, v[168:169]
	s_mov_b32 m0, s52
	s_nop 0
	global_load_lds_dwordx4 v[178:179], off
	v_lshl_add_u64 v[178:179], s[50:51], 0, v[188:189]
	s_add_i32 m0, s52, 0x2000
	s_nop 0
	global_load_lds_dwordx4 v[178:179], off
	v_lshl_add_u64 v[178:179], s[48:49], 0, v[192:193]
	s_mov_b32 m0, s57
	s_nop 0
	global_load_lds_dwordx4 v[178:179], off
	v_lshl_add_u64 v[178:179], s[48:49], 0, v[190:191]
	s_mov_b32 m0, s60
	s_nop 0
	global_load_lds_dwordx4 v[178:179], off
	s_waitcnt vmcnt(8)
	s_waitcnt lgkmcnt(0)
	s_barrier
	s_setprio 1
	s_waitcnt lgkmcnt(0)
	v_mfma_f32_16x16x32_bf16 v[60:63], v[128:131], v[160:163], v[60:63]
	v_mfma_f32_16x16x32_bf16 v[56:59], v[136:139], v[160:163], v[56:59]
	v_mfma_f32_16x16x32_bf16 v[44:47], v[128:131], v[170:173], v[44:47]
	v_mfma_f32_16x16x32_bf16 v[40:43], v[136:139], v[170:173], v[40:43]
	v_mfma_f32_16x16x32_bf16 v[28:31], v[128:131], v[202:205], v[28:31]
	v_mfma_f32_16x16x32_bf16 v[24:27], v[136:139], v[202:205], v[24:27]
	v_mfma_f32_16x16x32_bf16 v[12:15], v[128:131], v[210:213], v[12:15]
	v_mfma_f32_16x16x32_bf16 v[8:11], v[136:139], v[210:213], v[8:11]
	v_mfma_f32_16x16x32_bf16 v[60:63], v[132:135], v[164:167], v[60:63]
	v_mfma_f32_16x16x32_bf16 v[56:59], v[140:143], v[164:167], v[56:59]
	v_mfma_f32_16x16x32_bf16 v[44:47], v[132:135], v[198:201], v[44:47]
	v_mfma_f32_16x16x32_bf16 v[40:43], v[140:143], v[198:201], v[40:43]
	v_mfma_f32_16x16x32_bf16 v[28:31], v[132:135], v[206:209], v[28:31]
	v_mfma_f32_16x16x32_bf16 v[24:27], v[140:143], v[206:209], v[24:27]
	s_add_i32 s7, s7, 2
	v_mfma_f32_16x16x32_bf16 v[12:15], v[132:135], v[214:217], v[12:15]
	s_add_u32 s5, s5, 0x100
	v_mfma_f32_16x16x32_bf16 v[8:11], v[140:143], v[214:217], v[8:11]
	s_addc_u32 s6, s6, 0
	s_setprio 0
	s_setprio 1
	v_mfma_f32_16x16x32_bf16 v[52:55], v[144:147], v[160:163], v[52:55]
	s_add_u32 s38, s38, 0x8000
	v_mfma_f32_16x16x32_bf16 v[48:51], v[152:155], v[160:163], v[48:51]
	s_addc_u32 s39, s39, 0
	v_mfma_f32_16x16x32_bf16 v[36:39], v[144:147], v[170:173], v[36:39]
	s_add_u32 s48, s38, 0xfff54000
	v_mfma_f32_16x16x32_bf16 v[32:35], v[152:155], v[170:173], v[32:35]
	s_addc_u32 s49, s39, -1
	v_mfma_f32_16x16x32_bf16 v[20:23], v[144:147], v[202:205], v[20:23]
	s_cmp_eq_u32 s7, 40
	v_mfma_f32_16x16x32_bf16 v[16:19], v[152:155], v[202:205], v[16:19]
	s_cselect_b32 s52, s44, s48
	v_mfma_f32_16x16x32_bf16 v[4:7], v[144:147], v[210:213], v[4:7]
	s_cselect_b32 s53, s45, s49
	v_mfma_f32_16x16x32_bf16 v[0:3], v[152:155], v[210:213], v[0:3]
	s_cselect_b32 s50, s46, s5
	v_mfma_f32_16x16x32_bf16 v[52:55], v[148:151], v[164:167], v[52:55]
	s_cselect_b32 s51, s47, s6
	v_mfma_f32_16x16x32_bf16 v[48:51], v[156:159], v[164:167], v[48:51]
	s_add_u32 s48, s52, 0x4000
	v_mfma_f32_16x16x32_bf16 v[36:39], v[148:151], v[198:201], v[36:39]
	s_addc_u32 s49, s53, 0
	v_mfma_f32_16x16x32_bf16 v[32:35], v[156:159], v[198:201], v[32:35]
	s_add_i32 s64, 0, 0x10000
	v_mfma_f32_16x16x32_bf16 v[20:23], v[148:151], v[206:209], v[20:23]
	s_add_i32 s74, 0, 0x14000
	v_mfma_f32_16x16x32_bf16 v[16:19], v[156:159], v[206:209], v[16:19]
	v_add_u32_e32 v242, s64, v236
	v_mfma_f32_16x16x32_bf16 v[4:7], v[148:151], v[214:217], v[4:7]
	v_add_u32_e32 v243, s74, v236
	v_mfma_f32_16x16x32_bf16 v[0:3], v[156:159], v[214:217], v[0:3]
	s_setprio 0
	s_barrier
.LBB0_974:
	ds_read_b128 v[128:131], v242
	ds_read_b128 v[132:135], v242 offset:1024
	ds_read_b128 v[136:139], v242 offset:2048
	ds_read_b128 v[140:143], v242 offset:3072
	ds_read_b128 v[144:147], v243
	ds_read_b128 v[148:151], v243 offset:1024
	ds_read_b128 v[152:155], v243 offset:2048
	ds_read_b128 v[156:159], v243 offset:3072
	v_lshl_add_u64 v[178:179], s[38:39], 0, v[196:197]
	s_add_i32 m0, s3, 0xc000
	ds_read_b128 v[160:163], v237
	ds_read_b128 v[164:167], v237 offset:1024
	ds_read_b128 v[170:173], v237 offset:2048
	ds_read_b128 v[198:201], v237 offset:3072
	ds_read_b128 v[202:205], v237 offset:4096
	ds_read_b128 v[206:209], v237 offset:5120
	ds_read_b128 v[210:213], v237 offset:6144
	ds_read_b128 v[214:217], v237 offset:7168
	global_load_lds_dwordx4 v[178:179], off
	v_lshl_add_u64 v[178:179], s[38:39], 0, v[194:195]
	s_add_i32 m0, s3, 0xe000
	s_nop 0
	global_load_lds_dwordx4 v[178:179], off
	s_waitcnt vmcnt(8)
	s_waitcnt lgkmcnt(0)
	s_barrier
; #define PG8_STAGE(bufoff, gbase, voff) do { _Pragma("unroll") for (int _i = 0; _i < 2; ++_i) \
;         __builtin_amdgcn_global_load_lds((const unsigned*)((const char*)(gbase) + (voff)[_i]), (PG8_LAS unsigned*)(lds + (bufoff) + ldsw + _i * 8192), 16, 0, 0); } while (0)
; #define PG8_LDA(dst, b, h) do { _Pragma("unroll") for (int m = 0; m < 4; ++m) _Pragma("unroll") for (int k = 0; k < 2; ++k) dst[m][k] = *(const PG8_LAS bf16x8*)(lds + PG8_SA(b, h) + aoff + m * 2048 + k * 1024); } while (0)
; #define PG8_LDB(dst, b, h) do { _Pragma("unroll") for (int n = 0; n < 2; ++n) _Pragma("unroll") for (int k = 0; k < 2; ++k) dst[n][k] = *(const PG8_LAS bf16x8*)(lds + PG8_SB(b, h) + boff + n * 2048 + k * 1024); } while (0)
; #define PG8_MMA(ai, bj, At, Bt) do { __builtin_amdgcn_s_setprio(1); _Pragma("unroll") for (int m = 0; m < 4; ++m) _Pragma("unroll") for (int n = 0; n < 2; ++n) _Pragma("unroll") for (int k = 0; k < 2; ++k) \
;         acc[ai][bj][m][n] = __builtin_amdgcn_mfma_f32_16x16x32_bf16(Bt[n][k], At[m][k], acc[ai][bj][m][n], 0, 0, 0); __builtin_amdgcn_s_setprio(0); } while (0)
; #define PG8_WAIT_V(n) asm volatile("s_waitcnt vmcnt(" #n ")" ::: "memory")
; #define PG8_WAIT_L(n) asm volatile("s_waitcnt lgkmcnt(" #n ")" ::: "memory")
; #define PG8_BAR __builtin_amdgcn_s_barrier()
; #define PG8_SCHED __builtin_amdgcn_sched_barrier(0)
; template <class Epi, class Sched, bool ALIGN_EPI = false, bool SP2 = false>
; __device__ __forceinline__ void gemm_phase(PG8_LAS unsigned char* lds, const Gemm g, const Sched& S, const Epi& E) {
;     ...
;             PG8_LDB(B0, 0, 0); PG8_LDB(B1, 0, 1); PG8_SCHED; PG8_LDA(At, 0, 0); PG8_STAGE(PG8_SA(1, 1), a1 + hstepA, voffA);
;             PG8_WAIT_V(8); PG8_WAIT_L(0); PG8_BAR; PG8_MMA(0, 0, At, B0); PG8_MMA(0, 1, At, B1); PG8_BAR; PG8_SCHED;
;             PG8_LDA(At, 0, 1); PG8_STAGE(PG8_SB(0, 0), b2, voffB); PG8_STAGE(PG8_SB(0, 1), b2 + hstep, voffB); PG8_STAGE(PG8_SA(0, 0), a2, voffA);
;             PG8_WAIT_V(8); PG8_WAIT_L(0); PG8_BAR; PG8_MMA(1, 0, At, B0); PG8_MMA(1, 1, At, B1); PG8_BAR; PG8_SCHED;
	s_setprio 1
	s_waitcnt lgkmcnt(0)
	v_mfma_f32_16x16x32_bf16 v[124:127], v[128:131], v[160:163], v[124:127]
	v_mfma_f32_16x16x32_bf16 v[120:123], v[136:139], v[160:163], v[120:123]
	v_mfma_f32_16x16x32_bf16 v[108:111], v[128:131], v[170:173], v[108:111]
	v_mfma_f32_16x16x32_bf16 v[104:107], v[136:139], v[170:173], v[104:107]
	v_mfma_f32_16x16x32_bf16 v[92:95], v[128:131], v[202:205], v[92:95]
	v_mfma_f32_16x16x32_bf16 v[88:91], v[136:139], v[202:205], v[88:91]
	v_mfma_f32_16x16x32_bf16 v[76:79], v[128:131], v[210:213], v[76:79]
	v_mfma_f32_16x16x32_bf16 v[72:75], v[136:139], v[210:213], v[72:75]
	v_mfma_f32_16x16x32_bf16 v[124:127], v[132:135], v[164:167], v[124:127]
	v_mfma_f32_16x16x32_bf16 v[120:123], v[140:143], v[164:167], v[120:123]
	v_mfma_f32_16x16x32_bf16 v[108:111], v[132:135], v[198:201], v[108:111]
	v_mfma_f32_16x16x32_bf16 v[104:107], v[140:143], v[198:201], v[104:107]
	v_mfma_f32_16x16x32_bf16 v[92:95], v[132:135], v[206:209], v[92:95]
	v_mfma_f32_16x16x32_bf16 v[88:91], v[140:143], v[206:209], v[88:91]
	v_mfma_f32_16x16x32_bf16 v[76:79], v[132:135], v[214:217], v[76:79]
	v_mfma_f32_16x16x32_bf16 v[72:75], v[140:143], v[214:217], v[72:75]
	s_setprio 0
	s_setprio 1
	v_mfma_f32_16x16x32_bf16 v[116:119], v[144:147], v[160:163], v[116:119]
	v_mfma_f32_16x16x32_bf16 v[112:115], v[152:155], v[160:163], v[112:115]
	v_mfma_f32_16x16x32_bf16 v[100:103], v[144:147], v[170:173], v[100:103]
	v_mfma_f32_16x16x32_bf16 v[96:99], v[152:155], v[170:173], v[96:99]
	v_mfma_f32_16x16x32_bf16 v[84:87], v[144:147], v[202:205], v[84:87]
	v_mfma_f32_16x16x32_bf16 v[80:83], v[152:155], v[202:205], v[80:83]
	v_mfma_f32_16x16x32_bf16 v[68:71], v[144:147], v[210:213], v[68:71]
	v_mfma_f32_16x16x32_bf16 v[64:67], v[152:155], v[210:213], v[64:67]
	v_mfma_f32_16x16x32_bf16 v[116:119], v[148:151], v[164:167], v[116:119]
	v_mfma_f32_16x16x32_bf16 v[112:115], v[156:159], v[164:167], v[112:115]
	v_mfma_f32_16x16x32_bf16 v[100:103], v[148:151], v[198:201], v[100:103]
	v_mfma_f32_16x16x32_bf16 v[96:99], v[156:159], v[198:201], v[96:99]
	v_mfma_f32_16x16x32_bf16 v[84:87], v[148:151], v[206:209], v[84:87]
	s_add_i32 s64, s64, s2
	v_mfma_f32_16x16x32_bf16 v[80:83], v[156:159], v[206:209], v[80:83]
	v_lshl_add_u64 v[178:179], s[50:51], 0, v[168:169]
	v_mfma_f32_16x16x32_bf16 v[68:71], v[148:151], v[214:217], v[68:71]
	s_mov_b32 m0, s64
	v_mfma_f32_16x16x32_bf16 v[64:67], v[156:159], v[214:217], v[64:67]
	s_setprio 0
	s_barrier
	ds_read_b128 v[160:163], v237 offset:16384
	ds_read_b128 v[164:167], v237 offset:17408
	ds_read_b128 v[170:173], v237 offset:18432
	ds_read_b128 v[198:201], v237 offset:19456
	ds_read_b128 v[202:205], v237 offset:20480
	ds_read_b128 v[206:209], v237 offset:21504
	ds_read_b128 v[210:213], v237 offset:22528
	ds_read_b128 v[214:217], v237 offset:23552
	global_load_lds_dwordx4 v[178:179], off
	s_add_i32 m0, s64, 0x2000
	s_add_u32 s64, s50, 0xb0000
	v_lshl_add_u64 v[218:219], s[50:51], 0, v[188:189]
	s_addc_u32 s65, s51, 0
	s_add_i32 s74, s74, s2
	global_load_lds_dwordx4 v[218:219], off
	v_lshl_add_u64 v[220:221], s[64:65], 0, v[168:169]
	s_mov_b32 m0, s74
	s_nop 0
	global_load_lds_dwordx4 v[220:221], off
	v_lshl_add_u64 v[220:221], s[64:65], 0, v[188:189]
	s_add_i32 m0, s74, 0x2000
	s_nop 0
	global_load_lds_dwordx4 v[220:221], off
	v_lshl_add_u64 v[220:221], s[52:53], 0, v[192:193]
	s_mov_b32 m0, s3
	s_nop 0
	global_load_lds_dwordx4 v[220:221], off
	v_lshl_add_u64 v[220:221], s[52:53], 0, v[190:191]
	s_mov_b32 m0, s34
	s_nop 0
	global_load_lds_dwordx4 v[220:221], off
	s_waitcnt vmcnt(8)
	s_waitcnt lgkmcnt(0)
	s_barrier
	s_setprio 1
	s_waitcnt lgkmcnt(0)
	v_mfma_f32_16x16x32_bf16 v[60:63], v[128:131], v[160:163], v[60:63]
	v_mfma_f32_16x16x32_bf16 v[56:59], v[136:139], v[160:163], v[56:59]
	v_mfma_f32_16x16x32_bf16 v[44:47], v[128:131], v[170:173], v[44:47]
	v_mfma_f32_16x16x32_bf16 v[40:43], v[136:139], v[170:173], v[40:43]
	v_mfma_f32_16x16x32_bf16 v[28:31], v[128:131], v[202:205], v[28:31]
	v_mfma_f32_16x16x32_bf16 v[24:27], v[136:139], v[202:205], v[24:27]
	v_mfma_f32_16x16x32_bf16 v[12:15], v[128:131], v[210:213], v[12:15]
	v_mfma_f32_16x16x32_bf16 v[8:11], v[136:139], v[210:213], v[8:11]
	v_mfma_f32_16x16x32_bf16 v[60:63], v[132:135], v[164:167], v[60:63]
	v_mfma_f32_16x16x32_bf16 v[56:59], v[140:143], v[164:167], v[56:59]
	v_mfma_f32_16x16x32_bf16 v[44:47], v[132:135], v[198:201], v[44:47]
	v_mfma_f32_16x16x32_bf16 v[40:43], v[140:143], v[198:201], v[40:43]
	v_mfma_f32_16x16x32_bf16 v[28:31], v[132:135], v[206:209], v[28:31]
	v_mfma_f32_16x16x32_bf16 v[24:27], v[140:143], v[206:209], v[24:27]
	v_mfma_f32_16x16x32_bf16 v[12:15], v[132:135], v[214:217], v[12:15]
	v_mfma_f32_16x16x32_bf16 v[8:11], v[140:143], v[214:217], v[8:11]
	s_setprio 0
	s_setprio 1
	v_mfma_f32_16x16x32_bf16 v[52:55], v[144:147], v[160:163], v[52:55]
	v_mfma_f32_16x16x32_bf16 v[48:51], v[152:155], v[160:163], v[48:51]
	v_mfma_f32_16x16x32_bf16 v[36:39], v[144:147], v[170:173], v[36:39]
	v_mfma_f32_16x16x32_bf16 v[32:35], v[152:155], v[170:173], v[32:35]
	v_mfma_f32_16x16x32_bf16 v[20:23], v[144:147], v[202:205], v[20:23]
	v_mfma_f32_16x16x32_bf16 v[16:19], v[152:155], v[202:205], v[16:19]
	v_mfma_f32_16x16x32_bf16 v[4:7], v[144:147], v[210:213], v[4:7]
	v_mfma_f32_16x16x32_bf16 v[0:3], v[152:155], v[210:213], v[0:3]
	v_mfma_f32_16x16x32_bf16 v[52:55], v[148:151], v[164:167], v[52:55]
	v_mfma_f32_16x16x32_bf16 v[48:51], v[156:159], v[164:167], v[48:51]
	v_mfma_f32_16x16x32_bf16 v[36:39], v[148:151], v[198:201], v[36:39]
	v_mfma_f32_16x16x32_bf16 v[32:35], v[156:159], v[198:201], v[32:35]
	s_add_i32 s64, 0, 0x18000
	v_mfma_f32_16x16x32_bf16 v[20:23], v[148:151], v[206:209], v[20:23]
	s_add_i32 s65, 0, 0x1c000
	v_mfma_f32_16x16x32_bf16 v[16:19], v[156:159], v[206:209], v[16:19]
	v_add_u32_e32 v240, s64, v236
	v_mfma_f32_16x16x32_bf16 v[4:7], v[148:151], v[214:217], v[4:7]
	v_add_u32_e32 v241, s65, v236
	v_mfma_f32_16x16x32_bf16 v[0:3], v[156:159], v[214:217], v[0:3]
	s_setprio 0
	s_barrier
; #define PG8_STAGE(bufoff, gbase, voff) do { _Pragma("unroll") for (int _i = 0; _i < 2; ++_i) \
;         __builtin_amdgcn_global_load_lds((const unsigned*)((const char*)(gbase) + (voff)[_i]), (PG8_LAS unsigned*)(lds + (bufoff) + ldsw + _i * 8192), 16, 0, 0); } while (0)
; #define PG8_LDA(dst, b, h) do { _Pragma("unroll") for (int m = 0; m < 4; ++m) _Pragma("unroll") for (int k = 0; k < 2; ++k) dst[m][k] = *(const PG8_LAS bf16x8*)(lds + PG8_SA(b, h) + aoff + m * 2048 + k * 1024); } while (0)
; #define PG8_LDB(dst, b, h) do { _Pragma("unroll") for (int n = 0; n < 2; ++n) _Pragma("unroll") for (int k = 0; k < 2; ++k) dst[n][k] = *(const PG8_LAS bf16x8*)(lds + PG8_SB(b, h) + boff + n * 2048 + k * 1024); } while (0)
; #define PG8_MMA(ai, bj, At, Bt) do { __builtin_amdgcn_s_setprio(1); _Pragma("unroll") for (int m = 0; m < 4; ++m) _Pragma("unroll") for (int n = 0; n < 2; ++n) _Pragma("unroll") for (int k = 0; k < 2; ++k) \
;         acc[ai][bj][m][n] = __builtin_amdgcn_mfma_f32_16x16x32_bf16(Bt[n][k], At[m][k], acc[ai][bj][m][n], 0, 0, 0); __builtin_amdgcn_s_setprio(0); } while (0)
; #define PG8_WAIT_V(n) asm volatile("s_waitcnt vmcnt(" #n ")" ::: "memory")
; #define PG8_WAIT_L(n) asm volatile("s_waitcnt lgkmcnt(" #n ")" ::: "memory")
; #define PG8_BAR __builtin_amdgcn_s_barrier()
; #define PG8_SCHED __builtin_amdgcn_sched_barrier(0)
; template <class Epi, class Sched, bool ALIGN_EPI = false, bool SP2 = false>
; __device__ __forceinline__ void gemm_phase(PG8_LAS unsigned char* lds, const Gemm g, const Sched& S, const Epi& E) {
;     ...
;             PG8_LDB(B0, 1, 0); PG8_LDB(B1, 1, 1); PG8_SCHED; PG8_LDA(At, 1, 0); PG8_STAGE(PG8_SA(0, 1), a2 + hstepA, voffA);
;             PG8_WAIT_V(8); PG8_WAIT_L(0); PG8_BAR; PG8_MMA(0, 0, At, B0); PG8_MMA(0, 1, At, B1); PG8_BAR; PG8_SCHED;
;             PG8_LDA(At, 1, 1); PG8_STAGE(PG8_SB(1, 0), b3, voffB); PG8_STAGE(PG8_SB(1, 1), b3 + hstep, voffB); PG8_STAGE(PG8_SA(1, 0), a3, voffA);
	ds_read_b128 v[128:131], v240
	ds_read_b128 v[132:135], v240 offset:1024
	ds_read_b128 v[136:139], v240 offset:2048
	ds_read_b128 v[140:143], v240 offset:3072
	ds_read_b128 v[144:147], v241
	ds_read_b128 v[148:151], v241 offset:1024
	ds_read_b128 v[152:155], v241 offset:2048
	ds_read_b128 v[156:159], v241 offset:3072
	s_add_u32 s52, s52, 0xb0000
	s_addc_u32 s53, s53, 0
	s_mov_b32 m0, s35
	v_lshl_add_u64 v[220:221], s[52:53], 0, v[192:193]
	ds_read_b128 v[160:163], v237 offset:32768
	ds_read_b128 v[164:167], v237 offset:33792
	ds_read_b128 v[170:173], v237 offset:34816
	ds_read_b128 v[198:201], v237 offset:35840
	ds_read_b128 v[202:205], v237 offset:36864
	ds_read_b128 v[206:209], v237 offset:37888
	ds_read_b128 v[210:213], v237 offset:38912
	ds_read_b128 v[214:217], v237 offset:39936
	global_load_lds_dwordx4 v[220:221], off
	v_lshl_add_u64 v[220:221], s[52:53], 0, v[190:191]
	s_mov_b32 m0, s54
	s_nop 0
	global_load_lds_dwordx4 v[220:221], off
	s_waitcnt vmcnt(8)
	s_waitcnt lgkmcnt(0)
	s_barrier
	s_setprio 1
	s_waitcnt lgkmcnt(0)
	v_mfma_f32_16x16x32_bf16 v[124:127], v[128:131], v[160:163], v[124:127]
	v_mfma_f32_16x16x32_bf16 v[120:123], v[136:139], v[160:163], v[120:123]
	v_mfma_f32_16x16x32_bf16 v[108:111], v[128:131], v[170:173], v[108:111]
	v_mfma_f32_16x16x32_bf16 v[104:107], v[136:139], v[170:173], v[104:107]
	v_mfma_f32_16x16x32_bf16 v[92:95], v[128:131], v[202:205], v[92:95]
	v_mfma_f32_16x16x32_bf16 v[88:91], v[136:139], v[202:205], v[88:91]
	v_mfma_f32_16x16x32_bf16 v[76:79], v[128:131], v[210:213], v[76:79]
	v_mfma_f32_16x16x32_bf16 v[72:75], v[136:139], v[210:213], v[72:75]
	v_mfma_f32_16x16x32_bf16 v[124:127], v[132:135], v[164:167], v[124:127]
	v_mfma_f32_16x16x32_bf16 v[120:123], v[140:143], v[164:167], v[120:123]
	v_mfma_f32_16x16x32_bf16 v[108:111], v[132:135], v[198:201], v[108:111]
	v_mfma_f32_16x16x32_bf16 v[104:107], v[140:143], v[198:201], v[104:107]
	v_mfma_f32_16x16x32_bf16 v[92:95], v[132:135], v[206:209], v[92:95]
	v_mfma_f32_16x16x32_bf16 v[88:91], v[140:143], v[206:209], v[88:91]
	v_mfma_f32_16x16x32_bf16 v[76:79], v[132:135], v[214:217], v[76:79]
	v_mfma_f32_16x16x32_bf16 v[72:75], v[140:143], v[214:217], v[72:75]
	s_setprio 0
	s_setprio 1
	v_mfma_f32_16x16x32_bf16 v[116:119], v[144:147], v[160:163], v[116:119]
	v_mfma_f32_16x16x32_bf16 v[112:115], v[152:155], v[160:163], v[112:115]
	v_mfma_f32_16x16x32_bf16 v[100:103], v[144:147], v[170:173], v[100:103]
	v_mfma_f32_16x16x32_bf16 v[96:99], v[152:155], v[170:173], v[96:99]
	v_mfma_f32_16x16x32_bf16 v[84:87], v[144:147], v[202:205], v[84:87]
	v_mfma_f32_16x16x32_bf16 v[80:83], v[152:155], v[202:205], v[80:83]
	v_mfma_f32_16x16x32_bf16 v[68:71], v[144:147], v[210:213], v[68:71]
	v_mfma_f32_16x16x32_bf16 v[64:67], v[152:155], v[210:213], v[64:67]
	v_mfma_f32_16x16x32_bf16 v[116:119], v[148:151], v[164:167], v[116:119]
	v_mfma_f32_16x16x32_bf16 v[112:115], v[156:159], v[164:167], v[112:115]
	v_mfma_f32_16x16x32_bf16 v[100:103], v[148:151], v[198:201], v[100:103]
	v_mfma_f32_16x16x32_bf16 v[96:99], v[156:159], v[198:201], v[96:99]
	v_mfma_f32_16x16x32_bf16 v[84:87], v[148:151], v[206:209], v[84:87]
	s_add_i32 s52, s64, s2
	v_mfma_f32_16x16x32_bf16 v[80:83], v[156:159], v[206:209], v[80:83]
	v_lshl_add_u64 v[178:179], v[178:179], 0, s[30:31]
	v_mfma_f32_16x16x32_bf16 v[68:71], v[148:151], v[214:217], v[68:71]
	s_mov_b32 m0, s52
	v_mfma_f32_16x16x32_bf16 v[64:67], v[156:159], v[214:217], v[64:67]
	s_setprio 0
	s_barrier
; #define PG8_STAGE(bufoff, gbase, voff) do { _Pragma("unroll") for (int _i = 0; _i < 2; ++_i) \
;         __builtin_amdgcn_global_load_lds((const unsigned*)((const char*)(gbase) + (voff)[_i]), (PG8_LAS unsigned*)(lds + (bufoff) + ldsw + _i * 8192), 16, 0, 0); } while (0)
; #define PG8_LDA(dst, b, h) do { _Pragma("unroll") for (int m = 0; m < 4; ++m) _Pragma("unroll") for (int k = 0; k < 2; ++k) dst[m][k] = *(const PG8_LAS bf16x8*)(lds + PG8_SA(b, h) + aoff + m * 2048 + k * 1024); } while (0)
; #define PG8_LDB(dst, b, h) do { _Pragma("unroll") for (int n = 0; n < 2; ++n) _Pragma("unroll") for (int k = 0; k < 2; ++k) dst[n][k] = *(const PG8_LAS bf16x8*)(lds + PG8_SB(b, h) + boff + n * 2048 + k * 1024); } while (0)
; template <class Epi, class Sched, bool ALIGN_EPI = false, bool SP2 = false>
; __device__ __forceinline__ void gemm_phase(PG8_LAS unsigned char* lds, const Gemm g, const Sched& S, const Epi& E) {
;     ...
;         for (int t = 0; t < nt; t += 2) {
;             const bool last = (t == nt - 2);
;             const char* a1 = cA + (size_t)(t + 1) * kstepA;
;             const char* a2 = last ? nA : cA + (size_t)(t + 2) * kstepA; const char* b2 = last ? nB : cB + (size_t)(t + 2) * kstep;
;             const char* a3 = a2 + kstepA; const char* b3 = b2 + kstep;
;             if (last && has_next) S.a_ready(nxt);
;             if constexpr (SP2) {
;             PG8_LDB(B0, 0, 0); PG8_LDB(B1, 0, 1); PG8_SCHED; PG8_LDA(At, 0, 0); PG8_STAGE(PG8_SA(1, 1), a1 + hstepA, voffA);
;             PG8_WAIT_V(8); PG8_WAIT_L(0); PG8_BAR; PG8_MMA(0, 0, At, B0); PG8_MMA(0, 1, At, B1); PG8_BAR; PG8_SCHED;
;             PG8_LDA(At, 0, 1); PG8_STAGE(PG8_SB(0, 0), b2, voffB); PG8_STAGE(PG8_SB(0, 1), b2 + hstep, voffB); PG8_STAGE(PG8_SA(0, 0), a2, voffA);
;             PG8_WAIT_V(8); PG8_WAIT_L(0); PG8_BAR; PG8_MMA(1, 0, At, B0); PG8_MMA(1, 1, At, B1); PG8_BAR; PG8_SCHED;
;             PG8_LDB(B0, 1, 0); PG8_LDB(B1, 1, 1); PG8_SCHED; PG8_LDA(At, 1, 0); PG8_STAGE(PG8_SA(0, 1), a2 + hstepA, voffA);
;             PG8_WAIT_V(8); PG8_WAIT_L(0); PG8_BAR; PG8_MMA(0, 0, At, B0); PG8_MMA(0, 1, At, B1); PG8_BAR; PG8_SCHED;
;             PG8_LDA(At, 1, 1); PG8_STAGE(PG8_SB(1, 0), b3, voffB); PG8_STAGE(PG8_SB(1, 1), b3 + hstep, voffB); PG8_STAGE(PG8_SA(1, 0), a3, voffA);
;             PG8_WAIT_V(8); PG8_WAIT_L(0); PG8_BAR; PG8_MMA(1, 0, At, B0); PG8_MMA(1, 1, At, B1); PG8_BAR; PG8_SCHED;
	ds_read_b128 v[160:163], v237 offset:49152
	ds_read_b128 v[164:167], v237 offset:50176
	ds_read_b128 v[170:173], v237 offset:51200
	ds_read_b128 v[198:201], v237 offset:52224
	ds_read_b128 v[202:205], v237 offset:53248
	ds_read_b128 v[206:209], v237 offset:54272
	ds_read_b128 v[210:213], v237 offset:55296
	ds_read_b128 v[214:217], v237 offset:56320
	global_load_lds_dwordx4 v[178:179], off
	s_add_i32 m0, s52, 0x2000
	s_add_u32 s50, s50, 0xb0080
	v_lshl_add_u64 v[178:179], v[218:219], 0, s[30:31]
	s_addc_u32 s51, s51, 0
	s_add_i32 s52, s65, s2
	global_load_lds_dwordx4 v[178:179], off
	v_lshl_add_u64 v[178:179], s[50:51], 0, v[168:169]
	s_mov_b32 m0, s52
	s_nop 0
	global_load_lds_dwordx4 v[178:179], off
	v_lshl_add_u64 v[178:179], s[50:51], 0, v[188:189]
	s_add_i32 m0, s52, 0x2000
	s_nop 0
	global_load_lds_dwordx4 v[178:179], off
	v_lshl_add_u64 v[178:179], s[48:49], 0, v[192:193]
	s_mov_b32 m0, s57
	s_nop 0
	global_load_lds_dwordx4 v[178:179], off
	v_lshl_add_u64 v[178:179], s[48:49], 0, v[190:191]
	s_mov_b32 m0, s60
	s_nop 0
	global_load_lds_dwordx4 v[178:179], off
	s_waitcnt vmcnt(8)
	s_waitcnt lgkmcnt(0)
	s_barrier
	s_setprio 1
	s_waitcnt lgkmcnt(0)
	v_mfma_f32_16x16x32_bf16 v[60:63], v[128:131], v[160:163], v[60:63]
	v_mfma_f32_16x16x32_bf16 v[56:59], v[136:139], v[160:163], v[56:59]
	v_mfma_f32_16x16x32_bf16 v[44:47], v[128:131], v[170:173], v[44:47]
	v_mfma_f32_16x16x32_bf16 v[40:43], v[136:139], v[170:173], v[40:43]
	v_mfma_f32_16x16x32_bf16 v[28:31], v[128:131], v[202:205], v[28:31]
	v_mfma_f32_16x16x32_bf16 v[24:27], v[136:139], v[202:205], v[24:27]
	v_mfma_f32_16x16x32_bf16 v[12:15], v[128:131], v[210:213], v[12:15]
	v_mfma_f32_16x16x32_bf16 v[8:11], v[136:139], v[210:213], v[8:11]
	v_mfma_f32_16x16x32_bf16 v[60:63], v[132:135], v[164:167], v[60:63]
	v_mfma_f32_16x16x32_bf16 v[56:59], v[140:143], v[164:167], v[56:59]
	v_mfma_f32_16x16x32_bf16 v[44:47], v[132:135], v[198:201], v[44:47]
	v_mfma_f32_16x16x32_bf16 v[40:43], v[140:143], v[198:201], v[40:43]
	v_mfma_f32_16x16x32_bf16 v[28:31], v[132:135], v[206:209], v[28:31]
	s_add_i32 s7, s7, 2
	v_mfma_f32_16x16x32_bf16 v[24:27], v[140:143], v[206:209], v[24:27]
	s_add_u32 s5, s5, 0x100
	v_mfma_f32_16x16x32_bf16 v[12:15], v[132:135], v[214:217], v[12:15]
	s_addc_u32 s6, s6, 0
	v_mfma_f32_16x16x32_bf16 v[8:11], v[140:143], v[214:217], v[8:11]
	s_add_u32 s38, s38, 0x8000
	s_setprio 0
	s_setprio 1
	v_mfma_f32_16x16x32_bf16 v[52:55], v[144:147], v[160:163], v[52:55]
	s_addc_u32 s39, s39, 0
	v_mfma_f32_16x16x32_bf16 v[48:51], v[152:155], v[160:163], v[48:51]
	s_add_u32 s48, s38, 0xfff54000
	v_mfma_f32_16x16x32_bf16 v[36:39], v[144:147], v[170:173], v[36:39]
	s_addc_u32 s49, s39, -1
	v_mfma_f32_16x16x32_bf16 v[32:35], v[152:155], v[170:173], v[32:35]
	s_cmp_eq_u32 s7, 40
	v_mfma_f32_16x16x32_bf16 v[20:23], v[144:147], v[202:205], v[20:23]
	s_cselect_b32 s52, s44, s48
	v_mfma_f32_16x16x32_bf16 v[16:19], v[152:155], v[202:205], v[16:19]
	s_cselect_b32 s53, s45, s49
	v_mfma_f32_16x16x32_bf16 v[4:7], v[144:147], v[210:213], v[4:7]
	s_cselect_b32 s50, s46, s5
	v_mfma_f32_16x16x32_bf16 v[0:3], v[152:155], v[210:213], v[0:3]
	s_cselect_b32 s51, s47, s6
	v_mfma_f32_16x16x32_bf16 v[52:55], v[148:151], v[164:167], v[52:55]
	s_add_u32 s48, s52, 0x4000
	v_mfma_f32_16x16x32_bf16 v[48:51], v[156:159], v[164:167], v[48:51]
	s_addc_u32 s49, s53, 0
	v_mfma_f32_16x16x32_bf16 v[36:39], v[148:151], v[198:201], v[36:39]
	s_add_i32 s64, 0, 0x10000
	v_mfma_f32_16x16x32_bf16 v[32:35], v[156:159], v[198:201], v[32:35]
	s_add_i32 s74, 0, 0x14000
	v_mfma_f32_16x16x32_bf16 v[20:23], v[148:151], v[206:209], v[20:23]
	v_add_u32_e32 v242, s64, v236
	v_mfma_f32_16x16x32_bf16 v[16:19], v[156:159], v[206:209], v[16:19]
	v_add_u32_e32 v243, s74, v236
	v_mfma_f32_16x16x32_bf16 v[4:7], v[148:151], v[214:217], v[4:7]
	s_cmp_gt_u32 s7, 41
	v_mfma_f32_16x16x32_bf16 v[0:3], v[156:159], v[214:217], v[0:3]
	s_setprio 0
	s_barrier
	s_cbranch_scc0 .LBB0_974
	s_and_b64 vcc, exec, s[26:27]
	s_cbranch_vccz .LBB0_977
	s_barrier
